# GEMM load segments: M0 write moved ahead of the address add, 62 s_nop pads removed (on top of v044)
# speedup vs baseline: 1.0000x; 1.0000x over previous
; #define PG8_STAGE(bufoff, gbase, voff) do { _Pragma("unroll") for (int _i = 0; _i < 2; ++_i) \
;         __builtin_amdgcn_global_load_lds((const unsigned*)((const char*)(gbase) + (voff)[_i]), (PG8_LAS unsigned*)(lds + (bufoff) + ldsw + _i * 8192), 16, 0, 0); } while (0)
; #define PG8_LDA(dst, b, h) do { _Pragma("unroll") for (int m = 0; m < 4; ++m) _Pragma("unroll") for (int k = 0; k < 2; ++k) dst[m][k] = *(const PG8_LAS bf16x8*)(lds + PG8_SA(b, h) + aoff + m * 2048 + k * 1024); } while (0)
; #define PG8_LDB(dst, b, h) do { _Pragma("unroll") for (int n = 0; n < 2; ++n) _Pragma("unroll") for (int k = 0; k < 2; ++k) dst[n][k] = *(const PG8_LAS bf16x8*)(lds + PG8_SB(b, h) + boff + n * 2048 + k * 1024); } while (0)
; #define PG8_MMA(ai, bj, At, Bt) do { __builtin_amdgcn_s_setprio(1); _Pragma("unroll") for (int m = 0; m < 4; ++m) _Pragma("unroll") for (int n = 0; n < 2; ++n) _Pragma("unroll") for (int k = 0; k < 2; ++k) \
;         acc[ai][bj][m][n] = __builtin_amdgcn_mfma_f32_16x16x32_bf16(Bt[n][k], At[m][k], acc[ai][bj][m][n], 0, 0, 0); __builtin_amdgcn_s_setprio(0); } while (0)
; #define PG8_BAR __builtin_amdgcn_s_barrier()
; template <class Epi, class Sched, bool ALIGN_EPI = false, bool SP2 = false>
; __device__ __forceinline__ void gemm_phase(PG8_LAS unsigned char* lds, const Gemm g, const Sched& S, const Epi& E, int tid_in) {
;     ...
;             PG8_LDB(B0, 0, 0); PG8_LDB(B1, 0, 1); PG8_SCHED; PG8_LDA(At, 0, 0); PG8_STAGE(PG8_SA(1, 1), a1 + hstepA, voffA);
;             PG8_WAIT_V(8); PG8_WAIT_L(0); PG8_BAR; PG8_MMA(0, 0, At, B0); PG8_MMA(0, 1, At, B1); PG8_BAR; PG8_SCHED;
;             PG8_LDA(At, 0, 1); PG8_STAGE(PG8_SB(0, 0), b2, voffB); PG8_STAGE(PG8_SB(0, 1), b2 + hstep, voffB); PG8_STAGE(PG8_SA(0, 0), a2, voffA);
;             PG8_WAIT_V(8); PG8_WAIT_L(0); PG8_BAR; PG8_MMA(1, 0, At, B0); PG8_MMA(1, 1, At, B1); PG8_BAR; PG8_SCHED;
;             PG8_LDB(B0, 1, 0); PG8_LDB(B1, 1, 1); PG8_SCHED; PG8_LDA(At, 1, 0); PG8_STAGE(PG8_SA(0, 1), a2 + hstepA, voffA);
;             PG8_WAIT_V(8); PG8_WAIT_L(0); PG8_BAR; PG8_MMA(0, 0, At, B0); PG8_MMA(0, 1, At, B1); PG8_BAR; PG8_SCHED;
;             PG8_LDA(At, 1, 1); PG8_STAGE(PG8_SB(1, 0), b3, voffB); PG8_STAGE(PG8_SB(1, 1), b3 + hstep, voffB); PG8_STAGE(PG8_SA(1, 0), a3, voffA);
;             PG8_WAIT_V(8); PG8_WAIT_L(0); PG8_BAR; PG8_MMA(1, 0, At, B0); PG8_MMA(1, 1, At, B1); PG8_BAR; PG8_SCHED;
.LBB0_282:
	s_add_u32 s26, s24, 0xfff80080
	s_addc_u32 s27, s25, -1
	s_add_i32 s45, 0, 0x10000
	s_cmp_eq_u32 s23, 28
	s_cselect_b32 s29, s19, s27
	s_cselect_b32 s28, s18, s26
	s_cselect_b32 s27, s21, s17
	s_cselect_b32 s26, s20, s15
	s_add_i32 s48, 0, 0x14000
	v_add_u32_e32 v158, s45, v152
	v_add_u32_e32 v186, s48, v152
	ds_read_b128 v[142:145], v158
	ds_read_b128 v[146:149], v158 offset:1024
	ds_read_b128 v[154:157], v158 offset:2048
	ds_read_b128 v[158:161], v158 offset:3072
	ds_read_b128 v[162:165], v186
	ds_read_b128 v[166:169], v186 offset:1024
	ds_read_b128 v[182:185], v186 offset:2048
	ds_read_b128 v[186:189], v186 offset:3072
	v_lshl_add_u64 v[222:223], s[24:25], 0, v[138:139]
	s_add_i32 m0, s33, 0xc000
	ds_read_b128 v[190:193], v153
	ds_read_b128 v[194:197], v153 offset:1024
	ds_read_b128 v[198:201], v153 offset:2048
	ds_read_b128 v[202:205], v153 offset:3072
	ds_read_b128 v[206:209], v153 offset:4096
	ds_read_b128 v[210:213], v153 offset:5120
	ds_read_b128 v[214:217], v153 offset:6144
	ds_read_b128 v[218:221], v153 offset:7168
	global_load_lds_dwordx4 v[222:223], off
	s_add_i32 m0, s33, 0xe000
	v_lshl_add_u64 v[222:223], s[24:25], 0, v[140:141]
	global_load_lds_dwordx4 v[222:223], off
	s_waitcnt vmcnt(8)
	s_waitcnt lgkmcnt(0)
	s_barrier
	s_setprio 1
	s_waitcnt lgkmcnt(0)
	v_mfma_f32_16x16x32_bf16 v[126:129], v[142:145], v[190:193], v[126:129]
	v_mfma_f32_16x16x32_bf16 v[118:121], v[154:157], v[190:193], v[118:121]
	v_mfma_f32_16x16x32_bf16 v[110:113], v[142:145], v[198:201], v[110:113]
	v_mfma_f32_16x16x32_bf16 v[102:105], v[154:157], v[198:201], v[102:105]
	v_mfma_f32_16x16x32_bf16 v[94:97], v[142:145], v[206:209], v[94:97]
	v_mfma_f32_16x16x32_bf16 v[86:89], v[154:157], v[206:209], v[86:89]
	v_mfma_f32_16x16x32_bf16 v[78:81], v[142:145], v[214:217], v[78:81]
	v_mfma_f32_16x16x32_bf16 v[70:73], v[154:157], v[214:217], v[70:73]
	v_mfma_f32_16x16x32_bf16 v[126:129], v[146:149], v[194:197], v[126:129]
	v_mfma_f32_16x16x32_bf16 v[118:121], v[158:161], v[194:197], v[118:121]
	v_mfma_f32_16x16x32_bf16 v[110:113], v[146:149], v[202:205], v[110:113]
	v_mfma_f32_16x16x32_bf16 v[102:105], v[158:161], v[202:205], v[102:105]
	v_mfma_f32_16x16x32_bf16 v[94:97], v[146:149], v[210:213], v[94:97]
	v_mfma_f32_16x16x32_bf16 v[86:89], v[158:161], v[210:213], v[86:89]
	v_mfma_f32_16x16x32_bf16 v[78:81], v[146:149], v[218:221], v[78:81]
	v_mfma_f32_16x16x32_bf16 v[70:73], v[158:161], v[218:221], v[70:73]
	s_setprio 0
	s_setprio 1
	v_mfma_f32_16x16x32_bf16 v[122:125], v[162:165], v[190:193], v[122:125]
	v_mfma_f32_16x16x32_bf16 v[114:117], v[182:185], v[190:193], v[114:117]
	v_mfma_f32_16x16x32_bf16 v[106:109], v[162:165], v[198:201], v[106:109]
	v_mfma_f32_16x16x32_bf16 v[98:101], v[182:185], v[198:201], v[98:101]
	v_mfma_f32_16x16x32_bf16 v[90:93], v[162:165], v[206:209], v[90:93]
	v_mfma_f32_16x16x32_bf16 v[82:85], v[182:185], v[206:209], v[82:85]
	v_mfma_f32_16x16x32_bf16 v[74:77], v[162:165], v[214:217], v[74:77]
	v_mfma_f32_16x16x32_bf16 v[66:69], v[182:185], v[214:217], v[66:69]
	v_mfma_f32_16x16x32_bf16 v[122:125], v[166:169], v[194:197], v[122:125]
	v_mfma_f32_16x16x32_bf16 v[114:117], v[186:189], v[194:197], v[114:117]
	v_mfma_f32_16x16x32_bf16 v[106:109], v[166:169], v[202:205], v[106:109]
	v_mfma_f32_16x16x32_bf16 v[98:101], v[186:189], v[202:205], v[98:101]
	v_mfma_f32_16x16x32_bf16 v[90:93], v[166:169], v[210:213], v[90:93]
	v_mfma_f32_16x16x32_bf16 v[82:85], v[186:189], v[210:213], v[82:85]
	v_mfma_f32_16x16x32_bf16 v[74:77], v[166:169], v[218:221], v[74:77]
	v_mfma_f32_16x16x32_bf16 v[66:69], v[186:189], v[218:221], v[66:69]
	s_setprio 0
	s_barrier
	s_add_i32 s45, s45, s31
	v_lshl_add_u64 v[222:223], s[26:27], 0, v[0:1]
	s_mov_b32 m0, s45
	ds_read_b128 v[190:193], v153 offset:16384
	ds_read_b128 v[194:197], v153 offset:17408
	ds_read_b128 v[198:201], v153 offset:18432
	ds_read_b128 v[202:205], v153 offset:19456
	ds_read_b128 v[206:209], v153 offset:20480
	ds_read_b128 v[210:213], v153 offset:21504
	ds_read_b128 v[214:217], v153 offset:22528
	ds_read_b128 v[218:221], v153 offset:23552
	global_load_lds_dwordx4 v[222:223], off
	s_add_i32 m0, s45, 0x2000
	s_add_u32 s46, s26, 0x80000
	v_lshl_add_u64 v[224:225], s[26:27], 0, v[130:131]
	s_addc_u32 s47, s27, 0
	s_add_i32 s45, s48, s31
	global_load_lds_dwordx4 v[224:225], off
	v_lshl_add_u64 v[226:227], s[46:47], 0, v[0:1]
	s_mov_b32 m0, s45
	v_lshl_add_u64 v[228:229], s[28:29], 0, v[132:133]
	global_load_lds_dwordx4 v[226:227], off
	s_add_i32 m0, s45, 0x2000
	v_lshl_add_u64 v[226:227], s[46:47], 0, v[130:131]
	global_load_lds_dwordx4 v[226:227], off
	s_mov_b32 m0, s33
	v_lshl_add_u64 v[226:227], s[28:29], 0, v[134:135]
	global_load_lds_dwordx4 v[226:227], off
	s_mov_b32 m0, s34
	s_nop 0
	global_load_lds_dwordx4 v[228:229], off
	s_waitcnt vmcnt(8)
	s_waitcnt lgkmcnt(0)
	s_barrier
; #define PG8_STAGE(bufoff, gbase, voff) do { _Pragma("unroll") for (int _i = 0; _i < 2; ++_i) \
;         __builtin_amdgcn_global_load_lds((const unsigned*)((const char*)(gbase) + (voff)[_i]), (PG8_LAS unsigned*)(lds + (bufoff) + ldsw + _i * 8192), 16, 0, 0); } while (0)
; #define PG8_LDA(dst, b, h) do { _Pragma("unroll") for (int m = 0; m < 4; ++m) _Pragma("unroll") for (int k = 0; k < 2; ++k) dst[m][k] = *(const PG8_LAS bf16x8*)(lds + PG8_SA(b, h) + aoff + m * 2048 + k * 1024); } while (0)
; #define PG8_LDB(dst, b, h) do { _Pragma("unroll") for (int n = 0; n < 2; ++n) _Pragma("unroll") for (int k = 0; k < 2; ++k) dst[n][k] = *(const PG8_LAS bf16x8*)(lds + PG8_SB(b, h) + boff + n * 2048 + k * 1024); } while (0)
; #define PG8_MMA(ai, bj, At, Bt) do { __builtin_amdgcn_s_setprio(1); _Pragma("unroll") for (int m = 0; m < 4; ++m) _Pragma("unroll") for (int n = 0; n < 2; ++n) _Pragma("unroll") for (int k = 0; k < 2; ++k) \
;         acc[ai][bj][m][n] = __builtin_amdgcn_mfma_f32_16x16x32_bf16(Bt[n][k], At[m][k], acc[ai][bj][m][n], 0, 0, 0); __builtin_amdgcn_s_setprio(0); } while (0)
; #define PG8_BAR __builtin_amdgcn_s_barrier()
; template <class Epi, class Sched, bool ALIGN_EPI = false, bool SP2 = false>
; __device__ __forceinline__ void gemm_phase(PG8_LAS unsigned char* lds, const Gemm g, const Sched& S, const Epi& E, int tid_in) {
;     ...
;             PG8_LDB(B0, 0, 0); PG8_LDB(B1, 0, 1); PG8_SCHED; PG8_LDA(At, 0, 0); PG8_STAGE(PG8_SA(1, 1), a1 + hstepA, voffA);
;             PG8_WAIT_V(8); PG8_WAIT_L(0); PG8_BAR; PG8_MMA(0, 0, At, B0); PG8_MMA(0, 1, At, B1); PG8_BAR; PG8_SCHED;
;             PG8_LDA(At, 0, 1); PG8_STAGE(PG8_SB(0, 0), b2, voffB); PG8_STAGE(PG8_SB(0, 1), b2 + hstep, voffB); PG8_STAGE(PG8_SA(0, 0), a2, voffA);
;             PG8_WAIT_V(8); PG8_WAIT_L(0); PG8_BAR; PG8_MMA(1, 0, At, B0); PG8_MMA(1, 1, At, B1); PG8_BAR; PG8_SCHED;
;             PG8_LDB(B0, 1, 0); PG8_LDB(B1, 1, 1); PG8_SCHED; PG8_LDA(At, 1, 0); PG8_STAGE(PG8_SA(0, 1), a2 + hstepA, voffA);
;             PG8_WAIT_V(8); PG8_WAIT_L(0); PG8_BAR; PG8_MMA(0, 0, At, B0); PG8_MMA(0, 1, At, B1); PG8_BAR; PG8_SCHED;
;             PG8_LDA(At, 1, 1); PG8_STAGE(PG8_SB(1, 0), b3, voffB); PG8_STAGE(PG8_SB(1, 1), b3 + hstep, voffB); PG8_STAGE(PG8_SA(1, 0), a3, voffA);
;             PG8_WAIT_V(8); PG8_WAIT_L(0); PG8_BAR; PG8_MMA(1, 0, At, B0); PG8_MMA(1, 1, At, B1); PG8_BAR; PG8_SCHED;
	s_setprio 1
	s_waitcnt lgkmcnt(0)
	v_mfma_f32_16x16x32_bf16 v[62:65], v[142:145], v[190:193], v[62:65]
	v_mfma_f32_16x16x32_bf16 v[54:57], v[154:157], v[190:193], v[54:57]
	v_mfma_f32_16x16x32_bf16 v[46:49], v[142:145], v[198:201], v[46:49]
	v_mfma_f32_16x16x32_bf16 v[38:41], v[154:157], v[198:201], v[38:41]
	v_mfma_f32_16x16x32_bf16 v[30:33], v[142:145], v[206:209], v[30:33]
	v_mfma_f32_16x16x32_bf16 v[22:25], v[154:157], v[206:209], v[22:25]
	v_mfma_f32_16x16x32_bf16 v[14:17], v[142:145], v[214:217], v[14:17]
	v_mfma_f32_16x16x32_bf16 v[6:9], v[154:157], v[214:217], v[6:9]
	v_mfma_f32_16x16x32_bf16 v[62:65], v[146:149], v[194:197], v[62:65]
	v_mfma_f32_16x16x32_bf16 v[54:57], v[158:161], v[194:197], v[54:57]
	v_mfma_f32_16x16x32_bf16 v[46:49], v[146:149], v[202:205], v[46:49]
	v_mfma_f32_16x16x32_bf16 v[38:41], v[158:161], v[202:205], v[38:41]
	v_mfma_f32_16x16x32_bf16 v[30:33], v[146:149], v[210:213], v[30:33]
	v_mfma_f32_16x16x32_bf16 v[22:25], v[158:161], v[210:213], v[22:25]
	v_mfma_f32_16x16x32_bf16 v[14:17], v[146:149], v[218:221], v[14:17]
	v_mfma_f32_16x16x32_bf16 v[6:9], v[158:161], v[218:221], v[6:9]
	s_setprio 0
	s_setprio 1
	v_mfma_f32_16x16x32_bf16 v[58:61], v[162:165], v[190:193], v[58:61]
	v_mfma_f32_16x16x32_bf16 v[50:53], v[182:185], v[190:193], v[50:53]
	v_mfma_f32_16x16x32_bf16 v[42:45], v[162:165], v[198:201], v[42:45]
	v_mfma_f32_16x16x32_bf16 v[34:37], v[182:185], v[198:201], v[34:37]
	v_mfma_f32_16x16x32_bf16 v[26:29], v[162:165], v[206:209], v[26:29]
	v_mfma_f32_16x16x32_bf16 v[18:21], v[182:185], v[206:209], v[18:21]
	v_mfma_f32_16x16x32_bf16 v[10:13], v[162:165], v[214:217], v[10:13]
	v_mfma_f32_16x16x32_bf16 v[2:5], v[182:185], v[214:217], v[2:5]
	v_mfma_f32_16x16x32_bf16 v[58:61], v[166:169], v[194:197], v[58:61]
	v_mfma_f32_16x16x32_bf16 v[50:53], v[186:189], v[194:197], v[50:53]
	v_mfma_f32_16x16x32_bf16 v[42:45], v[166:169], v[202:205], v[42:45]
	v_mfma_f32_16x16x32_bf16 v[34:37], v[186:189], v[202:205], v[34:37]
	v_mfma_f32_16x16x32_bf16 v[26:29], v[166:169], v[210:213], v[26:29]
	v_mfma_f32_16x16x32_bf16 v[18:21], v[186:189], v[210:213], v[18:21]
	v_mfma_f32_16x16x32_bf16 v[10:13], v[166:169], v[218:221], v[10:13]
	v_mfma_f32_16x16x32_bf16 v[2:5], v[186:189], v[218:221], v[2:5]
	s_setprio 0
	s_barrier
	s_add_i32 s45, 0, 0x18000
	s_add_i32 s46, 0, 0x1c000
	v_add_u32_e32 v158, s45, v152
	v_add_u32_e32 v186, s46, v152
	ds_read_b128 v[142:145], v158
	ds_read_b128 v[146:149], v158 offset:1024
	ds_read_b128 v[154:157], v158 offset:2048
	ds_read_b128 v[158:161], v158 offset:3072
	ds_read_b128 v[162:165], v186
	ds_read_b128 v[166:169], v186 offset:1024
	ds_read_b128 v[182:185], v186 offset:2048
	ds_read_b128 v[186:189], v186 offset:3072
	s_add_u32 s28, s28, 0x80000
	s_addc_u32 s29, s29, 0
	s_mov_b32 m0, s35
	v_lshl_add_u64 v[240:241], s[28:29], 0, v[134:135]
	ds_read_b128 v[190:193], v153 offset:32768
	ds_read_b128 v[194:197], v153 offset:33792
	ds_read_b128 v[198:201], v153 offset:34816
	ds_read_b128 v[202:205], v153 offset:35840
	ds_read_b128 v[206:209], v153 offset:36864
	ds_read_b128 v[210:213], v153 offset:37888
	ds_read_b128 v[214:217], v153 offset:38912
	ds_read_b128 v[218:221], v153 offset:39936
	global_load_lds_dwordx4 v[240:241], off
	s_mov_b32 m0, s36
	v_lshl_add_u64 v[240:241], s[28:29], 0, v[132:133]
	global_load_lds_dwordx4 v[240:241], off
	s_waitcnt vmcnt(8)
	s_waitcnt lgkmcnt(0)
	s_barrier
	s_setprio 1
	s_waitcnt lgkmcnt(0)
	v_mfma_f32_16x16x32_bf16 v[126:129], v[142:145], v[190:193], v[126:129]
	v_mfma_f32_16x16x32_bf16 v[118:121], v[154:157], v[190:193], v[118:121]
	v_mfma_f32_16x16x32_bf16 v[110:113], v[142:145], v[198:201], v[110:113]
	v_mfma_f32_16x16x32_bf16 v[102:105], v[154:157], v[198:201], v[102:105]
	v_mfma_f32_16x16x32_bf16 v[94:97], v[142:145], v[206:209], v[94:97]
	v_mfma_f32_16x16x32_bf16 v[86:89], v[154:157], v[206:209], v[86:89]
	v_mfma_f32_16x16x32_bf16 v[78:81], v[142:145], v[214:217], v[78:81]
	v_mfma_f32_16x16x32_bf16 v[70:73], v[154:157], v[214:217], v[70:73]
	v_mfma_f32_16x16x32_bf16 v[126:129], v[146:149], v[194:197], v[126:129]
	v_mfma_f32_16x16x32_bf16 v[118:121], v[158:161], v[194:197], v[118:121]
	v_mfma_f32_16x16x32_bf16 v[110:113], v[146:149], v[202:205], v[110:113]
	v_mfma_f32_16x16x32_bf16 v[102:105], v[158:161], v[202:205], v[102:105]
	v_mfma_f32_16x16x32_bf16 v[94:97], v[146:149], v[210:213], v[94:97]
	v_mfma_f32_16x16x32_bf16 v[86:89], v[158:161], v[210:213], v[86:89]
	v_mfma_f32_16x16x32_bf16 v[78:81], v[146:149], v[218:221], v[78:81]
	v_mfma_f32_16x16x32_bf16 v[70:73], v[158:161], v[218:221], v[70:73]
	s_setprio 0
	s_setprio 1
	v_mfma_f32_16x16x32_bf16 v[122:125], v[162:165], v[190:193], v[122:125]
	v_mfma_f32_16x16x32_bf16 v[114:117], v[182:185], v[190:193], v[114:117]
	v_mfma_f32_16x16x32_bf16 v[106:109], v[162:165], v[198:201], v[106:109]
	v_mfma_f32_16x16x32_bf16 v[98:101], v[182:185], v[198:201], v[98:101]
	v_mfma_f32_16x16x32_bf16 v[90:93], v[162:165], v[206:209], v[90:93]
	v_mfma_f32_16x16x32_bf16 v[82:85], v[182:185], v[206:209], v[82:85]
	v_mfma_f32_16x16x32_bf16 v[74:77], v[162:165], v[214:217], v[74:77]
	v_mfma_f32_16x16x32_bf16 v[66:69], v[182:185], v[214:217], v[66:69]
	v_mfma_f32_16x16x32_bf16 v[122:125], v[166:169], v[194:197], v[122:125]
	v_mfma_f32_16x16x32_bf16 v[114:117], v[186:189], v[194:197], v[114:117]
	v_mfma_f32_16x16x32_bf16 v[106:109], v[166:169], v[202:205], v[106:109]
	v_mfma_f32_16x16x32_bf16 v[98:101], v[186:189], v[202:205], v[98:101]
	v_mfma_f32_16x16x32_bf16 v[90:93], v[166:169], v[210:213], v[90:93]
	v_mfma_f32_16x16x32_bf16 v[82:85], v[186:189], v[210:213], v[82:85]
	v_mfma_f32_16x16x32_bf16 v[74:77], v[166:169], v[218:221], v[74:77]
	v_mfma_f32_16x16x32_bf16 v[66:69], v[186:189], v[218:221], v[66:69]
	s_setprio 0
	s_barrier
; #define PG8_STAGE(bufoff, gbase, voff) do { _Pragma("unroll") for (int _i = 0; _i < 2; ++_i) \
;         __builtin_amdgcn_global_load_lds((const unsigned*)((const char*)(gbase) + (voff)[_i]), (PG8_LAS unsigned*)(lds + (bufoff) + ldsw + _i * 8192), 16, 0, 0); } while (0)
; #define PG8_LDA(dst, b, h) do { _Pragma("unroll") for (int m = 0; m < 4; ++m) _Pragma("unroll") for (int k = 0; k < 2; ++k) dst[m][k] = *(const PG8_LAS bf16x8*)(lds + PG8_SA(b, h) + aoff + m * 2048 + k * 1024); } while (0)
; #define PG8_LDB(dst, b, h) do { _Pragma("unroll") for (int n = 0; n < 2; ++n) _Pragma("unroll") for (int k = 0; k < 2; ++k) dst[n][k] = *(const PG8_LAS bf16x8*)(lds + PG8_SB(b, h) + boff + n * 2048 + k * 1024); } while (0)
; #define PG8_MMA(ai, bj, At, Bt) do { __builtin_amdgcn_s_setprio(1); _Pragma("unroll") for (int m = 0; m < 4; ++m) _Pragma("unroll") for (int n = 0; n < 2; ++n) _Pragma("unroll") for (int k = 0; k < 2; ++k) \
;         acc[ai][bj][m][n] = __builtin_amdgcn_mfma_f32_16x16x32_bf16(Bt[n][k], At[m][k], acc[ai][bj][m][n], 0, 0, 0); __builtin_amdgcn_s_setprio(0); } while (0)
; template <class Epi, class Sched, bool ALIGN_EPI = false, bool SP2 = false>
; __device__ __forceinline__ void gemm_phase(PG8_LAS unsigned char* lds, const Gemm g, const Sched& S, const Epi& E, int tid_in) {
;     ...
;             PG8_LDB(B0, 0, 0); PG8_LDB(B1, 0, 1); PG8_SCHED; PG8_LDA(At, 0, 0); PG8_STAGE(PG8_SA(1, 1), a1 + hstepA, voffA);
;             PG8_WAIT_V(8); PG8_WAIT_L(0); PG8_BAR; PG8_MMA(0, 0, At, B0); PG8_MMA(0, 1, At, B1); PG8_BAR; PG8_SCHED;
;             PG8_LDA(At, 0, 1); PG8_STAGE(PG8_SB(0, 0), b2, voffB); PG8_STAGE(PG8_SB(0, 1), b2 + hstep, voffB); PG8_STAGE(PG8_SA(0, 0), a2, voffA);
;             PG8_WAIT_V(8); PG8_WAIT_L(0); PG8_BAR; PG8_MMA(1, 0, At, B0); PG8_MMA(1, 1, At, B1); PG8_BAR; PG8_SCHED;
;             PG8_LDB(B0, 1, 0); PG8_LDB(B1, 1, 1); PG8_SCHED; PG8_LDA(At, 1, 0); PG8_STAGE(PG8_SA(0, 1), a2 + hstepA, voffA);
;             PG8_WAIT_V(8); PG8_WAIT_L(0); PG8_BAR; PG8_MMA(0, 0, At, B0); PG8_MMA(0, 1, At, B1); PG8_BAR; PG8_SCHED;
;             PG8_LDA(At, 1, 1); PG8_STAGE(PG8_SB(1, 0), b3, voffB); PG8_STAGE(PG8_SB(1, 1), b3 + hstep, voffB); PG8_STAGE(PG8_SA(1, 0), a3, voffA);
;             PG8_WAIT_V(8); PG8_WAIT_L(0); PG8_BAR; PG8_MMA(1, 0, At, B0); PG8_MMA(1, 1, At, B1); PG8_BAR; PG8_SCHED;
;     ...
;         if constexpr (ALIGN_EPI) { if (wr == 0) PG8_BAR; }
	s_add_i32 s28, s45, s31
	v_lshl_add_u64 v[222:223], v[222:223], 0, s[90:91]
	s_mov_b32 m0, s28
	ds_read_b128 v[190:193], v153 offset:49152
	ds_read_b128 v[194:197], v153 offset:50176
	ds_read_b128 v[198:201], v153 offset:51200
	ds_read_b128 v[202:205], v153 offset:52224
	ds_read_b128 v[206:209], v153 offset:53248
	ds_read_b128 v[210:213], v153 offset:54272
	ds_read_b128 v[214:217], v153 offset:55296
	ds_read_b128 v[218:221], v153 offset:56320
	global_load_lds_dwordx4 v[222:223], off
	s_add_i32 m0, s28, 0x2000
	s_add_u32 s26, s26, 0x80080
	v_lshl_add_u64 v[222:223], v[224:225], 0, s[90:91]
	s_addc_u32 s27, s27, 0
	s_add_i32 s28, s46, s31
	global_load_lds_dwordx4 v[222:223], off
	s_mov_b32 m0, s28
	v_lshl_add_u64 v[222:223], s[26:27], 0, v[0:1]
	global_load_lds_dwordx4 v[222:223], off
	s_add_i32 m0, s28, 0x2000
	v_lshl_add_u64 v[222:223], s[26:27], 0, v[130:131]
	global_load_lds_dwordx4 v[222:223], off
	s_mov_b32 m0, s39
	v_lshl_add_u64 v[222:223], v[226:227], 0, s[90:91]
	global_load_lds_dwordx4 v[222:223], off
	s_mov_b32 m0, s40
	v_lshl_add_u64 v[222:223], v[228:229], 0, s[90:91]
	global_load_lds_dwordx4 v[222:223], off
	s_waitcnt vmcnt(8)
	s_waitcnt lgkmcnt(0)
	s_barrier
	s_setprio 1
	s_waitcnt lgkmcnt(0)
	v_mfma_f32_16x16x32_bf16 v[62:65], v[142:145], v[190:193], v[62:65]
	v_mfma_f32_16x16x32_bf16 v[54:57], v[154:157], v[190:193], v[54:57]
	v_mfma_f32_16x16x32_bf16 v[46:49], v[142:145], v[198:201], v[46:49]
	v_mfma_f32_16x16x32_bf16 v[38:41], v[154:157], v[198:201], v[38:41]
	v_mfma_f32_16x16x32_bf16 v[30:33], v[142:145], v[206:209], v[30:33]
	v_mfma_f32_16x16x32_bf16 v[22:25], v[154:157], v[206:209], v[22:25]
	v_mfma_f32_16x16x32_bf16 v[14:17], v[142:145], v[214:217], v[14:17]
	v_mfma_f32_16x16x32_bf16 v[6:9], v[154:157], v[214:217], v[6:9]
	v_mfma_f32_16x16x32_bf16 v[62:65], v[146:149], v[194:197], v[62:65]
	v_mfma_f32_16x16x32_bf16 v[54:57], v[158:161], v[194:197], v[54:57]
	v_mfma_f32_16x16x32_bf16 v[46:49], v[146:149], v[202:205], v[46:49]
	v_mfma_f32_16x16x32_bf16 v[38:41], v[158:161], v[202:205], v[38:41]
	v_mfma_f32_16x16x32_bf16 v[30:33], v[146:149], v[210:213], v[30:33]
	v_mfma_f32_16x16x32_bf16 v[22:25], v[158:161], v[210:213], v[22:25]
	v_mfma_f32_16x16x32_bf16 v[14:17], v[146:149], v[218:221], v[14:17]
	v_mfma_f32_16x16x32_bf16 v[6:9], v[158:161], v[218:221], v[6:9]
	s_setprio 0
	s_setprio 1
	v_mfma_f32_16x16x32_bf16 v[58:61], v[162:165], v[190:193], v[58:61]
	v_mfma_f32_16x16x32_bf16 v[50:53], v[182:185], v[190:193], v[50:53]
	v_mfma_f32_16x16x32_bf16 v[42:45], v[162:165], v[198:201], v[42:45]
	v_mfma_f32_16x16x32_bf16 v[34:37], v[182:185], v[198:201], v[34:37]
	v_mfma_f32_16x16x32_bf16 v[26:29], v[162:165], v[206:209], v[26:29]
	v_mfma_f32_16x16x32_bf16 v[18:21], v[182:185], v[206:209], v[18:21]
	v_mfma_f32_16x16x32_bf16 v[10:13], v[162:165], v[214:217], v[10:13]
	v_mfma_f32_16x16x32_bf16 v[2:5], v[182:185], v[214:217], v[2:5]
	v_mfma_f32_16x16x32_bf16 v[58:61], v[166:169], v[194:197], v[58:61]
	v_mfma_f32_16x16x32_bf16 v[50:53], v[186:189], v[194:197], v[50:53]
	v_mfma_f32_16x16x32_bf16 v[42:45], v[166:169], v[202:205], v[42:45]
	v_mfma_f32_16x16x32_bf16 v[34:37], v[186:189], v[202:205], v[34:37]
	v_mfma_f32_16x16x32_bf16 v[26:29], v[166:169], v[210:213], v[26:29]
	v_mfma_f32_16x16x32_bf16 v[18:21], v[186:189], v[210:213], v[18:21]
	v_mfma_f32_16x16x32_bf16 v[10:13], v[166:169], v[218:221], v[10:13]
	v_mfma_f32_16x16x32_bf16 v[2:5], v[186:189], v[218:221], v[2:5]
	s_setprio 0
	s_barrier
	s_add_i32 s23, s23, 2
	s_add_u32 s24, s24, 0x100
	s_addc_u32 s25, s25, 0
	s_add_u32 s15, s15, 0x100
	s_addc_u32 s17, s17, 0
	s_cmp_gt_u32 s23, 29
	s_cbranch_scc0 .LBB0_282
	s_and_b64 vcc, exec, s[12:13]
	s_cbranch_vccz .LBB0_285
	s_barrier

; #define PG8_STAGE(bufoff, gbase, voff) do { _Pragma("unroll") for (int _i = 0; _i < 2; ++_i) \
;         __builtin_amdgcn_global_load_lds((const unsigned*)((const char*)(gbase) + (voff)[_i]), (PG8_LAS unsigned*)(lds + (bufoff) + ldsw + _i * 8192), 16, 0, 0); } while (0)
; #define PG8_LDA(dst, b, h) do { _Pragma("unroll") for (int m = 0; m < 4; ++m) _Pragma("unroll") for (int k = 0; k < 2; ++k) dst[m][k] = *(const PG8_LAS bf16x8*)(lds + PG8_SA(b, h) + aoff + m * 2048 + k * 1024); } while (0)
; #define PG8_LDB(dst, b, h) do { _Pragma("unroll") for (int n = 0; n < 2; ++n) _Pragma("unroll") for (int k = 0; k < 2; ++k) dst[n][k] = *(const PG8_LAS bf16x8*)(lds + PG8_SB(b, h) + boff + n * 2048 + k * 1024); } while (0)
; #define PG8_MMA(ai, bj, At, Bt) do { __builtin_amdgcn_s_setprio(1); _Pragma("unroll") for (int m = 0; m < 4; ++m) _Pragma("unroll") for (int n = 0; n < 2; ++n) _Pragma("unroll") for (int k = 0; k < 2; ++k) \
;         acc[ai][bj][m][n] = __builtin_amdgcn_mfma_f32_16x16x32_bf16(Bt[n][k], At[m][k], acc[ai][bj][m][n], 0, 0, 0); __builtin_amdgcn_s_setprio(0); } while (0)
; #define PG8_BAR __builtin_amdgcn_s_barrier()
; template <class Epi, class Sched, bool ALIGN_EPI = false, bool SP2 = false>
; __device__ __forceinline__ void gemm_phase(PG8_LAS unsigned char* lds, const Gemm g, const Sched& S, const Epi& E, int tid_in) {
;     ...
;             PG8_LDB(B0, 0, 0); PG8_LDB(B1, 0, 1); PG8_SCHED; PG8_LDA(At, 0, 0); PG8_STAGE(PG8_SA(1, 1), a1 + hstepA, voffA);
;             PG8_WAIT_V(8); PG8_WAIT_L(0); PG8_BAR; PG8_MMA(0, 0, At, B0); PG8_MMA(0, 1, At, B1); PG8_BAR; PG8_SCHED;
;             PG8_LDA(At, 0, 1); PG8_STAGE(PG8_SB(0, 0), b2, voffB); PG8_STAGE(PG8_SB(0, 1), b2 + hstep, voffB); PG8_STAGE(PG8_SA(0, 0), a2, voffA);
;             PG8_WAIT_V(8); PG8_WAIT_L(0); PG8_BAR; PG8_MMA(1, 0, At, B0); PG8_MMA(1, 1, At, B1); PG8_BAR; PG8_SCHED;
;             PG8_LDB(B0, 1, 0); PG8_LDB(B1, 1, 1); PG8_SCHED; PG8_LDA(At, 1, 0); PG8_STAGE(PG8_SA(0, 1), a2 + hstepA, voffA);
;             PG8_WAIT_V(8); PG8_WAIT_L(0); PG8_BAR; PG8_MMA(0, 0, At, B0); PG8_MMA(0, 1, At, B1); PG8_BAR; PG8_SCHED;
;             PG8_LDA(At, 1, 1); PG8_STAGE(PG8_SB(1, 0), b3, voffB); PG8_STAGE(PG8_SB(1, 1), b3 + hstep, voffB); PG8_STAGE(PG8_SA(1, 0), a3, voffA);
;             PG8_WAIT_V(8); PG8_WAIT_L(0); PG8_BAR; PG8_MMA(1, 0, At, B0); PG8_MMA(1, 1, At, B1); PG8_BAR; PG8_SCHED;
.LBB0_352:
	s_add_i32 s82, s28, 2
	s_add_u32 s26, s8, 0x100
	s_addc_u32 s27, s9, 0
	s_add_i32 s4, 0, 0x10000
	s_cmp_eq_u32 s70, s28
	s_cselect_b32 s31, s46, s27
	s_cselect_b32 s30, s47, s26
	s_cselect_b32 s29, s67, s79
	s_cselect_b32 s28, s68, s76
	s_add_i32 s5, 0, 0x14000
	v_add_u32_e32 v152, s4, v146
	v_add_u32_e32 v168, s5, v146
	ds_read_b128 v[136:139], v152
	ds_read_b128 v[140:143], v152 offset:1024
	ds_read_b128 v[148:151], v152 offset:2048
	ds_read_b128 v[152:155], v152 offset:3072
	ds_read_b128 v[156:159], v168
	ds_read_b128 v[160:163], v168 offset:1024
	ds_read_b128 v[164:167], v168 offset:2048
	ds_read_b128 v[182:185], v168 offset:3072
	v_lshl_add_u64 v[168:169], s[8:9], 0, v[132:133]
	s_add_i32 m0, s34, 0xc000
	ds_read_b128 v[186:189], v147
	ds_read_b128 v[190:193], v147 offset:1024
	ds_read_b128 v[194:197], v147 offset:2048
	ds_read_b128 v[198:201], v147 offset:3072
	ds_read_b128 v[202:205], v147 offset:4096
	ds_read_b128 v[206:209], v147 offset:5120
	ds_read_b128 v[210:213], v147 offset:6144
	ds_read_b128 v[214:217], v147 offset:7168
	global_load_lds_dwordx4 v[168:169], off
	s_add_i32 m0, s34, 0xe000
	v_lshl_add_u64 v[168:169], s[8:9], 0, v[134:135]
	global_load_lds_dwordx4 v[168:169], off
	s_waitcnt vmcnt(8)
	s_waitcnt lgkmcnt(0)
	s_barrier
	s_setprio 1
	s_waitcnt lgkmcnt(0)
	v_mfma_f32_16x16x32_bf16 v[126:129], v[136:139], v[186:189], v[126:129]
	v_mfma_f32_16x16x32_bf16 v[122:125], v[148:151], v[186:189], v[122:125]
	v_mfma_f32_16x16x32_bf16 v[118:121], v[136:139], v[194:197], v[118:121]
	v_mfma_f32_16x16x32_bf16 v[114:117], v[148:151], v[194:197], v[114:117]
	v_mfma_f32_16x16x32_bf16 v[110:113], v[136:139], v[202:205], v[110:113]
	v_mfma_f32_16x16x32_bf16 v[106:109], v[148:151], v[202:205], v[106:109]
	v_mfma_f32_16x16x32_bf16 v[102:105], v[136:139], v[210:213], v[102:105]
	v_mfma_f32_16x16x32_bf16 v[98:101], v[148:151], v[210:213], v[98:101]
	v_mfma_f32_16x16x32_bf16 v[126:129], v[140:143], v[190:193], v[126:129]
	v_mfma_f32_16x16x32_bf16 v[122:125], v[152:155], v[190:193], v[122:125]
	v_mfma_f32_16x16x32_bf16 v[118:121], v[140:143], v[198:201], v[118:121]
	v_mfma_f32_16x16x32_bf16 v[114:117], v[152:155], v[198:201], v[114:117]
	v_mfma_f32_16x16x32_bf16 v[110:113], v[140:143], v[206:209], v[110:113]
	v_mfma_f32_16x16x32_bf16 v[106:109], v[152:155], v[206:209], v[106:109]
	v_mfma_f32_16x16x32_bf16 v[102:105], v[140:143], v[214:217], v[102:105]
	v_mfma_f32_16x16x32_bf16 v[98:101], v[152:155], v[214:217], v[98:101]
	s_setprio 0
	s_setprio 1
	v_mfma_f32_16x16x32_bf16 v[94:97], v[156:159], v[186:189], v[94:97]
	v_mfma_f32_16x16x32_bf16 v[90:93], v[164:167], v[186:189], v[90:93]
	v_mfma_f32_16x16x32_bf16 v[86:89], v[156:159], v[194:197], v[86:89]
	v_mfma_f32_16x16x32_bf16 v[82:85], v[164:167], v[194:197], v[82:85]
	v_mfma_f32_16x16x32_bf16 v[78:81], v[156:159], v[202:205], v[78:81]
	v_mfma_f32_16x16x32_bf16 v[74:77], v[164:167], v[202:205], v[74:77]
	v_mfma_f32_16x16x32_bf16 v[70:73], v[156:159], v[210:213], v[70:73]
	v_mfma_f32_16x16x32_bf16 v[66:69], v[164:167], v[210:213], v[66:69]
	v_mfma_f32_16x16x32_bf16 v[94:97], v[160:163], v[190:193], v[94:97]
	v_mfma_f32_16x16x32_bf16 v[90:93], v[182:185], v[190:193], v[90:93]
	v_mfma_f32_16x16x32_bf16 v[86:89], v[160:163], v[198:201], v[86:89]
	v_mfma_f32_16x16x32_bf16 v[82:85], v[182:185], v[198:201], v[82:85]
	v_mfma_f32_16x16x32_bf16 v[78:81], v[160:163], v[206:209], v[78:81]
	v_mfma_f32_16x16x32_bf16 v[74:77], v[182:185], v[206:209], v[74:77]
	v_mfma_f32_16x16x32_bf16 v[70:73], v[160:163], v[214:217], v[70:73]
	v_mfma_f32_16x16x32_bf16 v[66:69], v[182:185], v[214:217], v[66:69]
	s_setprio 0
	s_barrier
	s_add_i32 s8, s4, s33
	v_lshl_add_u64 v[168:169], s[28:29], 0, v[0:1]
	s_mov_b32 m0, s8
	ds_read_b128 v[186:189], v147 offset:16384
	ds_read_b128 v[190:193], v147 offset:17408
	ds_read_b128 v[194:197], v147 offset:18432
	ds_read_b128 v[198:201], v147 offset:19456
	ds_read_b128 v[202:205], v147 offset:20480
	ds_read_b128 v[206:209], v147 offset:21504
	ds_read_b128 v[210:213], v147 offset:22528
	ds_read_b128 v[214:217], v147 offset:23552
	global_load_lds_dwordx4 v[168:169], off
	s_add_i32 m0, s8, 0x2000
	s_add_u32 s8, s28, 0x160000
	v_lshl_add_u64 v[218:219], s[28:29], 0, v[130:131]
	s_addc_u32 s9, s29, 0
	s_add_i32 s55, s5, s33
	global_load_lds_dwordx4 v[218:219], off
	v_lshl_add_u64 v[220:221], s[8:9], 0, v[0:1]
	s_mov_b32 m0, s55
	v_lshl_add_u64 v[222:223], s[30:31], 0, v[130:131]
	global_load_lds_dwordx4 v[220:221], off
	s_add_i32 m0, s55, 0x2000
	v_lshl_add_u64 v[220:221], s[8:9], 0, v[130:131]
	global_load_lds_dwordx4 v[220:221], off
	s_mov_b32 m0, s34
	v_lshl_add_u64 v[220:221], s[30:31], 0, v[0:1]
	global_load_lds_dwordx4 v[220:221], off
	s_mov_b32 m0, s35
	s_nop 0
	global_load_lds_dwordx4 v[222:223], off
	s_waitcnt vmcnt(8)
	s_waitcnt lgkmcnt(0)
	s_barrier
; #define PG8_STAGE(bufoff, gbase, voff) do { _Pragma("unroll") for (int _i = 0; _i < 2; ++_i) \
;         __builtin_amdgcn_global_load_lds((const unsigned*)((const char*)(gbase) + (voff)[_i]), (PG8_LAS unsigned*)(lds + (bufoff) + ldsw + _i * 8192), 16, 0, 0); } while (0)
; #define PG8_LDA(dst, b, h) do { _Pragma("unroll") for (int m = 0; m < 4; ++m) _Pragma("unroll") for (int k = 0; k < 2; ++k) dst[m][k] = *(const PG8_LAS bf16x8*)(lds + PG8_SA(b, h) + aoff + m * 2048 + k * 1024); } while (0)
; #define PG8_LDB(dst, b, h) do { _Pragma("unroll") for (int n = 0; n < 2; ++n) _Pragma("unroll") for (int k = 0; k < 2; ++k) dst[n][k] = *(const PG8_LAS bf16x8*)(lds + PG8_SB(b, h) + boff + n * 2048 + k * 1024); } while (0)
; #define PG8_MMA(ai, bj, At, Bt) do { __builtin_amdgcn_s_setprio(1); _Pragma("unroll") for (int m = 0; m < 4; ++m) _Pragma("unroll") for (int n = 0; n < 2; ++n) _Pragma("unroll") for (int k = 0; k < 2; ++k) \
;         acc[ai][bj][m][n] = __builtin_amdgcn_mfma_f32_16x16x32_bf16(Bt[n][k], At[m][k], acc[ai][bj][m][n], 0, 0, 0); __builtin_amdgcn_s_setprio(0); } while (0)
; #define PG8_BAR __builtin_amdgcn_s_barrier()
; template <class Epi, class Sched, bool ALIGN_EPI = false, bool SP2 = false>
; __device__ __forceinline__ void gemm_phase(PG8_LAS unsigned char* lds, const Gemm g, const Sched& S, const Epi& E, int tid_in) {
;     ...
;             PG8_LDB(B0, 0, 0); PG8_LDB(B1, 0, 1); PG8_SCHED; PG8_LDA(At, 0, 0); PG8_STAGE(PG8_SA(1, 1), a1 + hstepA, voffA);
;             PG8_WAIT_V(8); PG8_WAIT_L(0); PG8_BAR; PG8_MMA(0, 0, At, B0); PG8_MMA(0, 1, At, B1); PG8_BAR; PG8_SCHED;
;             PG8_LDA(At, 0, 1); PG8_STAGE(PG8_SB(0, 0), b2, voffB); PG8_STAGE(PG8_SB(0, 1), b2 + hstep, voffB); PG8_STAGE(PG8_SA(0, 0), a2, voffA);
;             PG8_WAIT_V(8); PG8_WAIT_L(0); PG8_BAR; PG8_MMA(1, 0, At, B0); PG8_MMA(1, 1, At, B1); PG8_BAR; PG8_SCHED;
;             PG8_LDB(B0, 1, 0); PG8_LDB(B1, 1, 1); PG8_SCHED; PG8_LDA(At, 1, 0); PG8_STAGE(PG8_SA(0, 1), a2 + hstepA, voffA);
;             PG8_WAIT_V(8); PG8_WAIT_L(0); PG8_BAR; PG8_MMA(0, 0, At, B0); PG8_MMA(0, 1, At, B1); PG8_BAR; PG8_SCHED;
;             PG8_LDA(At, 1, 1); PG8_STAGE(PG8_SB(1, 0), b3, voffB); PG8_STAGE(PG8_SB(1, 1), b3 + hstep, voffB); PG8_STAGE(PG8_SA(1, 0), a3, voffA);
;             PG8_WAIT_V(8); PG8_WAIT_L(0); PG8_BAR; PG8_MMA(1, 0, At, B0); PG8_MMA(1, 1, At, B1); PG8_BAR; PG8_SCHED;
	s_setprio 1
	s_waitcnt lgkmcnt(0)
	v_mfma_f32_16x16x32_bf16 v[62:65], v[136:139], v[186:189], v[62:65]
	v_mfma_f32_16x16x32_bf16 v[58:61], v[148:151], v[186:189], v[58:61]
	v_mfma_f32_16x16x32_bf16 v[54:57], v[136:139], v[194:197], v[54:57]
	v_mfma_f32_16x16x32_bf16 v[50:53], v[148:151], v[194:197], v[50:53]
	v_mfma_f32_16x16x32_bf16 v[46:49], v[136:139], v[202:205], v[46:49]
	v_mfma_f32_16x16x32_bf16 v[42:45], v[148:151], v[202:205], v[42:45]
	v_mfma_f32_16x16x32_bf16 v[38:41], v[136:139], v[210:213], v[38:41]
	v_mfma_f32_16x16x32_bf16 v[34:37], v[148:151], v[210:213], v[34:37]
	v_mfma_f32_16x16x32_bf16 v[62:65], v[140:143], v[190:193], v[62:65]
	v_mfma_f32_16x16x32_bf16 v[58:61], v[152:155], v[190:193], v[58:61]
	v_mfma_f32_16x16x32_bf16 v[54:57], v[140:143], v[198:201], v[54:57]
	v_mfma_f32_16x16x32_bf16 v[50:53], v[152:155], v[198:201], v[50:53]
	v_mfma_f32_16x16x32_bf16 v[46:49], v[140:143], v[206:209], v[46:49]
	v_mfma_f32_16x16x32_bf16 v[42:45], v[152:155], v[206:209], v[42:45]
	v_mfma_f32_16x16x32_bf16 v[38:41], v[140:143], v[214:217], v[38:41]
	v_mfma_f32_16x16x32_bf16 v[34:37], v[152:155], v[214:217], v[34:37]
	s_setprio 0
	s_setprio 1
	v_mfma_f32_16x16x32_bf16 v[30:33], v[156:159], v[186:189], v[30:33]
	v_mfma_f32_16x16x32_bf16 v[26:29], v[164:167], v[186:189], v[26:29]
	v_mfma_f32_16x16x32_bf16 v[22:25], v[156:159], v[194:197], v[22:25]
	v_mfma_f32_16x16x32_bf16 v[18:21], v[164:167], v[194:197], v[18:21]
	v_mfma_f32_16x16x32_bf16 v[14:17], v[156:159], v[202:205], v[14:17]
	v_mfma_f32_16x16x32_bf16 v[10:13], v[164:167], v[202:205], v[10:13]
	v_mfma_f32_16x16x32_bf16 v[6:9], v[156:159], v[210:213], v[6:9]
	v_mfma_f32_16x16x32_bf16 v[2:5], v[164:167], v[210:213], v[2:5]
	v_mfma_f32_16x16x32_bf16 v[30:33], v[160:163], v[190:193], v[30:33]
	v_mfma_f32_16x16x32_bf16 v[26:29], v[182:185], v[190:193], v[26:29]
	v_mfma_f32_16x16x32_bf16 v[22:25], v[160:163], v[198:201], v[22:25]
	v_mfma_f32_16x16x32_bf16 v[18:21], v[182:185], v[198:201], v[18:21]
	v_mfma_f32_16x16x32_bf16 v[14:17], v[160:163], v[206:209], v[14:17]
	v_mfma_f32_16x16x32_bf16 v[10:13], v[182:185], v[206:209], v[10:13]
	v_mfma_f32_16x16x32_bf16 v[6:9], v[160:163], v[214:217], v[6:9]
	v_mfma_f32_16x16x32_bf16 v[2:5], v[182:185], v[214:217], v[2:5]
	s_setprio 0
	s_barrier
	s_add_i32 s63, 0, 0x18000
	s_add_i32 s55, 0, 0x1c000
	v_add_u32_e32 v152, s63, v146
	v_add_u32_e32 v182, s55, v146
	ds_read_b128 v[136:139], v152
	ds_read_b128 v[140:143], v152 offset:1024
	ds_read_b128 v[148:151], v152 offset:2048
	ds_read_b128 v[152:155], v152 offset:3072
	ds_read_b128 v[156:159], v182
	ds_read_b128 v[160:163], v182 offset:1024
	ds_read_b128 v[164:167], v182 offset:2048
	ds_read_b128 v[182:185], v182 offset:3072
	s_add_u32 s8, s30, 0x160000
	s_addc_u32 s9, s31, 0
	s_mov_b32 m0, s36
	v_lshl_add_u64 v[224:225], s[8:9], 0, v[0:1]
	ds_read_b128 v[186:189], v147 offset:32768
	ds_read_b128 v[190:193], v147 offset:33792
	ds_read_b128 v[194:197], v147 offset:34816
	ds_read_b128 v[198:201], v147 offset:35840
	ds_read_b128 v[202:205], v147 offset:36864
	ds_read_b128 v[206:209], v147 offset:37888
	ds_read_b128 v[210:213], v147 offset:38912
	ds_read_b128 v[214:217], v147 offset:39936
	global_load_lds_dwordx4 v[224:225], off
	s_mov_b32 m0, s37
	v_lshl_add_u64 v[224:225], s[8:9], 0, v[130:131]
	global_load_lds_dwordx4 v[224:225], off
	s_waitcnt vmcnt(8)
	s_waitcnt lgkmcnt(0)
	s_barrier
	s_setprio 1
	s_waitcnt lgkmcnt(0)
	v_mfma_f32_16x16x32_bf16 v[126:129], v[136:139], v[186:189], v[126:129]
	v_mfma_f32_16x16x32_bf16 v[122:125], v[148:151], v[186:189], v[122:125]
	v_mfma_f32_16x16x32_bf16 v[118:121], v[136:139], v[194:197], v[118:121]
	v_mfma_f32_16x16x32_bf16 v[114:117], v[148:151], v[194:197], v[114:117]
	v_mfma_f32_16x16x32_bf16 v[110:113], v[136:139], v[202:205], v[110:113]
	v_mfma_f32_16x16x32_bf16 v[106:109], v[148:151], v[202:205], v[106:109]
	v_mfma_f32_16x16x32_bf16 v[102:105], v[136:139], v[210:213], v[102:105]
	v_mfma_f32_16x16x32_bf16 v[98:101], v[148:151], v[210:213], v[98:101]
	v_mfma_f32_16x16x32_bf16 v[126:129], v[140:143], v[190:193], v[126:129]
	v_mfma_f32_16x16x32_bf16 v[122:125], v[152:155], v[190:193], v[122:125]
	v_mfma_f32_16x16x32_bf16 v[118:121], v[140:143], v[198:201], v[118:121]
	v_mfma_f32_16x16x32_bf16 v[114:117], v[152:155], v[198:201], v[114:117]
	v_mfma_f32_16x16x32_bf16 v[110:113], v[140:143], v[206:209], v[110:113]
	v_mfma_f32_16x16x32_bf16 v[106:109], v[152:155], v[206:209], v[106:109]
	v_mfma_f32_16x16x32_bf16 v[102:105], v[140:143], v[214:217], v[102:105]
	v_mfma_f32_16x16x32_bf16 v[98:101], v[152:155], v[214:217], v[98:101]
	s_setprio 0
	s_setprio 1
	v_mfma_f32_16x16x32_bf16 v[94:97], v[156:159], v[186:189], v[94:97]
	v_mfma_f32_16x16x32_bf16 v[90:93], v[164:167], v[186:189], v[90:93]
	v_mfma_f32_16x16x32_bf16 v[86:89], v[156:159], v[194:197], v[86:89]
	v_mfma_f32_16x16x32_bf16 v[82:85], v[164:167], v[194:197], v[82:85]
	v_mfma_f32_16x16x32_bf16 v[78:81], v[156:159], v[202:205], v[78:81]
	v_mfma_f32_16x16x32_bf16 v[74:77], v[164:167], v[202:205], v[74:77]
	v_mfma_f32_16x16x32_bf16 v[70:73], v[156:159], v[210:213], v[70:73]
	v_mfma_f32_16x16x32_bf16 v[66:69], v[164:167], v[210:213], v[66:69]
	v_mfma_f32_16x16x32_bf16 v[94:97], v[160:163], v[190:193], v[94:97]
	v_mfma_f32_16x16x32_bf16 v[90:93], v[182:185], v[190:193], v[90:93]
	v_mfma_f32_16x16x32_bf16 v[86:89], v[160:163], v[198:201], v[86:89]
	v_mfma_f32_16x16x32_bf16 v[82:85], v[182:185], v[198:201], v[82:85]
	v_mfma_f32_16x16x32_bf16 v[78:81], v[160:163], v[206:209], v[78:81]
	v_mfma_f32_16x16x32_bf16 v[74:77], v[182:185], v[206:209], v[74:77]
	v_mfma_f32_16x16x32_bf16 v[70:73], v[160:163], v[214:217], v[70:73]
	v_mfma_f32_16x16x32_bf16 v[66:69], v[182:185], v[214:217], v[66:69]
	s_setprio 0
	s_barrier
; #define PG8_STAGE(bufoff, gbase, voff) do { _Pragma("unroll") for (int _i = 0; _i < 2; ++_i) \
;         __builtin_amdgcn_global_load_lds((const unsigned*)((const char*)(gbase) + (voff)[_i]), (PG8_LAS unsigned*)(lds + (bufoff) + ldsw + _i * 8192), 16, 0, 0); } while (0)
; #define PG8_LDA(dst, b, h) do { _Pragma("unroll") for (int m = 0; m < 4; ++m) _Pragma("unroll") for (int k = 0; k < 2; ++k) dst[m][k] = *(const PG8_LAS bf16x8*)(lds + PG8_SA(b, h) + aoff + m * 2048 + k * 1024); } while (0)
; #define PG8_LDB(dst, b, h) do { _Pragma("unroll") for (int n = 0; n < 2; ++n) _Pragma("unroll") for (int k = 0; k < 2; ++k) dst[n][k] = *(const PG8_LAS bf16x8*)(lds + PG8_SB(b, h) + boff + n * 2048 + k * 1024); } while (0)
; #define PG8_MMA(ai, bj, At, Bt) do { __builtin_amdgcn_s_setprio(1); _Pragma("unroll") for (int m = 0; m < 4; ++m) _Pragma("unroll") for (int n = 0; n < 2; ++n) _Pragma("unroll") for (int k = 0; k < 2; ++k) \
;         acc[ai][bj][m][n] = __builtin_amdgcn_mfma_f32_16x16x32_bf16(Bt[n][k], At[m][k], acc[ai][bj][m][n], 0, 0, 0); __builtin_amdgcn_s_setprio(0); } while (0)
; template <class Epi, class Sched, bool ALIGN_EPI = false, bool SP2 = false>
; __device__ __forceinline__ void gemm_phase(PG8_LAS unsigned char* lds, const Gemm g, const Sched& S, const Epi& E, int tid_in) {
;     ...
;             PG8_LDB(B0, 0, 0); PG8_LDB(B1, 0, 1); PG8_SCHED; PG8_LDA(At, 0, 0); PG8_STAGE(PG8_SA(1, 1), a1 + hstepA, voffA);
;             PG8_WAIT_V(8); PG8_WAIT_L(0); PG8_BAR; PG8_MMA(0, 0, At, B0); PG8_MMA(0, 1, At, B1); PG8_BAR; PG8_SCHED;
;             PG8_LDA(At, 0, 1); PG8_STAGE(PG8_SB(0, 0), b2, voffB); PG8_STAGE(PG8_SB(0, 1), b2 + hstep, voffB); PG8_STAGE(PG8_SA(0, 0), a2, voffA);
;             PG8_WAIT_V(8); PG8_WAIT_L(0); PG8_BAR; PG8_MMA(1, 0, At, B0); PG8_MMA(1, 1, At, B1); PG8_BAR; PG8_SCHED;
;             PG8_LDB(B0, 1, 0); PG8_LDB(B1, 1, 1); PG8_SCHED; PG8_LDA(At, 1, 0); PG8_STAGE(PG8_SA(0, 1), a2 + hstepA, voffA);
;             PG8_WAIT_V(8); PG8_WAIT_L(0); PG8_BAR; PG8_MMA(0, 0, At, B0); PG8_MMA(0, 1, At, B1); PG8_BAR; PG8_SCHED;
;             PG8_LDA(At, 1, 1); PG8_STAGE(PG8_SB(1, 0), b3, voffB); PG8_STAGE(PG8_SB(1, 1), b3 + hstep, voffB); PG8_STAGE(PG8_SA(1, 0), a3, voffA);
;             PG8_WAIT_V(8); PG8_WAIT_L(0); PG8_BAR; PG8_MMA(1, 0, At, B0); PG8_MMA(1, 1, At, B1); PG8_BAR; PG8_SCHED;
;     ...
;         if constexpr (ALIGN_EPI) { if (wr == 0) PG8_BAR; }
	s_add_i32 s8, s63, s33
	v_lshl_add_u64 v[168:169], v[168:169], 0, s[90:91]
	s_mov_b32 m0, s8
	ds_read_b128 v[186:189], v147 offset:49152
	ds_read_b128 v[190:193], v147 offset:50176
	ds_read_b128 v[194:197], v147 offset:51200
	ds_read_b128 v[198:201], v147 offset:52224
	ds_read_b128 v[202:205], v147 offset:53248
	ds_read_b128 v[206:209], v147 offset:54272
	ds_read_b128 v[210:213], v147 offset:55296
	ds_read_b128 v[214:217], v147 offset:56320
	global_load_lds_dwordx4 v[168:169], off
	s_add_i32 m0, s8, 0x2000
	s_add_u32 s8, s28, 0x160080
	v_lshl_add_u64 v[168:169], v[218:219], 0, s[90:91]
	s_addc_u32 s9, s29, 0
	s_add_i32 s28, s55, s33
	global_load_lds_dwordx4 v[168:169], off
	s_mov_b32 m0, s28
	v_lshl_add_u64 v[168:169], s[8:9], 0, v[0:1]
	global_load_lds_dwordx4 v[168:169], off
	s_add_i32 m0, s28, 0x2000
	v_lshl_add_u64 v[168:169], s[8:9], 0, v[130:131]
	global_load_lds_dwordx4 v[168:169], off
	s_mov_b32 m0, s43
	v_lshl_add_u64 v[168:169], v[220:221], 0, s[90:91]
	global_load_lds_dwordx4 v[168:169], off
	s_mov_b32 m0, s44
	v_lshl_add_u64 v[168:169], v[222:223], 0, s[90:91]
	global_load_lds_dwordx4 v[168:169], off
	s_waitcnt vmcnt(8)
	s_waitcnt lgkmcnt(0)
	s_barrier
	s_setprio 1
	s_waitcnt lgkmcnt(0)
	v_mfma_f32_16x16x32_bf16 v[62:65], v[136:139], v[186:189], v[62:65]
	v_mfma_f32_16x16x32_bf16 v[58:61], v[148:151], v[186:189], v[58:61]
	v_mfma_f32_16x16x32_bf16 v[54:57], v[136:139], v[194:197], v[54:57]
	v_mfma_f32_16x16x32_bf16 v[50:53], v[148:151], v[194:197], v[50:53]
	v_mfma_f32_16x16x32_bf16 v[46:49], v[136:139], v[202:205], v[46:49]
	v_mfma_f32_16x16x32_bf16 v[42:45], v[148:151], v[202:205], v[42:45]
	v_mfma_f32_16x16x32_bf16 v[38:41], v[136:139], v[210:213], v[38:41]
	v_mfma_f32_16x16x32_bf16 v[34:37], v[148:151], v[210:213], v[34:37]
	v_mfma_f32_16x16x32_bf16 v[62:65], v[140:143], v[190:193], v[62:65]
	v_mfma_f32_16x16x32_bf16 v[58:61], v[152:155], v[190:193], v[58:61]
	v_mfma_f32_16x16x32_bf16 v[54:57], v[140:143], v[198:201], v[54:57]
	v_mfma_f32_16x16x32_bf16 v[50:53], v[152:155], v[198:201], v[50:53]
	v_mfma_f32_16x16x32_bf16 v[46:49], v[140:143], v[206:209], v[46:49]
	v_mfma_f32_16x16x32_bf16 v[42:45], v[152:155], v[206:209], v[42:45]
	v_mfma_f32_16x16x32_bf16 v[38:41], v[140:143], v[214:217], v[38:41]
	v_mfma_f32_16x16x32_bf16 v[34:37], v[152:155], v[214:217], v[34:37]
	s_setprio 0
	s_setprio 1
	v_mfma_f32_16x16x32_bf16 v[30:33], v[156:159], v[186:189], v[30:33]
	v_mfma_f32_16x16x32_bf16 v[26:29], v[164:167], v[186:189], v[26:29]
	v_mfma_f32_16x16x32_bf16 v[22:25], v[156:159], v[194:197], v[22:25]
	v_mfma_f32_16x16x32_bf16 v[18:21], v[164:167], v[194:197], v[18:21]
	v_mfma_f32_16x16x32_bf16 v[14:17], v[156:159], v[202:205], v[14:17]
	v_mfma_f32_16x16x32_bf16 v[10:13], v[164:167], v[202:205], v[10:13]
	v_mfma_f32_16x16x32_bf16 v[6:9], v[156:159], v[210:213], v[6:9]
	v_mfma_f32_16x16x32_bf16 v[2:5], v[164:167], v[210:213], v[2:5]
	v_mfma_f32_16x16x32_bf16 v[30:33], v[160:163], v[190:193], v[30:33]
	v_mfma_f32_16x16x32_bf16 v[26:29], v[182:185], v[190:193], v[26:29]
	v_mfma_f32_16x16x32_bf16 v[22:25], v[160:163], v[198:201], v[22:25]
	v_mfma_f32_16x16x32_bf16 v[18:21], v[182:185], v[198:201], v[18:21]
	v_mfma_f32_16x16x32_bf16 v[14:17], v[160:163], v[206:209], v[14:17]
	v_mfma_f32_16x16x32_bf16 v[10:13], v[182:185], v[206:209], v[10:13]
	v_mfma_f32_16x16x32_bf16 v[6:9], v[160:163], v[214:217], v[6:9]
	v_mfma_f32_16x16x32_bf16 v[2:5], v[182:185], v[214:217], v[2:5]
	s_setprio 0
	s_barrier
	s_add_u32 s76, s76, 0x100
	s_addc_u32 s79, s79, 0
	s_cmp_ge_u32 s82, s66
	s_mov_b64 s[8:9], s[26:27]
	s_mov_b32 s28, s82
	s_cbranch_scc0 .LBB0_352
	s_and_b64 vcc, exec, s[18:19]
	s_cbranch_vccz .LBB0_355
	s_barrier

; #define PG8_STAGE(bufoff, gbase, voff) do { _Pragma("unroll") for (int _i = 0; _i < 2; ++_i) \
;         __builtin_amdgcn_global_load_lds((const unsigned*)((const char*)(gbase) + (voff)[_i]), (PG8_LAS unsigned*)(lds + (bufoff) + ldsw + _i * 8192), 16, 0, 0); } while (0)
; #define PG8_LDA(dst, b, h) do { _Pragma("unroll") for (int m = 0; m < 4; ++m) _Pragma("unroll") for (int k = 0; k < 2; ++k) dst[m][k] = *(const PG8_LAS bf16x8*)(lds + PG8_SA(b, h) + aoff + m * 2048 + k * 1024); } while (0)
; #define PG8_LDB(dst, b, h) do { _Pragma("unroll") for (int n = 0; n < 2; ++n) _Pragma("unroll") for (int k = 0; k < 2; ++k) dst[n][k] = *(const PG8_LAS bf16x8*)(lds + PG8_SB(b, h) + boff + n * 2048 + k * 1024); } while (0)
; #define PG8_MMA(ai, bj, At, Bt) do { __builtin_amdgcn_s_setprio(1); _Pragma("unroll") for (int m = 0; m < 4; ++m) _Pragma("unroll") for (int n = 0; n < 2; ++n) _Pragma("unroll") for (int k = 0; k < 2; ++k) \
;         acc[ai][bj][m][n] = __builtin_amdgcn_mfma_f32_16x16x32_bf16(Bt[n][k], At[m][k], acc[ai][bj][m][n], 0, 0, 0); __builtin_amdgcn_s_setprio(0); } while (0)
; #define PG8_WAIT_V(n) asm volatile("s_waitcnt vmcnt(" #n ")" ::: "memory")
; #define PG8_WAIT_L(n) asm volatile("s_waitcnt lgkmcnt(" #n ")" ::: "memory")
; template <class Epi, class Sched, bool ALIGN_EPI = false, bool SP2 = false>
; __device__ __forceinline__ void gemm_phase(PG8_LAS unsigned char* lds, const Gemm g, const Sched& S, const Epi& E, int tid_in) {
;     ...
;             const bool last = (t == nt - 2);
;             const char* a1 = cA + (size_t)(t + 1) * kstep;
;             const char* a2 = last ? nA : cA + (size_t)(t + 2) * kstep; const char* b2 = last ? nB : cB + (size_t)(t + 2) * kstep;
;             const char* a3 = a2 + kstep; const char* b3 = b2 + kstep;
;             if (last && has_next) S.a_ready(nxt);
;             if constexpr (SP2) {
;             PG8_LDB(B0, 0, 0); PG8_LDB(B1, 0, 1); PG8_SCHED; PG8_LDA(At, 0, 0); PG8_STAGE(PG8_SA(1, 1), a1 + hstepA, voffA);
;             PG8_WAIT_V(8); PG8_WAIT_L(0); PG8_BAR; PG8_MMA(0, 0, At, B0); PG8_MMA(0, 1, At, B1); PG8_BAR; PG8_SCHED;
;             PG8_LDA(At, 0, 1); PG8_STAGE(PG8_SB(0, 0), b2, voffB); PG8_STAGE(PG8_SB(0, 1), b2 + hstep, voffB); PG8_STAGE(PG8_SA(0, 0), a2, voffA);
;             PG8_WAIT_V(8); PG8_WAIT_L(0); PG8_BAR; PG8_MMA(1, 0, At, B0); PG8_MMA(1, 1, At, B1); PG8_BAR; PG8_SCHED;
.LBB0_513:
	v_add_u32_e32 v150, s4, v157
	ds_read_b128 v[142:145], v150
	ds_read_b128 v[146:149], v150 offset:1024
	ds_read_b128 v[152:155], v150 offset:2048
	ds_read_b128 v[160:163], v150 offset:3072
	v_add_u32_e32 v150, s5, v157
	ds_read_b128 v[164:167], v150
	ds_read_b128 v[182:185], v150 offset:1024
	ds_read_b128 v[186:189], v150 offset:2048
	ds_read_b128 v[190:193], v150 offset:3072
	s_add_u32 s28, s14, 0xfff80080
	s_addc_u32 s29, s15, -1
	s_cmp_eq_u32 s23, 28
	s_cselect_b32 s31, s25, s29
	s_cselect_b32 s30, s24, s28
	s_cselect_b32 s29, s27, s21
	s_cselect_b32 s28, s26, s13
	v_lshl_add_u64 v[168:169], s[14:15], 0, v[138:139]
	s_add_i32 m0, s38, 0xc000
	ds_read_b128 v[194:197], v158
	ds_read_b128 v[198:201], v158 offset:1024
	ds_read_b128 v[202:205], v158 offset:2048
	ds_read_b128 v[206:209], v158 offset:3072
	ds_read_b128 v[210:213], v158 offset:4096
	ds_read_b128 v[214:217], v158 offset:5120
	ds_read_b128 v[218:221], v158 offset:6144
	ds_read_b128 v[222:225], v158 offset:7168
	global_load_lds_dwordx4 v[168:169], off
	s_add_i32 m0, s38, 0xe000
	v_lshl_add_u64 v[168:169], s[14:15], 0, v[140:141]
	global_load_lds_dwordx4 v[168:169], off
	s_waitcnt vmcnt(8)
	s_waitcnt lgkmcnt(0)
	s_barrier
	s_setprio 1
	s_waitcnt lgkmcnt(0)
	v_mfma_f32_16x16x32_bf16 v[126:129], v[142:145], v[194:197], v[126:129]
	v_mfma_f32_16x16x32_bf16 v[122:125], v[152:155], v[194:197], v[122:125]
	v_mfma_f32_16x16x32_bf16 v[110:113], v[142:145], v[202:205], v[110:113]
	v_mfma_f32_16x16x32_bf16 v[106:109], v[152:155], v[202:205], v[106:109]
	v_mfma_f32_16x16x32_bf16 v[94:97], v[142:145], v[210:213], v[94:97]
	v_mfma_f32_16x16x32_bf16 v[90:93], v[152:155], v[210:213], v[90:93]
	v_mfma_f32_16x16x32_bf16 v[78:81], v[142:145], v[218:221], v[78:81]
	v_mfma_f32_16x16x32_bf16 v[74:77], v[152:155], v[218:221], v[74:77]
	v_mfma_f32_16x16x32_bf16 v[126:129], v[146:149], v[198:201], v[126:129]
	v_mfma_f32_16x16x32_bf16 v[122:125], v[160:163], v[198:201], v[122:125]
	v_mfma_f32_16x16x32_bf16 v[110:113], v[146:149], v[206:209], v[110:113]
	v_mfma_f32_16x16x32_bf16 v[106:109], v[160:163], v[206:209], v[106:109]
	v_mfma_f32_16x16x32_bf16 v[94:97], v[146:149], v[214:217], v[94:97]
	v_mfma_f32_16x16x32_bf16 v[90:93], v[160:163], v[214:217], v[90:93]
	v_mfma_f32_16x16x32_bf16 v[78:81], v[146:149], v[222:225], v[78:81]
	v_mfma_f32_16x16x32_bf16 v[74:77], v[160:163], v[222:225], v[74:77]
	s_setprio 0
	s_setprio 1
	v_mfma_f32_16x16x32_bf16 v[118:121], v[164:167], v[194:197], v[118:121]
	v_mfma_f32_16x16x32_bf16 v[114:117], v[186:189], v[194:197], v[114:117]
	v_mfma_f32_16x16x32_bf16 v[102:105], v[164:167], v[202:205], v[102:105]
	v_mfma_f32_16x16x32_bf16 v[98:101], v[186:189], v[202:205], v[98:101]
	v_mfma_f32_16x16x32_bf16 v[86:89], v[164:167], v[210:213], v[86:89]
	v_mfma_f32_16x16x32_bf16 v[82:85], v[186:189], v[210:213], v[82:85]
	v_mfma_f32_16x16x32_bf16 v[70:73], v[164:167], v[218:221], v[70:73]
	v_mfma_f32_16x16x32_bf16 v[66:69], v[186:189], v[218:221], v[66:69]
	v_mfma_f32_16x16x32_bf16 v[118:121], v[182:185], v[198:201], v[118:121]
	v_mfma_f32_16x16x32_bf16 v[114:117], v[190:193], v[198:201], v[114:117]
	v_mfma_f32_16x16x32_bf16 v[102:105], v[182:185], v[206:209], v[102:105]
	v_mfma_f32_16x16x32_bf16 v[98:101], v[190:193], v[206:209], v[98:101]
	v_mfma_f32_16x16x32_bf16 v[86:89], v[182:185], v[214:217], v[86:89]
	v_mfma_f32_16x16x32_bf16 v[82:85], v[190:193], v[214:217], v[82:85]
	v_mfma_f32_16x16x32_bf16 v[70:73], v[182:185], v[222:225], v[70:73]
	v_mfma_f32_16x16x32_bf16 v[66:69], v[190:193], v[222:225], v[66:69]
	s_setprio 0
	s_barrier
	s_add_i32 s46, s4, s37
	v_lshl_add_u64 v[168:169], s[28:29], 0, v[0:1]
	s_mov_b32 m0, s46
	ds_read_b128 v[194:197], v158 offset:16384
	ds_read_b128 v[198:201], v158 offset:17408
	ds_read_b128 v[202:205], v158 offset:18432
	ds_read_b128 v[206:209], v158 offset:19456
	ds_read_b128 v[210:213], v158 offset:20480
	ds_read_b128 v[214:217], v158 offset:21504
	ds_read_b128 v[218:221], v158 offset:22528
	ds_read_b128 v[222:225], v158 offset:23552
	global_load_lds_dwordx4 v[168:169], off
	s_add_i32 m0, s46, 0x2000
	s_add_u32 s46, s28, 0x80000
	v_lshl_add_u64 v[226:227], s[28:29], 0, v[134:135]
	s_addc_u32 s47, s29, 0
	s_add_i32 s64, s5, s37
	global_load_lds_dwordx4 v[226:227], off
	v_lshl_add_u64 v[228:229], s[46:47], 0, v[0:1]
	s_mov_b32 m0, s64
	v_lshl_add_u64 v[240:241], s[30:31], 0, v[132:133]
	global_load_lds_dwordx4 v[228:229], off
	s_add_i32 m0, s64, 0x2000
	v_lshl_add_u64 v[228:229], s[46:47], 0, v[134:135]
	global_load_lds_dwordx4 v[228:229], off
	s_mov_b32 m0, s38
	v_lshl_add_u64 v[228:229], s[30:31], 0, v[130:131]
	global_load_lds_dwordx4 v[228:229], off
	s_mov_b32 m0, s39
	s_nop 0
	global_load_lds_dwordx4 v[240:241], off
	s_waitcnt vmcnt(8)
	s_waitcnt lgkmcnt(0)
	s_barrier
; #define PG8_STAGE(bufoff, gbase, voff) do { _Pragma("unroll") for (int _i = 0; _i < 2; ++_i) \
;         __builtin_amdgcn_global_load_lds((const unsigned*)((const char*)(gbase) + (voff)[_i]), (PG8_LAS unsigned*)(lds + (bufoff) + ldsw + _i * 8192), 16, 0, 0); } while (0)
; #define PG8_LDA(dst, b, h) do { _Pragma("unroll") for (int m = 0; m < 4; ++m) _Pragma("unroll") for (int k = 0; k < 2; ++k) dst[m][k] = *(const PG8_LAS bf16x8*)(lds + PG8_SA(b, h) + aoff + m * 2048 + k * 1024); } while (0)
; #define PG8_LDB(dst, b, h) do { _Pragma("unroll") for (int n = 0; n < 2; ++n) _Pragma("unroll") for (int k = 0; k < 2; ++k) dst[n][k] = *(const PG8_LAS bf16x8*)(lds + PG8_SB(b, h) + boff + n * 2048 + k * 1024); } while (0)
; #define PG8_MMA(ai, bj, At, Bt) do { __builtin_amdgcn_s_setprio(1); _Pragma("unroll") for (int m = 0; m < 4; ++m) _Pragma("unroll") for (int n = 0; n < 2; ++n) _Pragma("unroll") for (int k = 0; k < 2; ++k) \
;         acc[ai][bj][m][n] = __builtin_amdgcn_mfma_f32_16x16x32_bf16(Bt[n][k], At[m][k], acc[ai][bj][m][n], 0, 0, 0); __builtin_amdgcn_s_setprio(0); } while (0)
; #define PG8_WAIT_V(n) asm volatile("s_waitcnt vmcnt(" #n ")" ::: "memory")
; #define PG8_WAIT_L(n) asm volatile("s_waitcnt lgkmcnt(" #n ")" ::: "memory")
; #define PG8_BAR __builtin_amdgcn_s_barrier()
; #define PG8_SCHED __builtin_amdgcn_sched_barrier(0)
; template <class Epi, class Sched, bool ALIGN_EPI = false, bool SP2 = false>
; __device__ __forceinline__ void gemm_phase(PG8_LAS unsigned char* lds, const Gemm g, const Sched& S, const Epi& E, int tid_in) {
;     ...
;             PG8_WAIT_V(8); PG8_WAIT_L(0); PG8_BAR; PG8_MMA(1, 0, At, B0); PG8_MMA(1, 1, At, B1); PG8_BAR; PG8_SCHED;
;             PG8_LDB(B0, 1, 0); PG8_LDB(B1, 1, 1); PG8_SCHED; PG8_LDA(At, 1, 0); PG8_STAGE(PG8_SA(0, 1), a2 + hstepA, voffA);
;             PG8_WAIT_V(8); PG8_WAIT_L(0); PG8_BAR; PG8_MMA(0, 0, At, B0); PG8_MMA(0, 1, At, B1); PG8_BAR; PG8_SCHED;
	s_setprio 1
	s_waitcnt lgkmcnt(0)
	v_mfma_f32_16x16x32_bf16 v[62:65], v[142:145], v[194:197], v[62:65]
	v_mfma_f32_16x16x32_bf16 v[58:61], v[152:155], v[194:197], v[58:61]
	v_mfma_f32_16x16x32_bf16 v[46:49], v[142:145], v[202:205], v[46:49]
	v_mfma_f32_16x16x32_bf16 v[42:45], v[152:155], v[202:205], v[42:45]
	v_mfma_f32_16x16x32_bf16 v[30:33], v[142:145], v[210:213], v[30:33]
	v_mfma_f32_16x16x32_bf16 v[26:29], v[152:155], v[210:213], v[26:29]
	v_mfma_f32_16x16x32_bf16 v[14:17], v[142:145], v[218:221], v[14:17]
	v_mfma_f32_16x16x32_bf16 v[10:13], v[152:155], v[218:221], v[10:13]
	v_mfma_f32_16x16x32_bf16 v[62:65], v[146:149], v[198:201], v[62:65]
	v_mfma_f32_16x16x32_bf16 v[58:61], v[160:163], v[198:201], v[58:61]
	v_mfma_f32_16x16x32_bf16 v[46:49], v[146:149], v[206:209], v[46:49]
	v_mfma_f32_16x16x32_bf16 v[42:45], v[160:163], v[206:209], v[42:45]
	v_mfma_f32_16x16x32_bf16 v[30:33], v[146:149], v[214:217], v[30:33]
	v_mfma_f32_16x16x32_bf16 v[26:29], v[160:163], v[214:217], v[26:29]
	v_mfma_f32_16x16x32_bf16 v[14:17], v[146:149], v[222:225], v[14:17]
	v_mfma_f32_16x16x32_bf16 v[10:13], v[160:163], v[222:225], v[10:13]
	s_setprio 0
	s_setprio 1
	v_mfma_f32_16x16x32_bf16 v[54:57], v[164:167], v[194:197], v[54:57]
	v_mfma_f32_16x16x32_bf16 v[50:53], v[186:189], v[194:197], v[50:53]
	v_mfma_f32_16x16x32_bf16 v[38:41], v[164:167], v[202:205], v[38:41]
	v_mfma_f32_16x16x32_bf16 v[34:37], v[186:189], v[202:205], v[34:37]
	v_mfma_f32_16x16x32_bf16 v[22:25], v[164:167], v[210:213], v[22:25]
	v_mfma_f32_16x16x32_bf16 v[18:21], v[186:189], v[210:213], v[18:21]
	v_mfma_f32_16x16x32_bf16 v[6:9], v[164:167], v[218:221], v[6:9]
	v_mfma_f32_16x16x32_bf16 v[2:5], v[186:189], v[218:221], v[2:5]
	v_mfma_f32_16x16x32_bf16 v[54:57], v[182:185], v[198:201], v[54:57]
	v_mfma_f32_16x16x32_bf16 v[50:53], v[190:193], v[198:201], v[50:53]
	v_mfma_f32_16x16x32_bf16 v[38:41], v[182:185], v[206:209], v[38:41]
	v_mfma_f32_16x16x32_bf16 v[34:37], v[190:193], v[206:209], v[34:37]
	v_mfma_f32_16x16x32_bf16 v[22:25], v[182:185], v[214:217], v[22:25]
	v_mfma_f32_16x16x32_bf16 v[18:21], v[190:193], v[214:217], v[18:21]
	v_mfma_f32_16x16x32_bf16 v[6:9], v[182:185], v[222:225], v[6:9]
	v_mfma_f32_16x16x32_bf16 v[2:5], v[190:193], v[222:225], v[2:5]
	s_setprio 0
	s_barrier
	v_add_u32_e32 v150, s63, v157
	ds_read_b128 v[142:145], v150
	ds_read_b128 v[146:149], v150 offset:1024
	ds_read_b128 v[152:155], v150 offset:2048
	ds_read_b128 v[160:163], v150 offset:3072
	v_add_u32_e32 v150, s55, v157
	ds_read_b128 v[164:167], v150
	ds_read_b128 v[182:185], v150 offset:1024
	ds_read_b128 v[186:189], v150 offset:2048
	ds_read_b128 v[190:193], v150 offset:3072
	s_add_u32 s30, s30, 0x80000
	s_addc_u32 s31, s31, 0
	s_mov_b32 m0, s40
	v_lshl_add_u64 v[242:243], s[30:31], 0, v[130:131]
	ds_read_b128 v[194:197], v158 offset:32768
	ds_read_b128 v[198:201], v158 offset:33792
	ds_read_b128 v[202:205], v158 offset:34816
	ds_read_b128 v[206:209], v158 offset:35840
	ds_read_b128 v[210:213], v158 offset:36864
	ds_read_b128 v[214:217], v158 offset:37888
	ds_read_b128 v[218:221], v158 offset:38912
	ds_read_b128 v[222:225], v158 offset:39936
	global_load_lds_dwordx4 v[242:243], off
	s_mov_b32 m0, s41
	v_lshl_add_u64 v[242:243], s[30:31], 0, v[132:133]
	global_load_lds_dwordx4 v[242:243], off
	s_waitcnt vmcnt(8)
	s_waitcnt lgkmcnt(0)
	s_barrier
	s_setprio 1
	s_waitcnt lgkmcnt(0)
	v_mfma_f32_16x16x32_bf16 v[126:129], v[142:145], v[194:197], v[126:129]
	v_mfma_f32_16x16x32_bf16 v[122:125], v[152:155], v[194:197], v[122:125]
	v_mfma_f32_16x16x32_bf16 v[110:113], v[142:145], v[202:205], v[110:113]
	v_mfma_f32_16x16x32_bf16 v[106:109], v[152:155], v[202:205], v[106:109]
	v_mfma_f32_16x16x32_bf16 v[94:97], v[142:145], v[210:213], v[94:97]
	v_mfma_f32_16x16x32_bf16 v[90:93], v[152:155], v[210:213], v[90:93]
	v_mfma_f32_16x16x32_bf16 v[78:81], v[142:145], v[218:221], v[78:81]
	v_mfma_f32_16x16x32_bf16 v[74:77], v[152:155], v[218:221], v[74:77]
	v_mfma_f32_16x16x32_bf16 v[126:129], v[146:149], v[198:201], v[126:129]
	v_mfma_f32_16x16x32_bf16 v[122:125], v[160:163], v[198:201], v[122:125]
	v_mfma_f32_16x16x32_bf16 v[110:113], v[146:149], v[206:209], v[110:113]
	v_mfma_f32_16x16x32_bf16 v[106:109], v[160:163], v[206:209], v[106:109]
	v_mfma_f32_16x16x32_bf16 v[94:97], v[146:149], v[214:217], v[94:97]
	v_mfma_f32_16x16x32_bf16 v[90:93], v[160:163], v[214:217], v[90:93]
	v_mfma_f32_16x16x32_bf16 v[78:81], v[146:149], v[222:225], v[78:81]
	v_mfma_f32_16x16x32_bf16 v[74:77], v[160:163], v[222:225], v[74:77]
	s_setprio 0
	s_setprio 1
	v_mfma_f32_16x16x32_bf16 v[118:121], v[164:167], v[194:197], v[118:121]
	v_mfma_f32_16x16x32_bf16 v[114:117], v[186:189], v[194:197], v[114:117]
	v_mfma_f32_16x16x32_bf16 v[102:105], v[164:167], v[202:205], v[102:105]
	v_mfma_f32_16x16x32_bf16 v[98:101], v[186:189], v[202:205], v[98:101]
	v_mfma_f32_16x16x32_bf16 v[86:89], v[164:167], v[210:213], v[86:89]
	v_mfma_f32_16x16x32_bf16 v[82:85], v[186:189], v[210:213], v[82:85]
	v_mfma_f32_16x16x32_bf16 v[70:73], v[164:167], v[218:221], v[70:73]
	v_mfma_f32_16x16x32_bf16 v[66:69], v[186:189], v[218:221], v[66:69]
	v_mfma_f32_16x16x32_bf16 v[118:121], v[182:185], v[198:201], v[118:121]
	v_mfma_f32_16x16x32_bf16 v[114:117], v[190:193], v[198:201], v[114:117]
	v_mfma_f32_16x16x32_bf16 v[102:105], v[182:185], v[206:209], v[102:105]
	v_mfma_f32_16x16x32_bf16 v[98:101], v[190:193], v[206:209], v[98:101]
	v_mfma_f32_16x16x32_bf16 v[86:89], v[182:185], v[214:217], v[86:89]
	v_mfma_f32_16x16x32_bf16 v[82:85], v[190:193], v[214:217], v[82:85]
	v_mfma_f32_16x16x32_bf16 v[70:73], v[182:185], v[222:225], v[70:73]
	v_mfma_f32_16x16x32_bf16 v[66:69], v[190:193], v[222:225], v[66:69]
	s_setprio 0
	s_barrier
; #define PG8_STAGE(bufoff, gbase, voff) do { _Pragma("unroll") for (int _i = 0; _i < 2; ++_i) \
;         __builtin_amdgcn_global_load_lds((const unsigned*)((const char*)(gbase) + (voff)[_i]), (PG8_LAS unsigned*)(lds + (bufoff) + ldsw + _i * 8192), 16, 0, 0); } while (0)
; #define PG8_LDA(dst, b, h) do { _Pragma("unroll") for (int m = 0; m < 4; ++m) _Pragma("unroll") for (int k = 0; k < 2; ++k) dst[m][k] = *(const PG8_LAS bf16x8*)(lds + PG8_SA(b, h) + aoff + m * 2048 + k * 1024); } while (0)
; #define PG8_MMA(ai, bj, At, Bt) do { __builtin_amdgcn_s_setprio(1); _Pragma("unroll") for (int m = 0; m < 4; ++m) _Pragma("unroll") for (int n = 0; n < 2; ++n) _Pragma("unroll") for (int k = 0; k < 2; ++k) \
;         acc[ai][bj][m][n] = __builtin_amdgcn_mfma_f32_16x16x32_bf16(Bt[n][k], At[m][k], acc[ai][bj][m][n], 0, 0, 0); __builtin_amdgcn_s_setprio(0); } while (0)
; #define PG8_WAIT_V(n) asm volatile("s_waitcnt vmcnt(" #n ")" ::: "memory")
; #define PG8_WAIT_L(n) asm volatile("s_waitcnt lgkmcnt(" #n ")" ::: "memory")
; #define PG8_BAR __builtin_amdgcn_s_barrier()
; #define PG8_SCHED __builtin_amdgcn_sched_barrier(0)
; template <class Epi, class Sched, bool ALIGN_EPI = false, bool SP2 = false>
; __device__ __forceinline__ void gemm_phase(PG8_LAS unsigned char* lds, const Gemm g, const Sched& S, const Epi& E, int tid_in) {
;     ...
;         for (int t = 0; t < nt; t += 2) {
;             const bool last = (t == nt - 2);
;     ...
;             PG8_LDA(At, 1, 1); PG8_STAGE(PG8_SB(1, 0), b3, voffB); PG8_STAGE(PG8_SB(1, 1), b3 + hstep, voffB); PG8_STAGE(PG8_SA(1, 0), a3, voffA);
;             PG8_WAIT_V(8); PG8_WAIT_L(0); PG8_BAR; PG8_MMA(1, 0, At, B0); PG8_MMA(1, 1, At, B1); PG8_BAR; PG8_SCHED;
	s_add_i32 s30, s63, s37
	v_lshl_add_u64 v[168:169], v[168:169], 0, s[90:91]
	s_mov_b32 m0, s30
	ds_read_b128 v[194:197], v158 offset:49152
	ds_read_b128 v[198:201], v158 offset:50176
	ds_read_b128 v[202:205], v158 offset:51200
	ds_read_b128 v[206:209], v158 offset:52224
	ds_read_b128 v[210:213], v158 offset:53248
	ds_read_b128 v[214:217], v158 offset:54272
	ds_read_b128 v[218:221], v158 offset:55296
	ds_read_b128 v[222:225], v158 offset:56320
	global_load_lds_dwordx4 v[168:169], off
	s_add_i32 m0, s30, 0x2000
	s_add_u32 s28, s28, 0x80080
	v_lshl_add_u64 v[168:169], v[226:227], 0, s[90:91]
	s_addc_u32 s29, s29, 0
	s_add_i32 s30, s55, s37
	global_load_lds_dwordx4 v[168:169], off
	s_mov_b32 m0, s30
	v_lshl_add_u64 v[168:169], s[28:29], 0, v[0:1]
	global_load_lds_dwordx4 v[168:169], off
	s_add_i32 m0, s30, 0x2000
	v_lshl_add_u64 v[168:169], s[28:29], 0, v[134:135]
	global_load_lds_dwordx4 v[168:169], off
	s_mov_b32 m0, s45
	v_lshl_add_u64 v[168:169], v[228:229], 0, s[90:91]
	global_load_lds_dwordx4 v[168:169], off
	s_mov_b32 m0, s48
	v_lshl_add_u64 v[168:169], v[240:241], 0, s[90:91]
	global_load_lds_dwordx4 v[168:169], off
	s_waitcnt vmcnt(8)
	s_waitcnt lgkmcnt(0)
	s_barrier
	s_setprio 1
	s_waitcnt lgkmcnt(0)
	v_mfma_f32_16x16x32_bf16 v[62:65], v[142:145], v[194:197], v[62:65]
	v_mfma_f32_16x16x32_bf16 v[58:61], v[152:155], v[194:197], v[58:61]
	v_mfma_f32_16x16x32_bf16 v[46:49], v[142:145], v[202:205], v[46:49]
	v_mfma_f32_16x16x32_bf16 v[42:45], v[152:155], v[202:205], v[42:45]
	v_mfma_f32_16x16x32_bf16 v[30:33], v[142:145], v[210:213], v[30:33]
	v_mfma_f32_16x16x32_bf16 v[26:29], v[152:155], v[210:213], v[26:29]
	v_mfma_f32_16x16x32_bf16 v[14:17], v[142:145], v[218:221], v[14:17]
	v_mfma_f32_16x16x32_bf16 v[10:13], v[152:155], v[218:221], v[10:13]
	v_mfma_f32_16x16x32_bf16 v[62:65], v[146:149], v[198:201], v[62:65]
	v_mfma_f32_16x16x32_bf16 v[58:61], v[160:163], v[198:201], v[58:61]
	v_mfma_f32_16x16x32_bf16 v[46:49], v[146:149], v[206:209], v[46:49]
	v_mfma_f32_16x16x32_bf16 v[42:45], v[160:163], v[206:209], v[42:45]
	v_mfma_f32_16x16x32_bf16 v[30:33], v[146:149], v[214:217], v[30:33]
	v_mfma_f32_16x16x32_bf16 v[26:29], v[160:163], v[214:217], v[26:29]
	v_mfma_f32_16x16x32_bf16 v[14:17], v[146:149], v[222:225], v[14:17]
	v_mfma_f32_16x16x32_bf16 v[10:13], v[160:163], v[222:225], v[10:13]
	s_setprio 0
	s_setprio 1
	v_mfma_f32_16x16x32_bf16 v[54:57], v[164:167], v[194:197], v[54:57]
	v_mfma_f32_16x16x32_bf16 v[50:53], v[186:189], v[194:197], v[50:53]
	v_mfma_f32_16x16x32_bf16 v[38:41], v[164:167], v[202:205], v[38:41]
	v_mfma_f32_16x16x32_bf16 v[34:37], v[186:189], v[202:205], v[34:37]
	v_mfma_f32_16x16x32_bf16 v[22:25], v[164:167], v[210:213], v[22:25]
	v_mfma_f32_16x16x32_bf16 v[18:21], v[186:189], v[210:213], v[18:21]
	v_mfma_f32_16x16x32_bf16 v[6:9], v[164:167], v[218:221], v[6:9]
	v_mfma_f32_16x16x32_bf16 v[2:5], v[186:189], v[218:221], v[2:5]
	v_mfma_f32_16x16x32_bf16 v[54:57], v[182:185], v[198:201], v[54:57]
	v_mfma_f32_16x16x32_bf16 v[50:53], v[190:193], v[198:201], v[50:53]
	v_mfma_f32_16x16x32_bf16 v[38:41], v[182:185], v[206:209], v[38:41]
	v_mfma_f32_16x16x32_bf16 v[34:37], v[190:193], v[206:209], v[34:37]
	v_mfma_f32_16x16x32_bf16 v[22:25], v[182:185], v[214:217], v[22:25]
	v_mfma_f32_16x16x32_bf16 v[18:21], v[190:193], v[214:217], v[18:21]
	v_mfma_f32_16x16x32_bf16 v[6:9], v[182:185], v[222:225], v[6:9]
	v_mfma_f32_16x16x32_bf16 v[2:5], v[190:193], v[222:225], v[2:5]
	s_setprio 0
	s_barrier
	s_add_i32 s23, s23, 2
	s_add_u32 s14, s14, 0x100
	s_addc_u32 s15, s15, 0
	s_add_u32 s13, s13, 0x100
	s_addc_u32 s21, s21, 0
	s_cmp_gt_u32 s23, 29
	s_cbranch_scc0 .LBB0_513
	s_and_b64 vcc, exec, s[18:19]
	s_cbranch_vccz .LBB0_516
	s_barrier

; #define PG8_STAGE(bufoff, gbase, voff) do { _Pragma("unroll") for (int _i = 0; _i < 2; ++_i) \
;         __builtin_amdgcn_global_load_lds((const unsigned*)((const char*)(gbase) + (voff)[_i]), (PG8_LAS unsigned*)(lds + (bufoff) + ldsw + _i * 8192), 16, 0, 0); } while (0)
; #define PG8_LDA(dst, b, h) do { _Pragma("unroll") for (int m = 0; m < 4; ++m) _Pragma("unroll") for (int k = 0; k < 2; ++k) dst[m][k] = *(const PG8_LAS bf16x8*)(lds + PG8_SA(b, h) + aoff + m * 2048 + k * 1024); } while (0)
; #define PG8_LDB(dst, b, h) do { _Pragma("unroll") for (int n = 0; n < 2; ++n) _Pragma("unroll") for (int k = 0; k < 2; ++k) dst[n][k] = *(const PG8_LAS bf16x8*)(lds + PG8_SB(b, h) + boff + n * 2048 + k * 1024); } while (0)
; #define PG8_MMA(ai, bj, At, Bt) do { __builtin_amdgcn_s_setprio(1); _Pragma("unroll") for (int m = 0; m < 4; ++m) _Pragma("unroll") for (int n = 0; n < 2; ++n) _Pragma("unroll") for (int k = 0; k < 2; ++k) \
;         acc[ai][bj][m][n] = __builtin_amdgcn_mfma_f32_16x16x32_bf16(Bt[n][k], At[m][k], acc[ai][bj][m][n], 0, 0, 0); __builtin_amdgcn_s_setprio(0); } while (0)
; #define PG8_WAIT_V(n) asm volatile("s_waitcnt vmcnt(" #n ")" ::: "memory")
; #define PG8_WAIT_L(n) asm volatile("s_waitcnt lgkmcnt(" #n ")" ::: "memory")
; template <class Epi, class Sched, bool ALIGN_EPI = false, bool SP2 = false>
; __device__ __forceinline__ void gemm_phase(PG8_LAS unsigned char* lds, const Gemm g, const Sched& S, const Epi& E, int tid_in) {
;     ...
;             const bool last = (t == nt - 2);
;             const char* a1 = cA + (size_t)(t + 1) * kstep;
;             const char* a2 = last ? nA : cA + (size_t)(t + 2) * kstep; const char* b2 = last ? nB : cB + (size_t)(t + 2) * kstep;
;             const char* a3 = a2 + kstep; const char* b3 = b2 + kstep;
;             if (last && has_next) S.a_ready(nxt);
;             if constexpr (SP2) {
;             PG8_LDB(B0, 0, 0); PG8_LDB(B1, 0, 1); PG8_SCHED; PG8_LDA(At, 0, 0); PG8_STAGE(PG8_SA(1, 1), a1 + hstepA, voffA);
;             PG8_WAIT_V(8); PG8_WAIT_L(0); PG8_BAR; PG8_MMA(0, 0, At, B0); PG8_MMA(0, 1, At, B1); PG8_BAR; PG8_SCHED;
;             PG8_LDA(At, 0, 1); PG8_STAGE(PG8_SB(0, 0), b2, voffB); PG8_STAGE(PG8_SB(0, 1), b2 + hstep, voffB); PG8_STAGE(PG8_SA(0, 0), a2, voffA);
;             PG8_WAIT_V(8); PG8_WAIT_L(0); PG8_BAR; PG8_MMA(1, 0, At, B0); PG8_MMA(1, 1, At, B1); PG8_BAR; PG8_SCHED;
.LBB0_627:
	v_add_u32_e32 v140, s4, v145
	ds_read_b128 v[148:151], v140
	ds_read_b128 v[152:155], v140 offset:1024
	ds_read_b128 v[156:159], v140 offset:2048
	ds_read_b128 v[160:163], v140 offset:3072
	v_add_u32_e32 v140, s5, v145
	ds_read_b128 v[164:167], v140
	ds_read_b128 v[182:185], v140 offset:1024
	ds_read_b128 v[186:189], v140 offset:2048
	ds_read_b128 v[190:193], v140 offset:3072
	s_add_u32 s22, s20, 0x100
	s_addc_u32 s23, s21, 0
	s_cmp_eq_u32 s48, 4
	s_cselect_b32 s27, s17, s23
	s_cselect_b32 s26, s16, s22
	s_cselect_b32 s25, s19, s15
	s_cselect_b32 s24, s18, s0
	v_lshl_add_u64 v[168:169], s[20:21], 0, v[136:137]
	s_add_i32 m0, s34, 0xc000
	ds_read_b128 v[194:197], v147
	ds_read_b128 v[198:201], v147 offset:1024
	ds_read_b128 v[202:205], v147 offset:2048
	ds_read_b128 v[206:209], v147 offset:3072
	ds_read_b128 v[210:213], v147 offset:4096
	ds_read_b128 v[214:217], v147 offset:5120
	ds_read_b128 v[218:221], v147 offset:6144
	ds_read_b128 v[222:225], v147 offset:7168
	global_load_lds_dwordx4 v[168:169], off
	s_add_i32 m0, s34, 0xe000
	v_lshl_add_u64 v[168:169], s[20:21], 0, v[138:139]
	global_load_lds_dwordx4 v[168:169], off
	s_waitcnt vmcnt(8)
	s_waitcnt lgkmcnt(0)
	s_barrier
	s_setprio 1
	s_waitcnt lgkmcnt(0)
	v_mfma_f32_16x16x32_bf16 v[126:129], v[148:151], v[194:197], v[126:129]
	v_mfma_f32_16x16x32_bf16 v[122:125], v[156:159], v[194:197], v[122:125]
	v_mfma_f32_16x16x32_bf16 v[114:117], v[148:151], v[202:205], v[114:117]
	v_mfma_f32_16x16x32_bf16 v[106:109], v[156:159], v[202:205], v[106:109]
	v_mfma_f32_16x16x32_bf16 v[98:101], v[148:151], v[210:213], v[98:101]
	v_mfma_f32_16x16x32_bf16 v[90:93], v[156:159], v[210:213], v[90:93]
	v_mfma_f32_16x16x32_bf16 v[82:85], v[148:151], v[218:221], v[82:85]
	v_mfma_f32_16x16x32_bf16 v[74:77], v[156:159], v[218:221], v[74:77]
	v_mfma_f32_16x16x32_bf16 v[126:129], v[152:155], v[198:201], v[126:129]
	v_mfma_f32_16x16x32_bf16 v[122:125], v[160:163], v[198:201], v[122:125]
	v_mfma_f32_16x16x32_bf16 v[114:117], v[152:155], v[206:209], v[114:117]
	v_mfma_f32_16x16x32_bf16 v[106:109], v[160:163], v[206:209], v[106:109]
	v_mfma_f32_16x16x32_bf16 v[98:101], v[152:155], v[214:217], v[98:101]
	v_mfma_f32_16x16x32_bf16 v[90:93], v[160:163], v[214:217], v[90:93]
	v_mfma_f32_16x16x32_bf16 v[82:85], v[152:155], v[222:225], v[82:85]
	v_mfma_f32_16x16x32_bf16 v[74:77], v[160:163], v[222:225], v[74:77]
	s_setprio 0
	s_setprio 1
	v_mfma_f32_16x16x32_bf16 v[118:121], v[164:167], v[194:197], v[118:121]
	v_mfma_f32_16x16x32_bf16 v[110:113], v[186:189], v[194:197], v[110:113]
	v_mfma_f32_16x16x32_bf16 v[102:105], v[164:167], v[202:205], v[102:105]
	v_mfma_f32_16x16x32_bf16 v[94:97], v[186:189], v[202:205], v[94:97]
	v_mfma_f32_16x16x32_bf16 v[86:89], v[164:167], v[210:213], v[86:89]
	v_mfma_f32_16x16x32_bf16 v[78:81], v[186:189], v[210:213], v[78:81]
	v_mfma_f32_16x16x32_bf16 v[70:73], v[164:167], v[218:221], v[70:73]
	v_mfma_f32_16x16x32_bf16 v[66:69], v[186:189], v[218:221], v[66:69]
	v_mfma_f32_16x16x32_bf16 v[118:121], v[182:185], v[198:201], v[118:121]
	v_mfma_f32_16x16x32_bf16 v[110:113], v[190:193], v[198:201], v[110:113]
	v_mfma_f32_16x16x32_bf16 v[102:105], v[182:185], v[206:209], v[102:105]
	v_mfma_f32_16x16x32_bf16 v[94:97], v[190:193], v[206:209], v[94:97]
	v_mfma_f32_16x16x32_bf16 v[86:89], v[182:185], v[214:217], v[86:89]
	v_mfma_f32_16x16x32_bf16 v[78:81], v[190:193], v[214:217], v[78:81]
	v_mfma_f32_16x16x32_bf16 v[70:73], v[182:185], v[222:225], v[70:73]
	v_mfma_f32_16x16x32_bf16 v[66:69], v[190:193], v[222:225], v[66:69]
	s_setprio 0
	s_barrier
	s_add_i32 s20, s4, s33
	v_lshl_add_u64 v[168:169], s[24:25], 0, v[0:1]
	s_mov_b32 m0, s20
	ds_read_b128 v[194:197], v147 offset:16384
	ds_read_b128 v[198:201], v147 offset:17408
	ds_read_b128 v[202:205], v147 offset:18432
	ds_read_b128 v[206:209], v147 offset:19456
	ds_read_b128 v[210:213], v147 offset:20480
	ds_read_b128 v[214:217], v147 offset:21504
	ds_read_b128 v[218:221], v147 offset:22528
	ds_read_b128 v[222:225], v147 offset:23552
	global_load_lds_dwordx4 v[168:169], off
	s_add_i32 m0, s20, 0x2000
	s_add_u32 s20, s24, 0x20000
	v_lshl_add_u64 v[226:227], s[24:25], 0, v[134:135]
	s_addc_u32 s21, s25, 0
	s_add_i32 s49, s5, s33
	global_load_lds_dwordx4 v[226:227], off
	v_lshl_add_u64 v[228:229], s[20:21], 0, v[0:1]
	s_mov_b32 m0, s49
	v_lshl_add_u64 v[240:241], s[26:27], 0, v[132:133]
	global_load_lds_dwordx4 v[228:229], off
	s_add_i32 m0, s49, 0x2000
	v_lshl_add_u64 v[228:229], s[20:21], 0, v[134:135]
	global_load_lds_dwordx4 v[228:229], off
	s_mov_b32 m0, s34
	v_lshl_add_u64 v[228:229], s[26:27], 0, v[130:131]
	global_load_lds_dwordx4 v[228:229], off
	s_mov_b32 m0, s35
	s_nop 0
	global_load_lds_dwordx4 v[240:241], off
	s_waitcnt vmcnt(8)
	s_waitcnt lgkmcnt(0)
	s_barrier
; #define PG8_STAGE(bufoff, gbase, voff) do { _Pragma("unroll") for (int _i = 0; _i < 2; ++_i) \
;         __builtin_amdgcn_global_load_lds((const unsigned*)((const char*)(gbase) + (voff)[_i]), (PG8_LAS unsigned*)(lds + (bufoff) + ldsw + _i * 8192), 16, 0, 0); } while (0)
; #define PG8_LDA(dst, b, h) do { _Pragma("unroll") for (int m = 0; m < 4; ++m) _Pragma("unroll") for (int k = 0; k < 2; ++k) dst[m][k] = *(const PG8_LAS bf16x8*)(lds + PG8_SA(b, h) + aoff + m * 2048 + k * 1024); } while (0)
; #define PG8_LDB(dst, b, h) do { _Pragma("unroll") for (int n = 0; n < 2; ++n) _Pragma("unroll") for (int k = 0; k < 2; ++k) dst[n][k] = *(const PG8_LAS bf16x8*)(lds + PG8_SB(b, h) + boff + n * 2048 + k * 1024); } while (0)
; #define PG8_MMA(ai, bj, At, Bt) do { __builtin_amdgcn_s_setprio(1); _Pragma("unroll") for (int m = 0; m < 4; ++m) _Pragma("unroll") for (int n = 0; n < 2; ++n) _Pragma("unroll") for (int k = 0; k < 2; ++k) \
;         acc[ai][bj][m][n] = __builtin_amdgcn_mfma_f32_16x16x32_bf16(Bt[n][k], At[m][k], acc[ai][bj][m][n], 0, 0, 0); __builtin_amdgcn_s_setprio(0); } while (0)
; #define PG8_WAIT_V(n) asm volatile("s_waitcnt vmcnt(" #n ")" ::: "memory")
; #define PG8_WAIT_L(n) asm volatile("s_waitcnt lgkmcnt(" #n ")" ::: "memory")
; #define PG8_BAR __builtin_amdgcn_s_barrier()
; #define PG8_SCHED __builtin_amdgcn_sched_barrier(0)
; template <class Epi, class Sched, bool ALIGN_EPI = false, bool SP2 = false>
; __device__ __forceinline__ void gemm_phase(PG8_LAS unsigned char* lds, const Gemm g, const Sched& S, const Epi& E, int tid_in) {
;     ...
;             PG8_WAIT_V(8); PG8_WAIT_L(0); PG8_BAR; PG8_MMA(1, 0, At, B0); PG8_MMA(1, 1, At, B1); PG8_BAR; PG8_SCHED;
;             PG8_LDB(B0, 1, 0); PG8_LDB(B1, 1, 1); PG8_SCHED; PG8_LDA(At, 1, 0); PG8_STAGE(PG8_SA(0, 1), a2 + hstepA, voffA);
;             PG8_WAIT_V(8); PG8_WAIT_L(0); PG8_BAR; PG8_MMA(0, 0, At, B0); PG8_MMA(0, 1, At, B1); PG8_BAR; PG8_SCHED;
	s_setprio 1
	s_waitcnt lgkmcnt(0)
	v_mfma_f32_16x16x32_bf16 v[62:65], v[148:151], v[194:197], v[62:65]
	v_mfma_f32_16x16x32_bf16 v[58:61], v[156:159], v[194:197], v[58:61]
	v_mfma_f32_16x16x32_bf16 v[50:53], v[148:151], v[202:205], v[50:53]
	v_mfma_f32_16x16x32_bf16 v[42:45], v[156:159], v[202:205], v[42:45]
	v_mfma_f32_16x16x32_bf16 v[34:37], v[148:151], v[210:213], v[34:37]
	v_mfma_f32_16x16x32_bf16 v[26:29], v[156:159], v[210:213], v[26:29]
	v_mfma_f32_16x16x32_bf16 v[18:21], v[148:151], v[218:221], v[18:21]
	v_mfma_f32_16x16x32_bf16 v[10:13], v[156:159], v[218:221], v[10:13]
	v_mfma_f32_16x16x32_bf16 v[62:65], v[152:155], v[198:201], v[62:65]
	v_mfma_f32_16x16x32_bf16 v[58:61], v[160:163], v[198:201], v[58:61]
	v_mfma_f32_16x16x32_bf16 v[50:53], v[152:155], v[206:209], v[50:53]
	v_mfma_f32_16x16x32_bf16 v[42:45], v[160:163], v[206:209], v[42:45]
	v_mfma_f32_16x16x32_bf16 v[34:37], v[152:155], v[214:217], v[34:37]
	v_mfma_f32_16x16x32_bf16 v[26:29], v[160:163], v[214:217], v[26:29]
	v_mfma_f32_16x16x32_bf16 v[18:21], v[152:155], v[222:225], v[18:21]
	v_mfma_f32_16x16x32_bf16 v[10:13], v[160:163], v[222:225], v[10:13]
	s_setprio 0
	s_setprio 1
	v_mfma_f32_16x16x32_bf16 v[54:57], v[164:167], v[194:197], v[54:57]
	v_mfma_f32_16x16x32_bf16 v[46:49], v[186:189], v[194:197], v[46:49]
	v_mfma_f32_16x16x32_bf16 v[38:41], v[164:167], v[202:205], v[38:41]
	v_mfma_f32_16x16x32_bf16 v[30:33], v[186:189], v[202:205], v[30:33]
	v_mfma_f32_16x16x32_bf16 v[22:25], v[164:167], v[210:213], v[22:25]
	v_mfma_f32_16x16x32_bf16 v[14:17], v[186:189], v[210:213], v[14:17]
	v_mfma_f32_16x16x32_bf16 v[6:9], v[164:167], v[218:221], v[6:9]
	v_mfma_f32_16x16x32_bf16 v[2:5], v[186:189], v[218:221], v[2:5]
	v_mfma_f32_16x16x32_bf16 v[54:57], v[182:185], v[198:201], v[54:57]
	v_mfma_f32_16x16x32_bf16 v[46:49], v[190:193], v[198:201], v[46:49]
	v_mfma_f32_16x16x32_bf16 v[38:41], v[182:185], v[206:209], v[38:41]
	v_mfma_f32_16x16x32_bf16 v[30:33], v[190:193], v[206:209], v[30:33]
	v_mfma_f32_16x16x32_bf16 v[22:25], v[182:185], v[214:217], v[22:25]
	v_mfma_f32_16x16x32_bf16 v[14:17], v[190:193], v[214:217], v[14:17]
	v_mfma_f32_16x16x32_bf16 v[6:9], v[182:185], v[222:225], v[6:9]
	v_mfma_f32_16x16x32_bf16 v[2:5], v[190:193], v[222:225], v[2:5]
	s_setprio 0
	s_barrier
	v_add_u32_e32 v140, s63, v145
	ds_read_b128 v[148:151], v140
	ds_read_b128 v[152:155], v140 offset:1024
	ds_read_b128 v[156:159], v140 offset:2048
	ds_read_b128 v[160:163], v140 offset:3072
	v_add_u32_e32 v140, s55, v145
	ds_read_b128 v[164:167], v140
	ds_read_b128 v[182:185], v140 offset:1024
	ds_read_b128 v[186:189], v140 offset:2048
	ds_read_b128 v[190:193], v140 offset:3072
	s_add_u32 s20, s26, 0x2e0000
	s_addc_u32 s21, s27, 0
	s_mov_b32 m0, s36
	v_lshl_add_u64 v[242:243], s[20:21], 0, v[130:131]
	ds_read_b128 v[194:197], v147 offset:32768
	ds_read_b128 v[198:201], v147 offset:33792
	ds_read_b128 v[202:205], v147 offset:34816
	ds_read_b128 v[206:209], v147 offset:35840
	ds_read_b128 v[210:213], v147 offset:36864
	ds_read_b128 v[214:217], v147 offset:37888
	ds_read_b128 v[218:221], v147 offset:38912
	ds_read_b128 v[222:225], v147 offset:39936
	global_load_lds_dwordx4 v[242:243], off
	s_mov_b32 m0, s37
	v_lshl_add_u64 v[242:243], s[20:21], 0, v[132:133]
	global_load_lds_dwordx4 v[242:243], off
	s_waitcnt vmcnt(8)
	s_waitcnt lgkmcnt(0)
	s_barrier
	s_setprio 1
	s_waitcnt lgkmcnt(0)
	v_mfma_f32_16x16x32_bf16 v[126:129], v[148:151], v[194:197], v[126:129]
	v_mfma_f32_16x16x32_bf16 v[122:125], v[156:159], v[194:197], v[122:125]
	v_mfma_f32_16x16x32_bf16 v[114:117], v[148:151], v[202:205], v[114:117]
	v_mfma_f32_16x16x32_bf16 v[106:109], v[156:159], v[202:205], v[106:109]
	v_mfma_f32_16x16x32_bf16 v[98:101], v[148:151], v[210:213], v[98:101]
	v_mfma_f32_16x16x32_bf16 v[90:93], v[156:159], v[210:213], v[90:93]
	v_mfma_f32_16x16x32_bf16 v[82:85], v[148:151], v[218:221], v[82:85]
	v_mfma_f32_16x16x32_bf16 v[74:77], v[156:159], v[218:221], v[74:77]
	v_mfma_f32_16x16x32_bf16 v[126:129], v[152:155], v[198:201], v[126:129]
	v_mfma_f32_16x16x32_bf16 v[122:125], v[160:163], v[198:201], v[122:125]
	v_mfma_f32_16x16x32_bf16 v[114:117], v[152:155], v[206:209], v[114:117]
	v_mfma_f32_16x16x32_bf16 v[106:109], v[160:163], v[206:209], v[106:109]
	v_mfma_f32_16x16x32_bf16 v[98:101], v[152:155], v[214:217], v[98:101]
	v_mfma_f32_16x16x32_bf16 v[90:93], v[160:163], v[214:217], v[90:93]
	v_mfma_f32_16x16x32_bf16 v[82:85], v[152:155], v[222:225], v[82:85]
	v_mfma_f32_16x16x32_bf16 v[74:77], v[160:163], v[222:225], v[74:77]
	s_setprio 0
	s_setprio 1
	v_mfma_f32_16x16x32_bf16 v[118:121], v[164:167], v[194:197], v[118:121]
	v_mfma_f32_16x16x32_bf16 v[110:113], v[186:189], v[194:197], v[110:113]
	v_mfma_f32_16x16x32_bf16 v[102:105], v[164:167], v[202:205], v[102:105]
	v_mfma_f32_16x16x32_bf16 v[94:97], v[186:189], v[202:205], v[94:97]
	v_mfma_f32_16x16x32_bf16 v[86:89], v[164:167], v[210:213], v[86:89]
	v_mfma_f32_16x16x32_bf16 v[78:81], v[186:189], v[210:213], v[78:81]
	v_mfma_f32_16x16x32_bf16 v[70:73], v[164:167], v[218:221], v[70:73]
	v_mfma_f32_16x16x32_bf16 v[66:69], v[186:189], v[218:221], v[66:69]
	v_mfma_f32_16x16x32_bf16 v[118:121], v[182:185], v[198:201], v[118:121]
	v_mfma_f32_16x16x32_bf16 v[110:113], v[190:193], v[198:201], v[110:113]
	v_mfma_f32_16x16x32_bf16 v[102:105], v[182:185], v[206:209], v[102:105]
	v_mfma_f32_16x16x32_bf16 v[94:97], v[190:193], v[206:209], v[94:97]
	v_mfma_f32_16x16x32_bf16 v[86:89], v[182:185], v[214:217], v[86:89]
	v_mfma_f32_16x16x32_bf16 v[78:81], v[190:193], v[214:217], v[78:81]
	v_mfma_f32_16x16x32_bf16 v[70:73], v[182:185], v[222:225], v[70:73]
	v_mfma_f32_16x16x32_bf16 v[66:69], v[190:193], v[222:225], v[66:69]
	s_setprio 0
	s_barrier
; #define PG8_STAGE(bufoff, gbase, voff) do { _Pragma("unroll") for (int _i = 0; _i < 2; ++_i) \
;         __builtin_amdgcn_global_load_lds((const unsigned*)((const char*)(gbase) + (voff)[_i]), (PG8_LAS unsigned*)(lds + (bufoff) + ldsw + _i * 8192), 16, 0, 0); } while (0)
; #define PG8_LDA(dst, b, h) do { _Pragma("unroll") for (int m = 0; m < 4; ++m) _Pragma("unroll") for (int k = 0; k < 2; ++k) dst[m][k] = *(const PG8_LAS bf16x8*)(lds + PG8_SA(b, h) + aoff + m * 2048 + k * 1024); } while (0)
; #define PG8_MMA(ai, bj, At, Bt) do { __builtin_amdgcn_s_setprio(1); _Pragma("unroll") for (int m = 0; m < 4; ++m) _Pragma("unroll") for (int n = 0; n < 2; ++n) _Pragma("unroll") for (int k = 0; k < 2; ++k) \
;         acc[ai][bj][m][n] = __builtin_amdgcn_mfma_f32_16x16x32_bf16(Bt[n][k], At[m][k], acc[ai][bj][m][n], 0, 0, 0); __builtin_amdgcn_s_setprio(0); } while (0)
; #define PG8_WAIT_V(n) asm volatile("s_waitcnt vmcnt(" #n ")" ::: "memory")
; #define PG8_WAIT_L(n) asm volatile("s_waitcnt lgkmcnt(" #n ")" ::: "memory")
; #define PG8_BAR __builtin_amdgcn_s_barrier()
; #define PG8_SCHED __builtin_amdgcn_sched_barrier(0)
; template <class Epi, class Sched, bool ALIGN_EPI = false, bool SP2 = false>
; __device__ __forceinline__ void gemm_phase(PG8_LAS unsigned char* lds, const Gemm g, const Sched& S, const Epi& E, int tid_in) {
;     ...
;         for (int t = 0; t < nt; t += 2) {
;             const bool last = (t == nt - 2);
;     ...
;             PG8_LDA(At, 1, 1); PG8_STAGE(PG8_SB(1, 0), b3, voffB); PG8_STAGE(PG8_SB(1, 1), b3 + hstep, voffB); PG8_STAGE(PG8_SA(1, 0), a3, voffA);
;             PG8_WAIT_V(8); PG8_WAIT_L(0); PG8_BAR; PG8_MMA(1, 0, At, B0); PG8_MMA(1, 1, At, B1); PG8_BAR; PG8_SCHED;
	s_add_i32 s20, s63, s33
	v_lshl_add_u64 v[168:169], v[168:169], 0, s[90:91]
	s_mov_b32 m0, s20
	ds_read_b128 v[194:197], v147 offset:49152
	ds_read_b128 v[198:201], v147 offset:50176
	ds_read_b128 v[202:205], v147 offset:51200
	ds_read_b128 v[206:209], v147 offset:52224
	ds_read_b128 v[210:213], v147 offset:53248
	ds_read_b128 v[214:217], v147 offset:54272
	ds_read_b128 v[218:221], v147 offset:55296
	ds_read_b128 v[222:225], v147 offset:56320
	global_load_lds_dwordx4 v[168:169], off
	s_add_i32 m0, s20, 0x2000
	s_add_u32 s20, s24, 0x20080
	v_lshl_add_u64 v[168:169], v[226:227], 0, s[90:91]
	s_addc_u32 s21, s25, 0
	s_add_i32 s24, s55, s33
	global_load_lds_dwordx4 v[168:169], off
	s_mov_b32 m0, s24
	v_lshl_add_u64 v[168:169], s[20:21], 0, v[0:1]
	global_load_lds_dwordx4 v[168:169], off
	s_add_i32 m0, s24, 0x2000
	v_lshl_add_u64 v[168:169], s[20:21], 0, v[134:135]
	global_load_lds_dwordx4 v[168:169], off
	s_mov_b32 m0, s42
	v_lshl_add_u64 v[168:169], v[228:229], 0, s[90:91]
	global_load_lds_dwordx4 v[168:169], off
	s_mov_b32 m0, s43
	v_lshl_add_u64 v[168:169], v[240:241], 0, s[90:91]
	global_load_lds_dwordx4 v[168:169], off
	s_waitcnt vmcnt(8)
	s_waitcnt lgkmcnt(0)
	s_barrier
	s_setprio 1
	s_waitcnt lgkmcnt(0)
	v_mfma_f32_16x16x32_bf16 v[62:65], v[148:151], v[194:197], v[62:65]
	v_mfma_f32_16x16x32_bf16 v[58:61], v[156:159], v[194:197], v[58:61]
	v_mfma_f32_16x16x32_bf16 v[50:53], v[148:151], v[202:205], v[50:53]
	v_mfma_f32_16x16x32_bf16 v[42:45], v[156:159], v[202:205], v[42:45]
	v_mfma_f32_16x16x32_bf16 v[34:37], v[148:151], v[210:213], v[34:37]
	v_mfma_f32_16x16x32_bf16 v[26:29], v[156:159], v[210:213], v[26:29]
	v_mfma_f32_16x16x32_bf16 v[18:21], v[148:151], v[218:221], v[18:21]
	v_mfma_f32_16x16x32_bf16 v[10:13], v[156:159], v[218:221], v[10:13]
	v_mfma_f32_16x16x32_bf16 v[62:65], v[152:155], v[198:201], v[62:65]
	v_mfma_f32_16x16x32_bf16 v[58:61], v[160:163], v[198:201], v[58:61]
	v_mfma_f32_16x16x32_bf16 v[50:53], v[152:155], v[206:209], v[50:53]
	v_mfma_f32_16x16x32_bf16 v[42:45], v[160:163], v[206:209], v[42:45]
	v_mfma_f32_16x16x32_bf16 v[34:37], v[152:155], v[214:217], v[34:37]
	v_mfma_f32_16x16x32_bf16 v[26:29], v[160:163], v[214:217], v[26:29]
	v_mfma_f32_16x16x32_bf16 v[18:21], v[152:155], v[222:225], v[18:21]
	v_mfma_f32_16x16x32_bf16 v[10:13], v[160:163], v[222:225], v[10:13]
	s_setprio 0
	s_setprio 1
	v_mfma_f32_16x16x32_bf16 v[54:57], v[164:167], v[194:197], v[54:57]
	v_mfma_f32_16x16x32_bf16 v[46:49], v[186:189], v[194:197], v[46:49]
	v_mfma_f32_16x16x32_bf16 v[38:41], v[164:167], v[202:205], v[38:41]
	v_mfma_f32_16x16x32_bf16 v[30:33], v[186:189], v[202:205], v[30:33]
	v_mfma_f32_16x16x32_bf16 v[22:25], v[164:167], v[210:213], v[22:25]
	v_mfma_f32_16x16x32_bf16 v[14:17], v[186:189], v[210:213], v[14:17]
	v_mfma_f32_16x16x32_bf16 v[6:9], v[164:167], v[218:221], v[6:9]
	v_mfma_f32_16x16x32_bf16 v[2:5], v[186:189], v[218:221], v[2:5]
	v_mfma_f32_16x16x32_bf16 v[54:57], v[182:185], v[198:201], v[54:57]
	v_mfma_f32_16x16x32_bf16 v[46:49], v[190:193], v[198:201], v[46:49]
	v_mfma_f32_16x16x32_bf16 v[38:41], v[182:185], v[206:209], v[38:41]
	v_mfma_f32_16x16x32_bf16 v[30:33], v[190:193], v[206:209], v[30:33]
	v_mfma_f32_16x16x32_bf16 v[22:25], v[182:185], v[214:217], v[22:25]
	v_mfma_f32_16x16x32_bf16 v[14:17], v[190:193], v[214:217], v[14:17]
	v_mfma_f32_16x16x32_bf16 v[6:9], v[182:185], v[222:225], v[6:9]
	v_mfma_f32_16x16x32_bf16 v[2:5], v[190:193], v[222:225], v[2:5]
	s_setprio 0
	s_barrier
	s_add_i32 s48, s48, 2
	s_add_u32 s0, s0, 0x100
	s_addc_u32 s15, s15, 0
	s_cmp_gt_u32 s48, 5
	s_mov_b64 s[20:21], s[22:23]
	s_cbranch_scc0 .LBB0_627
	s_and_b64 vcc, exec, s[12:13]
	s_cbranch_vccz .LBB0_630
	s_barrier

; #define PG8_STAGE(bufoff, gbase, voff) do { _Pragma("unroll") for (int _i = 0; _i < 2; ++_i) \
;         __builtin_amdgcn_global_load_lds((const unsigned*)((const char*)(gbase) + (voff)[_i]), (PG8_LAS unsigned*)(lds + (bufoff) + ldsw + _i * 8192), 16, 0, 0); } while (0)
; #define PG8_LDA(dst, b, h) do { _Pragma("unroll") for (int m = 0; m < 4; ++m) _Pragma("unroll") for (int k = 0; k < 2; ++k) dst[m][k] = *(const PG8_LAS bf16x8*)(lds + PG8_SA(b, h) + aoff + m * 2048 + k * 1024); } while (0)
; #define PG8_LDB(dst, b, h) do { _Pragma("unroll") for (int n = 0; n < 2; ++n) _Pragma("unroll") for (int k = 0; k < 2; ++k) dst[n][k] = *(const PG8_LAS bf16x8*)(lds + PG8_SB(b, h) + boff + n * 2048 + k * 1024); } while (0)
; #define PG8_MMA(ai, bj, At, Bt) do { __builtin_amdgcn_s_setprio(1); _Pragma("unroll") for (int m = 0; m < 4; ++m) _Pragma("unroll") for (int n = 0; n < 2; ++n) _Pragma("unroll") for (int k = 0; k < 2; ++k) \
;         acc[ai][bj][m][n] = __builtin_amdgcn_mfma_f32_16x16x32_bf16(Bt[n][k], At[m][k], acc[ai][bj][m][n], 0, 0, 0); __builtin_amdgcn_s_setprio(0); } while (0)
; #define PG8_WAIT_V(n) asm volatile("s_waitcnt vmcnt(" #n ")" ::: "memory")
; #define PG8_WAIT_L(n) asm volatile("s_waitcnt lgkmcnt(" #n ")" ::: "memory")
; template <class Epi, class Sched, bool ALIGN_EPI = false, bool SP2 = false>
; __device__ __forceinline__ void gemm_phase(PG8_LAS unsigned char* lds, const Gemm g, const Sched& S, const Epi& E, int tid_in) {
;     ...
;             const bool last = (t == nt - 2);
;             const char* a1 = cA + (size_t)(t + 1) * kstep;
;             const char* a2 = last ? nA : cA + (size_t)(t + 2) * kstep; const char* b2 = last ? nB : cB + (size_t)(t + 2) * kstep;
;             const char* a3 = a2 + kstep; const char* b3 = b2 + kstep;
;             if (last && has_next) S.a_ready(nxt);
;             if constexpr (SP2) {
;             PG8_LDB(B0, 0, 0); PG8_LDB(B1, 0, 1); PG8_SCHED; PG8_LDA(At, 0, 0); PG8_STAGE(PG8_SA(1, 1), a1 + hstepA, voffA);
;             PG8_WAIT_V(8); PG8_WAIT_L(0); PG8_BAR; PG8_MMA(0, 0, At, B0); PG8_MMA(0, 1, At, B1); PG8_BAR; PG8_SCHED;
;             PG8_LDA(At, 0, 1); PG8_STAGE(PG8_SB(0, 0), b2, voffB); PG8_STAGE(PG8_SB(0, 1), b2 + hstep, voffB); PG8_STAGE(PG8_SA(0, 0), a2, voffA);
;             PG8_WAIT_V(8); PG8_WAIT_L(0); PG8_BAR; PG8_MMA(1, 0, At, B0); PG8_MMA(1, 1, At, B1); PG8_BAR; PG8_SCHED;
.LBB0_900:
	v_add_u32_e32 v0, s4, v242
	ds_read_b128 v[132:135], v0
	ds_read_b128 v[144:147], v0 offset:1024
	ds_read_b128 v[148:151], v0 offset:2048
	ds_read_b128 v[152:155], v0 offset:3072
	v_add_u32_e32 v0, s5, v242
	ds_read_b128 v[156:159], v0
	ds_read_b128 v[160:163], v0 offset:1024
	ds_read_b128 v[164:167], v0 offset:2048
	ds_read_b128 v[182:185], v0 offset:3072
	s_add_i32 vcc_hi, s10, 2
	s_add_u32 s11, s8, 0xfffc0080
	s_addc_u32 s12, s9, -1
	s_cmp_eq_u32 s68, s10
	s_cselect_b32 s10, s47, s76
	s_cselect_b32 s13, s30, s12
	s_cselect_b32 s12, s31, s11
	s_cselect_b32 s11, s46, vcc_lo
	v_lshl_add_u64 v[2:3], s[8:9], 0, v[140:141]
	s_add_i32 m0, s37, 0xc000
	ds_read_b128 v[186:189], v243
	ds_read_b128 v[190:193], v243 offset:1024
	ds_read_b128 v[194:197], v243 offset:2048
	ds_read_b128 v[198:201], v243 offset:3072
	ds_read_b128 v[202:205], v243 offset:4096
	ds_read_b128 v[206:209], v243 offset:5120
	ds_read_b128 v[210:213], v243 offset:6144
	ds_read_b128 v[214:217], v243 offset:7168
	global_load_lds_dwordx4 v[2:3], off
	s_add_i32 m0, s37, 0xe000
	v_lshl_add_u64 v[2:3], s[8:9], 0, v[142:143]
	global_load_lds_dwordx4 v[2:3], off
	s_waitcnt vmcnt(8)
	s_waitcnt lgkmcnt(0)
	s_barrier
	s_setprio 1
	s_waitcnt lgkmcnt(0)
	v_mfma_f32_16x16x32_bf16 v[128:131], v[132:135], v[186:189], v[128:131]
	v_mfma_f32_16x16x32_bf16 v[124:127], v[148:151], v[186:189], v[124:127]
	v_mfma_f32_16x16x32_bf16 v[120:123], v[132:135], v[194:197], v[120:123]
	v_mfma_f32_16x16x32_bf16 v[116:119], v[148:151], v[194:197], v[116:119]
	v_mfma_f32_16x16x32_bf16 v[112:115], v[132:135], v[202:205], v[112:115]
	v_mfma_f32_16x16x32_bf16 v[108:111], v[148:151], v[202:205], v[108:111]
	v_mfma_f32_16x16x32_bf16 v[104:107], v[132:135], v[210:213], v[104:107]
	v_mfma_f32_16x16x32_bf16 v[100:103], v[148:151], v[210:213], v[100:103]
	v_mfma_f32_16x16x32_bf16 v[128:131], v[144:147], v[190:193], v[128:131]
	v_mfma_f32_16x16x32_bf16 v[124:127], v[152:155], v[190:193], v[124:127]
	v_mfma_f32_16x16x32_bf16 v[120:123], v[144:147], v[198:201], v[120:123]
	v_mfma_f32_16x16x32_bf16 v[116:119], v[152:155], v[198:201], v[116:119]
	v_mfma_f32_16x16x32_bf16 v[112:115], v[144:147], v[206:209], v[112:115]
	v_mfma_f32_16x16x32_bf16 v[108:111], v[152:155], v[206:209], v[108:111]
	v_mfma_f32_16x16x32_bf16 v[104:107], v[144:147], v[214:217], v[104:107]
	v_mfma_f32_16x16x32_bf16 v[100:103], v[152:155], v[214:217], v[100:103]
	s_setprio 0
	s_setprio 1
	v_mfma_f32_16x16x32_bf16 v[96:99], v[156:159], v[186:189], v[96:99]
	v_mfma_f32_16x16x32_bf16 v[92:95], v[164:167], v[186:189], v[92:95]
	v_mfma_f32_16x16x32_bf16 v[88:91], v[156:159], v[194:197], v[88:91]
	v_mfma_f32_16x16x32_bf16 v[84:87], v[164:167], v[194:197], v[84:87]
	v_mfma_f32_16x16x32_bf16 v[80:83], v[156:159], v[202:205], v[80:83]
	v_mfma_f32_16x16x32_bf16 v[76:79], v[164:167], v[202:205], v[76:79]
	v_mfma_f32_16x16x32_bf16 v[72:75], v[156:159], v[210:213], v[72:75]
	v_mfma_f32_16x16x32_bf16 v[68:71], v[164:167], v[210:213], v[68:71]
	v_mfma_f32_16x16x32_bf16 v[96:99], v[160:163], v[190:193], v[96:99]
	v_mfma_f32_16x16x32_bf16 v[92:95], v[182:185], v[190:193], v[92:95]
	v_mfma_f32_16x16x32_bf16 v[88:91], v[160:163], v[198:201], v[88:91]
	v_mfma_f32_16x16x32_bf16 v[84:87], v[182:185], v[198:201], v[84:87]
	v_mfma_f32_16x16x32_bf16 v[80:83], v[160:163], v[206:209], v[80:83]
	v_mfma_f32_16x16x32_bf16 v[76:79], v[182:185], v[206:209], v[76:79]
	v_mfma_f32_16x16x32_bf16 v[72:75], v[160:163], v[214:217], v[72:75]
	v_mfma_f32_16x16x32_bf16 v[68:71], v[182:185], v[214:217], v[68:71]
	s_setprio 0
	s_barrier
	s_add_i32 s64, s4, s36
	v_lshl_add_u64 v[168:169], s[10:11], 0, v[136:137]
	s_mov_b32 m0, s64
	ds_read_b128 v[186:189], v243 offset:16384
	ds_read_b128 v[190:193], v243 offset:17408
	ds_read_b128 v[194:197], v243 offset:18432
	ds_read_b128 v[198:201], v243 offset:19456
	ds_read_b128 v[202:205], v243 offset:20480
	ds_read_b128 v[206:209], v243 offset:21504
	ds_read_b128 v[210:213], v243 offset:22528
	ds_read_b128 v[214:217], v243 offset:23552
	global_load_lds_dwordx4 v[168:169], off
	s_add_i32 m0, s64, 0x2000
	s_add_u32 s64, s10, 0x40000
	v_lshl_add_u64 v[218:219], s[10:11], 0, v[138:139]
	s_addc_u32 s65, s11, 0
	s_add_i32 s95, s5, s36
	global_load_lds_dwordx4 v[218:219], off
	v_lshl_add_u64 v[2:3], s[64:65], 0, v[136:137]
	s_mov_b32 m0, s95
	v_lshl_add_u64 v[220:221], s[12:13], 0, v[136:137]
	global_load_lds_dwordx4 v[2:3], off
	v_lshl_add_u64 v[2:3], s[64:65], 0, v[138:139]
	s_add_i32 m0, s95, 0x2000
	v_lshl_add_u64 v[222:223], s[12:13], 0, v[138:139]
	global_load_lds_dwordx4 v[2:3], off
	s_mov_b32 m0, s37
	s_nop 0
	global_load_lds_dwordx4 v[220:221], off
	s_mov_b32 m0, s38
	s_nop 0
	global_load_lds_dwordx4 v[222:223], off
	s_waitcnt vmcnt(8)
	s_waitcnt lgkmcnt(0)
	s_barrier
; #define PG8_STAGE(bufoff, gbase, voff) do { _Pragma("unroll") for (int _i = 0; _i < 2; ++_i) \
;         __builtin_amdgcn_global_load_lds((const unsigned*)((const char*)(gbase) + (voff)[_i]), (PG8_LAS unsigned*)(lds + (bufoff) + ldsw + _i * 8192), 16, 0, 0); } while (0)
; #define PG8_LDA(dst, b, h) do { _Pragma("unroll") for (int m = 0; m < 4; ++m) _Pragma("unroll") for (int k = 0; k < 2; ++k) dst[m][k] = *(const PG8_LAS bf16x8*)(lds + PG8_SA(b, h) + aoff + m * 2048 + k * 1024); } while (0)
; #define PG8_LDB(dst, b, h) do { _Pragma("unroll") for (int n = 0; n < 2; ++n) _Pragma("unroll") for (int k = 0; k < 2; ++k) dst[n][k] = *(const PG8_LAS bf16x8*)(lds + PG8_SB(b, h) + boff + n * 2048 + k * 1024); } while (0)
; #define PG8_MMA(ai, bj, At, Bt) do { __builtin_amdgcn_s_setprio(1); _Pragma("unroll") for (int m = 0; m < 4; ++m) _Pragma("unroll") for (int n = 0; n < 2; ++n) _Pragma("unroll") for (int k = 0; k < 2; ++k) \
;         acc[ai][bj][m][n] = __builtin_amdgcn_mfma_f32_16x16x32_bf16(Bt[n][k], At[m][k], acc[ai][bj][m][n], 0, 0, 0); __builtin_amdgcn_s_setprio(0); } while (0)
; #define PG8_WAIT_V(n) asm volatile("s_waitcnt vmcnt(" #n ")" ::: "memory")
; #define PG8_WAIT_L(n) asm volatile("s_waitcnt lgkmcnt(" #n ")" ::: "memory")
; #define PG8_BAR __builtin_amdgcn_s_barrier()
; #define PG8_SCHED __builtin_amdgcn_sched_barrier(0)
; template <class Epi, class Sched, bool ALIGN_EPI = false, bool SP2 = false>
; __device__ __forceinline__ void gemm_phase(PG8_LAS unsigned char* lds, const Gemm g, const Sched& S, const Epi& E, int tid_in) {
;     ...
;             PG8_WAIT_V(8); PG8_WAIT_L(0); PG8_BAR; PG8_MMA(1, 0, At, B0); PG8_MMA(1, 1, At, B1); PG8_BAR; PG8_SCHED;
;             PG8_LDB(B0, 1, 0); PG8_LDB(B1, 1, 1); PG8_SCHED; PG8_LDA(At, 1, 0); PG8_STAGE(PG8_SA(0, 1), a2 + hstepA, voffA);
;             PG8_WAIT_V(8); PG8_WAIT_L(0); PG8_BAR; PG8_MMA(0, 0, At, B0); PG8_MMA(0, 1, At, B1); PG8_BAR; PG8_SCHED;
	s_setprio 1
	s_waitcnt lgkmcnt(0)
	v_mfma_f32_16x16x32_bf16 v[64:67], v[132:135], v[186:189], v[64:67]
	v_mfma_f32_16x16x32_bf16 v[60:63], v[148:151], v[186:189], v[60:63]
	v_mfma_f32_16x16x32_bf16 v[56:59], v[132:135], v[194:197], v[56:59]
	v_mfma_f32_16x16x32_bf16 v[52:55], v[148:151], v[194:197], v[52:55]
	v_mfma_f32_16x16x32_bf16 v[48:51], v[132:135], v[202:205], v[48:51]
	v_mfma_f32_16x16x32_bf16 v[44:47], v[148:151], v[202:205], v[44:47]
	v_mfma_f32_16x16x32_bf16 v[40:43], v[132:135], v[210:213], v[40:43]
	v_mfma_f32_16x16x32_bf16 v[36:39], v[148:151], v[210:213], v[36:39]
	v_mfma_f32_16x16x32_bf16 v[64:67], v[144:147], v[190:193], v[64:67]
	v_mfma_f32_16x16x32_bf16 v[60:63], v[152:155], v[190:193], v[60:63]
	v_mfma_f32_16x16x32_bf16 v[56:59], v[144:147], v[198:201], v[56:59]
	v_mfma_f32_16x16x32_bf16 v[52:55], v[152:155], v[198:201], v[52:55]
	v_mfma_f32_16x16x32_bf16 v[48:51], v[144:147], v[206:209], v[48:51]
	v_mfma_f32_16x16x32_bf16 v[44:47], v[152:155], v[206:209], v[44:47]
	v_mfma_f32_16x16x32_bf16 v[40:43], v[144:147], v[214:217], v[40:43]
	v_mfma_f32_16x16x32_bf16 v[36:39], v[152:155], v[214:217], v[36:39]
	s_setprio 0
	s_setprio 1
	v_mfma_f32_16x16x32_bf16 v[32:35], v[156:159], v[186:189], v[32:35]
	v_mfma_f32_16x16x32_bf16 v[28:31], v[164:167], v[186:189], v[28:31]
	v_mfma_f32_16x16x32_bf16 v[24:27], v[156:159], v[194:197], v[24:27]
	v_mfma_f32_16x16x32_bf16 v[20:23], v[164:167], v[194:197], v[20:23]
	v_mfma_f32_16x16x32_bf16 v[16:19], v[156:159], v[202:205], v[16:19]
	v_mfma_f32_16x16x32_bf16 v[12:15], v[164:167], v[202:205], v[12:15]
	v_mfma_f32_16x16x32_bf16 v[8:11], v[156:159], v[210:213], v[8:11]
	v_mfma_f32_16x16x32_bf16 v[2:5], v[164:167], v[210:213], v[4:7]
	v_mfma_f32_16x16x32_bf16 v[32:35], v[160:163], v[190:193], v[32:35]
	v_mfma_f32_16x16x32_bf16 v[28:31], v[182:185], v[190:193], v[28:31]
	v_mfma_f32_16x16x32_bf16 v[24:27], v[160:163], v[198:201], v[24:27]
	v_mfma_f32_16x16x32_bf16 v[20:23], v[182:185], v[198:201], v[20:23]
	v_mfma_f32_16x16x32_bf16 v[16:19], v[160:163], v[206:209], v[16:19]
	v_mfma_f32_16x16x32_bf16 v[12:15], v[182:185], v[206:209], v[12:15]
	v_mfma_f32_16x16x32_bf16 v[8:11], v[160:163], v[214:217], v[8:11]
	v_mfma_f32_16x16x32_bf16 v[2:5], v[182:185], v[214:217], v[2:5]
	s_setprio 0
	s_barrier
	v_add_u32_e32 v0, s63, v242
	ds_read_b128 v[132:135], v0
	ds_read_b128 v[144:147], v0 offset:1024
	ds_read_b128 v[148:151], v0 offset:2048
	ds_read_b128 v[152:155], v0 offset:3072
	v_add_u32_e32 v0, s55, v242
	ds_read_b128 v[156:159], v0
	ds_read_b128 v[160:163], v0 offset:1024
	ds_read_b128 v[164:167], v0 offset:2048
	ds_read_b128 v[182:185], v0 offset:3072
	s_add_u32 s12, s12, 0x40000
	s_addc_u32 s13, s13, 0
	s_mov_b32 m0, s39
	v_lshl_add_u64 v[6:7], s[12:13], 0, v[136:137]
	ds_read_b128 v[186:189], v243 offset:32768
	ds_read_b128 v[190:193], v243 offset:33792
	ds_read_b128 v[194:197], v243 offset:34816
	ds_read_b128 v[198:201], v243 offset:35840
	ds_read_b128 v[202:205], v243 offset:36864
	ds_read_b128 v[206:209], v243 offset:37888
	ds_read_b128 v[210:213], v243 offset:38912
	ds_read_b128 v[214:217], v243 offset:39936
	global_load_lds_dwordx4 v[6:7], off
	s_mov_b32 m0, s40
	v_lshl_add_u64 v[6:7], s[12:13], 0, v[138:139]
	global_load_lds_dwordx4 v[6:7], off
	s_waitcnt vmcnt(8)
	s_waitcnt lgkmcnt(0)
	s_barrier
	s_setprio 1
	s_waitcnt lgkmcnt(0)
	v_mfma_f32_16x16x32_bf16 v[128:131], v[132:135], v[186:189], v[128:131]
	v_mfma_f32_16x16x32_bf16 v[124:127], v[148:151], v[186:189], v[124:127]
	v_mfma_f32_16x16x32_bf16 v[120:123], v[132:135], v[194:197], v[120:123]
	v_mfma_f32_16x16x32_bf16 v[116:119], v[148:151], v[194:197], v[116:119]
	v_mfma_f32_16x16x32_bf16 v[112:115], v[132:135], v[202:205], v[112:115]
	v_mfma_f32_16x16x32_bf16 v[108:111], v[148:151], v[202:205], v[108:111]
	v_mfma_f32_16x16x32_bf16 v[104:107], v[132:135], v[210:213], v[104:107]
	v_mfma_f32_16x16x32_bf16 v[100:103], v[148:151], v[210:213], v[100:103]
	v_mfma_f32_16x16x32_bf16 v[128:131], v[144:147], v[190:193], v[128:131]
	v_mfma_f32_16x16x32_bf16 v[124:127], v[152:155], v[190:193], v[124:127]
	v_mfma_f32_16x16x32_bf16 v[120:123], v[144:147], v[198:201], v[120:123]
	v_mfma_f32_16x16x32_bf16 v[116:119], v[152:155], v[198:201], v[116:119]
	v_mfma_f32_16x16x32_bf16 v[112:115], v[144:147], v[206:209], v[112:115]
	v_mfma_f32_16x16x32_bf16 v[108:111], v[152:155], v[206:209], v[108:111]
	v_mfma_f32_16x16x32_bf16 v[104:107], v[144:147], v[214:217], v[104:107]
	v_mfma_f32_16x16x32_bf16 v[100:103], v[152:155], v[214:217], v[100:103]
	s_setprio 0
	s_setprio 1
	v_mfma_f32_16x16x32_bf16 v[96:99], v[156:159], v[186:189], v[96:99]
	v_mfma_f32_16x16x32_bf16 v[92:95], v[164:167], v[186:189], v[92:95]
	v_mfma_f32_16x16x32_bf16 v[88:91], v[156:159], v[194:197], v[88:91]
	v_mfma_f32_16x16x32_bf16 v[84:87], v[164:167], v[194:197], v[84:87]
	v_mfma_f32_16x16x32_bf16 v[80:83], v[156:159], v[202:205], v[80:83]
	v_mfma_f32_16x16x32_bf16 v[76:79], v[164:167], v[202:205], v[76:79]
	v_mfma_f32_16x16x32_bf16 v[72:75], v[156:159], v[210:213], v[72:75]
	v_mfma_f32_16x16x32_bf16 v[68:71], v[164:167], v[210:213], v[68:71]
	v_mfma_f32_16x16x32_bf16 v[96:99], v[160:163], v[190:193], v[96:99]
	v_mfma_f32_16x16x32_bf16 v[92:95], v[182:185], v[190:193], v[92:95]
	v_mfma_f32_16x16x32_bf16 v[88:91], v[160:163], v[198:201], v[88:91]
	v_mfma_f32_16x16x32_bf16 v[84:87], v[182:185], v[198:201], v[84:87]
	v_mfma_f32_16x16x32_bf16 v[80:83], v[160:163], v[206:209], v[80:83]
	v_mfma_f32_16x16x32_bf16 v[76:79], v[182:185], v[206:209], v[76:79]
	v_mfma_f32_16x16x32_bf16 v[72:75], v[160:163], v[214:217], v[72:75]
	v_mfma_f32_16x16x32_bf16 v[68:71], v[182:185], v[214:217], v[68:71]
	s_setprio 0
	s_barrier
; #define PG8_STAGE(bufoff, gbase, voff) do { _Pragma("unroll") for (int _i = 0; _i < 2; ++_i) \
;         __builtin_amdgcn_global_load_lds((const unsigned*)((const char*)(gbase) + (voff)[_i]), (PG8_LAS unsigned*)(lds + (bufoff) + ldsw + _i * 8192), 16, 0, 0); } while (0)
; #define PG8_LDA(dst, b, h) do { _Pragma("unroll") for (int m = 0; m < 4; ++m) _Pragma("unroll") for (int k = 0; k < 2; ++k) dst[m][k] = *(const PG8_LAS bf16x8*)(lds + PG8_SA(b, h) + aoff + m * 2048 + k * 1024); } while (0)
; #define PG8_MMA(ai, bj, At, Bt) do { __builtin_amdgcn_s_setprio(1); _Pragma("unroll") for (int m = 0; m < 4; ++m) _Pragma("unroll") for (int n = 0; n < 2; ++n) _Pragma("unroll") for (int k = 0; k < 2; ++k) \
;         acc[ai][bj][m][n] = __builtin_amdgcn_mfma_f32_16x16x32_bf16(Bt[n][k], At[m][k], acc[ai][bj][m][n], 0, 0, 0); __builtin_amdgcn_s_setprio(0); } while (0)
; #define PG8_WAIT_V(n) asm volatile("s_waitcnt vmcnt(" #n ")" ::: "memory")
; #define PG8_WAIT_L(n) asm volatile("s_waitcnt lgkmcnt(" #n ")" ::: "memory")
; #define PG8_BAR __builtin_amdgcn_s_barrier()
; #define PG8_SCHED __builtin_amdgcn_sched_barrier(0)
; template <class Epi, class Sched, bool ALIGN_EPI = false, bool SP2 = false>
; __device__ __forceinline__ void gemm_phase(PG8_LAS unsigned char* lds, const Gemm g, const Sched& S, const Epi& E, int tid_in) {
;     ...
;         for (int t = 0; t < nt; t += 2) {
;             const bool last = (t == nt - 2);
;     ...
;             PG8_LDA(At, 1, 1); PG8_STAGE(PG8_SB(1, 0), b3, voffB); PG8_STAGE(PG8_SB(1, 1), b3 + hstep, voffB); PG8_STAGE(PG8_SA(1, 0), a3, voffA);
;             PG8_WAIT_V(8); PG8_WAIT_L(0); PG8_BAR; PG8_MMA(1, 0, At, B0); PG8_MMA(1, 1, At, B1); PG8_BAR; PG8_SCHED;
	s_add_i32 s12, s63, s36
	v_lshl_add_u64 v[6:7], v[168:169], 0, s[90:91]
	s_mov_b32 m0, s12
	ds_read_b128 v[186:189], v243 offset:49152
	ds_read_b128 v[190:193], v243 offset:50176
	ds_read_b128 v[194:197], v243 offset:51200
	ds_read_b128 v[198:201], v243 offset:52224
	ds_read_b128 v[202:205], v243 offset:53248
	ds_read_b128 v[206:209], v243 offset:54272
	ds_read_b128 v[210:213], v243 offset:55296
	ds_read_b128 v[214:217], v243 offset:56320
	global_load_lds_dwordx4 v[6:7], off
	s_add_i32 m0, s12, 0x2000
	s_add_u32 s10, s10, 0x40080
	v_lshl_add_u64 v[6:7], v[218:219], 0, s[90:91]
	s_addc_u32 s11, s11, 0
	s_add_i32 s12, s55, s36
	global_load_lds_dwordx4 v[6:7], off
	s_mov_b32 m0, s12
	v_lshl_add_u64 v[6:7], s[10:11], 0, v[136:137]
	global_load_lds_dwordx4 v[6:7], off
	s_add_i32 m0, s12, 0x2000
	v_lshl_add_u64 v[6:7], s[10:11], 0, v[138:139]
	global_load_lds_dwordx4 v[6:7], off
	s_mov_b32 m0, s49
	v_lshl_add_u64 v[6:7], v[220:221], 0, s[90:91]
	global_load_lds_dwordx4 v[6:7], off
	s_mov_b32 m0, s79
	v_lshl_add_u64 v[6:7], v[222:223], 0, s[90:91]
	global_load_lds_dwordx4 v[6:7], off
	s_waitcnt vmcnt(8)
	s_waitcnt lgkmcnt(0)
	s_barrier
	s_setprio 1
	s_waitcnt lgkmcnt(0)
	v_mfma_f32_16x16x32_bf16 v[64:67], v[132:135], v[186:189], v[64:67]
	v_mfma_f32_16x16x32_bf16 v[60:63], v[148:151], v[186:189], v[60:63]
	v_mfma_f32_16x16x32_bf16 v[56:59], v[132:135], v[194:197], v[56:59]
	v_mfma_f32_16x16x32_bf16 v[52:55], v[148:151], v[194:197], v[52:55]
	v_mfma_f32_16x16x32_bf16 v[48:51], v[132:135], v[202:205], v[48:51]
	v_mfma_f32_16x16x32_bf16 v[44:47], v[148:151], v[202:205], v[44:47]
	v_mfma_f32_16x16x32_bf16 v[40:43], v[132:135], v[210:213], v[40:43]
	v_mfma_f32_16x16x32_bf16 v[36:39], v[148:151], v[210:213], v[36:39]
	v_mfma_f32_16x16x32_bf16 v[64:67], v[144:147], v[190:193], v[64:67]
	v_mfma_f32_16x16x32_bf16 v[60:63], v[152:155], v[190:193], v[60:63]
	v_mfma_f32_16x16x32_bf16 v[56:59], v[144:147], v[198:201], v[56:59]
	v_mfma_f32_16x16x32_bf16 v[52:55], v[152:155], v[198:201], v[52:55]
	v_mfma_f32_16x16x32_bf16 v[48:51], v[144:147], v[206:209], v[48:51]
	v_mfma_f32_16x16x32_bf16 v[44:47], v[152:155], v[206:209], v[44:47]
	v_mfma_f32_16x16x32_bf16 v[40:43], v[144:147], v[214:217], v[40:43]
	v_mfma_f32_16x16x32_bf16 v[36:39], v[152:155], v[214:217], v[36:39]
	s_setprio 0
	s_setprio 1
	v_mfma_f32_16x16x32_bf16 v[32:35], v[156:159], v[186:189], v[32:35]
	v_mfma_f32_16x16x32_bf16 v[28:31], v[164:167], v[186:189], v[28:31]
	v_mfma_f32_16x16x32_bf16 v[24:27], v[156:159], v[194:197], v[24:27]
	v_mfma_f32_16x16x32_bf16 v[20:23], v[164:167], v[194:197], v[20:23]
	v_mfma_f32_16x16x32_bf16 v[16:19], v[156:159], v[202:205], v[16:19]
	v_mfma_f32_16x16x32_bf16 v[12:15], v[164:167], v[202:205], v[12:15]
	v_mfma_f32_16x16x32_bf16 v[6:9], v[156:159], v[210:213], v[8:11]
	v_mfma_f32_16x16x32_bf16 v[2:5], v[164:167], v[210:213], v[2:5]
	v_mfma_f32_16x16x32_bf16 v[32:35], v[160:163], v[190:193], v[32:35]
	v_mfma_f32_16x16x32_bf16 v[28:31], v[182:185], v[190:193], v[28:31]
	v_mfma_f32_16x16x32_bf16 v[24:27], v[160:163], v[198:201], v[24:27]
	v_mfma_f32_16x16x32_bf16 v[20:23], v[182:185], v[198:201], v[20:23]
	v_mfma_f32_16x16x32_bf16 v[16:19], v[160:163], v[206:209], v[16:19]
	v_mfma_f32_16x16x32_bf16 v[12:15], v[182:185], v[206:209], v[12:15]
	v_mfma_f32_16x16x32_bf16 v[8:11], v[160:163], v[214:217], v[6:9]
	v_mfma_f32_16x16x32_bf16 v[4:7], v[182:185], v[214:217], v[2:5]
	s_setprio 0
	s_barrier
	s_add_u32 s8, s8, 0x100
	s_addc_u32 s9, s9, 0
	s_add_u32 s76, s76, 0x100
	s_addc_u32 vcc_lo, vcc_lo, 0
	s_cmp_ge_i32 vcc_hi, s14
	s_mov_b32 s10, vcc_hi
	s_cbranch_scc0 .LBB0_900
	s_and_b64 vcc, exec, s[18:19]
	s_cbranch_vccz .LBB0_903
	s_barrier

; #define PG8_STAGE(bufoff, gbase, voff) do { _Pragma("unroll") for (int _i = 0; _i < 2; ++_i) \
;         __builtin_amdgcn_global_load_lds((const unsigned*)((const char*)(gbase) + (voff)[_i]), (PG8_LAS unsigned*)(lds + (bufoff) + ldsw + _i * 8192), 16, 0, 0); } while (0)
; #define PG8_LDA(dst, b, h) do { _Pragma("unroll") for (int m = 0; m < 4; ++m) _Pragma("unroll") for (int k = 0; k < 2; ++k) dst[m][k] = *(const PG8_LAS bf16x8*)(lds + PG8_SA(b, h) + aoff + m * 2048 + k * 1024); } while (0)
; #define PG8_LDB(dst, b, h) do { _Pragma("unroll") for (int n = 0; n < 2; ++n) _Pragma("unroll") for (int k = 0; k < 2; ++k) dst[n][k] = *(const PG8_LAS bf16x8*)(lds + PG8_SB(b, h) + boff + n * 2048 + k * 1024); } while (0)
; #define PG8_MMA(ai, bj, At, Bt) do { __builtin_amdgcn_s_setprio(1); _Pragma("unroll") for (int m = 0; m < 4; ++m) _Pragma("unroll") for (int n = 0; n < 2; ++n) _Pragma("unroll") for (int k = 0; k < 2; ++k) \
;         acc[ai][bj][m][n] = __builtin_amdgcn_mfma_f32_16x16x32_bf16(Bt[n][k], At[m][k], acc[ai][bj][m][n], 0, 0, 0); __builtin_amdgcn_s_setprio(0); } while (0)
; #define PG8_WAIT_V(n) asm volatile("s_waitcnt vmcnt(" #n ")" ::: "memory")
; #define PG8_WAIT_L(n) asm volatile("s_waitcnt lgkmcnt(" #n ")" ::: "memory")
; template <class Epi, class Sched, bool ALIGN_EPI = false, bool SP2 = false>
; __device__ __forceinline__ void gemm_phase(PG8_LAS unsigned char* lds, const Gemm g, const Sched& S, const Epi& E, int tid_in) {
;     ...
;             const bool last = (t == nt - 2);
;             const char* a1 = cA + (size_t)(t + 1) * kstep;
;             const char* a2 = last ? nA : cA + (size_t)(t + 2) * kstep; const char* b2 = last ? nB : cB + (size_t)(t + 2) * kstep;
;             const char* a3 = a2 + kstep; const char* b3 = b2 + kstep;
;             if (last && has_next) S.a_ready(nxt);
;             if constexpr (SP2) {
;             PG8_LDB(B0, 0, 0); PG8_LDB(B1, 0, 1); PG8_SCHED; PG8_LDA(At, 0, 0); PG8_STAGE(PG8_SA(1, 1), a1 + hstepA, voffA);
;             PG8_WAIT_V(8); PG8_WAIT_L(0); PG8_BAR; PG8_MMA(0, 0, At, B0); PG8_MMA(0, 1, At, B1); PG8_BAR; PG8_SCHED;
;             PG8_LDA(At, 0, 1); PG8_STAGE(PG8_SB(0, 0), b2, voffB); PG8_STAGE(PG8_SB(0, 1), b2 + hstep, voffB); PG8_STAGE(PG8_SA(0, 0), a2, voffA);
;             PG8_WAIT_V(8); PG8_WAIT_L(0); PG8_BAR; PG8_MMA(1, 0, At, B0); PG8_MMA(1, 1, At, B1); PG8_BAR; PG8_SCHED;
.LBB0_1348:
	v_add_u32_e32 v152, s4, v146
	v_add_u32_e32 v168, s5, v146
	ds_read_b128 v[136:139], v152
	ds_read_b128 v[140:143], v152 offset:1024
	ds_read_b128 v[148:151], v152 offset:2048
	ds_read_b128 v[152:155], v152 offset:3072
	ds_read_b128 v[156:159], v168
	ds_read_b128 v[160:163], v168 offset:1024
	ds_read_b128 v[164:167], v168 offset:2048
	ds_read_b128 v[182:185], v168 offset:3072
	s_add_i32 s76, s26, 2
	s_add_u32 s27, s24, 0xfff80080
	s_addc_u32 s28, s25, -1
	s_cmp_eq_u32 s67, s26
	s_cselect_b32 s26, s66, s68
	s_cselect_b32 s29, s46, s28
	s_cselect_b32 s28, s47, s27
	s_cselect_b32 s27, s49, s70
	v_lshl_add_u64 v[168:169], s[24:25], 0, v[132:133]
	s_add_i32 m0, s31, 0xc000
	ds_read_b128 v[186:189], v147
	ds_read_b128 v[190:193], v147 offset:1024
	ds_read_b128 v[194:197], v147 offset:2048
	ds_read_b128 v[198:201], v147 offset:3072
	ds_read_b128 v[202:205], v147 offset:4096
	ds_read_b128 v[206:209], v147 offset:5120
	ds_read_b128 v[210:213], v147 offset:6144
	ds_read_b128 v[214:217], v147 offset:7168
	global_load_lds_dwordx4 v[168:169], off
	s_add_i32 m0, s31, 0xe000
	v_lshl_add_u64 v[168:169], s[24:25], 0, v[134:135]
	global_load_lds_dwordx4 v[168:169], off
	s_waitcnt vmcnt(8)
	s_waitcnt lgkmcnt(0)
	s_barrier
	s_setprio 1
	s_waitcnt lgkmcnt(0)
	v_mfma_f32_16x16x32_bf16 v[126:129], v[136:139], v[186:189], v[126:129]
	v_mfma_f32_16x16x32_bf16 v[122:125], v[148:151], v[186:189], v[122:125]
	v_mfma_f32_16x16x32_bf16 v[118:121], v[136:139], v[194:197], v[118:121]
	v_mfma_f32_16x16x32_bf16 v[114:117], v[148:151], v[194:197], v[114:117]
	v_mfma_f32_16x16x32_bf16 v[110:113], v[136:139], v[202:205], v[110:113]
	v_mfma_f32_16x16x32_bf16 v[106:109], v[148:151], v[202:205], v[106:109]
	v_mfma_f32_16x16x32_bf16 v[102:105], v[136:139], v[210:213], v[102:105]
	v_mfma_f32_16x16x32_bf16 v[98:101], v[148:151], v[210:213], v[98:101]
	v_mfma_f32_16x16x32_bf16 v[126:129], v[140:143], v[190:193], v[126:129]
	v_mfma_f32_16x16x32_bf16 v[122:125], v[152:155], v[190:193], v[122:125]
	v_mfma_f32_16x16x32_bf16 v[118:121], v[140:143], v[198:201], v[118:121]
	v_mfma_f32_16x16x32_bf16 v[114:117], v[152:155], v[198:201], v[114:117]
	v_mfma_f32_16x16x32_bf16 v[110:113], v[140:143], v[206:209], v[110:113]
	v_mfma_f32_16x16x32_bf16 v[106:109], v[152:155], v[206:209], v[106:109]
	v_mfma_f32_16x16x32_bf16 v[102:105], v[140:143], v[214:217], v[102:105]
	v_mfma_f32_16x16x32_bf16 v[98:101], v[152:155], v[214:217], v[98:101]
	s_setprio 0
	s_setprio 1
	v_mfma_f32_16x16x32_bf16 v[94:97], v[156:159], v[186:189], v[94:97]
	v_mfma_f32_16x16x32_bf16 v[90:93], v[164:167], v[186:189], v[90:93]
	v_mfma_f32_16x16x32_bf16 v[86:89], v[156:159], v[194:197], v[86:89]
	v_mfma_f32_16x16x32_bf16 v[82:85], v[164:167], v[194:197], v[82:85]
	v_mfma_f32_16x16x32_bf16 v[78:81], v[156:159], v[202:205], v[78:81]
	v_mfma_f32_16x16x32_bf16 v[74:77], v[164:167], v[202:205], v[74:77]
	v_mfma_f32_16x16x32_bf16 v[70:73], v[156:159], v[210:213], v[70:73]
	v_mfma_f32_16x16x32_bf16 v[66:69], v[164:167], v[210:213], v[66:69]
	v_mfma_f32_16x16x32_bf16 v[94:97], v[160:163], v[190:193], v[94:97]
	v_mfma_f32_16x16x32_bf16 v[90:93], v[182:185], v[190:193], v[90:93]
	v_mfma_f32_16x16x32_bf16 v[86:89], v[160:163], v[198:201], v[86:89]
	v_mfma_f32_16x16x32_bf16 v[82:85], v[182:185], v[198:201], v[82:85]
	v_mfma_f32_16x16x32_bf16 v[78:81], v[160:163], v[206:209], v[78:81]
	v_mfma_f32_16x16x32_bf16 v[74:77], v[182:185], v[206:209], v[74:77]
	v_mfma_f32_16x16x32_bf16 v[70:73], v[160:163], v[214:217], v[70:73]
	v_mfma_f32_16x16x32_bf16 v[66:69], v[182:185], v[214:217], v[66:69]
	s_setprio 0
	s_barrier
	s_add_i32 s64, s4, s30
	v_lshl_add_u64 v[168:169], s[26:27], 0, v[0:1]
	s_mov_b32 m0, s64
	ds_read_b128 v[186:189], v147 offset:16384
	ds_read_b128 v[190:193], v147 offset:17408
	ds_read_b128 v[194:197], v147 offset:18432
	ds_read_b128 v[198:201], v147 offset:19456
	ds_read_b128 v[202:205], v147 offset:20480
	ds_read_b128 v[206:209], v147 offset:21504
	ds_read_b128 v[210:213], v147 offset:22528
	ds_read_b128 v[214:217], v147 offset:23552
	global_load_lds_dwordx4 v[168:169], off
	s_add_i32 m0, s64, 0x2000
	s_add_u32 s64, s26, 0x80000
	v_lshl_add_u64 v[218:219], s[26:27], 0, v[130:131]
	s_addc_u32 s65, s27, 0
	s_add_i32 s79, s5, s30
	global_load_lds_dwordx4 v[218:219], off
	v_lshl_add_u64 v[220:221], s[64:65], 0, v[0:1]
	s_mov_b32 m0, s79
	v_lshl_add_u64 v[222:223], s[28:29], 0, v[130:131]
	global_load_lds_dwordx4 v[220:221], off
	s_add_i32 m0, s79, 0x2000
	v_lshl_add_u64 v[220:221], s[64:65], 0, v[130:131]
	global_load_lds_dwordx4 v[220:221], off
	s_mov_b32 m0, s31
	v_lshl_add_u64 v[220:221], s[28:29], 0, v[0:1]
	global_load_lds_dwordx4 v[220:221], off
	s_mov_b32 m0, s33
	s_nop 0
	global_load_lds_dwordx4 v[222:223], off
	s_waitcnt vmcnt(8)
	s_waitcnt lgkmcnt(0)
	s_barrier
; #define PG8_STAGE(bufoff, gbase, voff) do { _Pragma("unroll") for (int _i = 0; _i < 2; ++_i) \
;         __builtin_amdgcn_global_load_lds((const unsigned*)((const char*)(gbase) + (voff)[_i]), (PG8_LAS unsigned*)(lds + (bufoff) + ldsw + _i * 8192), 16, 0, 0); } while (0)
; #define PG8_LDA(dst, b, h) do { _Pragma("unroll") for (int m = 0; m < 4; ++m) _Pragma("unroll") for (int k = 0; k < 2; ++k) dst[m][k] = *(const PG8_LAS bf16x8*)(lds + PG8_SA(b, h) + aoff + m * 2048 + k * 1024); } while (0)
; #define PG8_LDB(dst, b, h) do { _Pragma("unroll") for (int n = 0; n < 2; ++n) _Pragma("unroll") for (int k = 0; k < 2; ++k) dst[n][k] = *(const PG8_LAS bf16x8*)(lds + PG8_SB(b, h) + boff + n * 2048 + k * 1024); } while (0)
; #define PG8_MMA(ai, bj, At, Bt) do { __builtin_amdgcn_s_setprio(1); _Pragma("unroll") for (int m = 0; m < 4; ++m) _Pragma("unroll") for (int n = 0; n < 2; ++n) _Pragma("unroll") for (int k = 0; k < 2; ++k) \
;         acc[ai][bj][m][n] = __builtin_amdgcn_mfma_f32_16x16x32_bf16(Bt[n][k], At[m][k], acc[ai][bj][m][n], 0, 0, 0); __builtin_amdgcn_s_setprio(0); } while (0)
; #define PG8_WAIT_V(n) asm volatile("s_waitcnt vmcnt(" #n ")" ::: "memory")
; #define PG8_WAIT_L(n) asm volatile("s_waitcnt lgkmcnt(" #n ")" ::: "memory")
; #define PG8_BAR __builtin_amdgcn_s_barrier()
; #define PG8_SCHED __builtin_amdgcn_sched_barrier(0)
; template <class Epi, class Sched, bool ALIGN_EPI = false, bool SP2 = false>
; __device__ __forceinline__ void gemm_phase(PG8_LAS unsigned char* lds, const Gemm g, const Sched& S, const Epi& E, int tid_in) {
;     ...
;             PG8_WAIT_V(8); PG8_WAIT_L(0); PG8_BAR; PG8_MMA(1, 0, At, B0); PG8_MMA(1, 1, At, B1); PG8_BAR; PG8_SCHED;
;             PG8_LDB(B0, 1, 0); PG8_LDB(B1, 1, 1); PG8_SCHED; PG8_LDA(At, 1, 0); PG8_STAGE(PG8_SA(0, 1), a2 + hstepA, voffA);
;             PG8_WAIT_V(8); PG8_WAIT_L(0); PG8_BAR; PG8_MMA(0, 0, At, B0); PG8_MMA(0, 1, At, B1); PG8_BAR; PG8_SCHED;
	s_setprio 1
	s_waitcnt lgkmcnt(0)
	v_mfma_f32_16x16x32_bf16 v[62:65], v[136:139], v[186:189], v[62:65]
	v_mfma_f32_16x16x32_bf16 v[58:61], v[148:151], v[186:189], v[58:61]
	v_mfma_f32_16x16x32_bf16 v[54:57], v[136:139], v[194:197], v[54:57]
	v_mfma_f32_16x16x32_bf16 v[50:53], v[148:151], v[194:197], v[50:53]
	v_mfma_f32_16x16x32_bf16 v[46:49], v[136:139], v[202:205], v[46:49]
	v_mfma_f32_16x16x32_bf16 v[42:45], v[148:151], v[202:205], v[42:45]
	v_mfma_f32_16x16x32_bf16 v[38:41], v[136:139], v[210:213], v[38:41]
	v_mfma_f32_16x16x32_bf16 v[34:37], v[148:151], v[210:213], v[34:37]
	v_mfma_f32_16x16x32_bf16 v[62:65], v[140:143], v[190:193], v[62:65]
	v_mfma_f32_16x16x32_bf16 v[58:61], v[152:155], v[190:193], v[58:61]
	v_mfma_f32_16x16x32_bf16 v[54:57], v[140:143], v[198:201], v[54:57]
	v_mfma_f32_16x16x32_bf16 v[50:53], v[152:155], v[198:201], v[50:53]
	v_mfma_f32_16x16x32_bf16 v[46:49], v[140:143], v[206:209], v[46:49]
	v_mfma_f32_16x16x32_bf16 v[42:45], v[152:155], v[206:209], v[42:45]
	v_mfma_f32_16x16x32_bf16 v[38:41], v[140:143], v[214:217], v[38:41]
	v_mfma_f32_16x16x32_bf16 v[34:37], v[152:155], v[214:217], v[34:37]
	s_setprio 0
	s_setprio 1
	v_mfma_f32_16x16x32_bf16 v[30:33], v[156:159], v[186:189], v[30:33]
	v_mfma_f32_16x16x32_bf16 v[26:29], v[164:167], v[186:189], v[26:29]
	v_mfma_f32_16x16x32_bf16 v[22:25], v[156:159], v[194:197], v[22:25]
	v_mfma_f32_16x16x32_bf16 v[18:21], v[164:167], v[194:197], v[18:21]
	v_mfma_f32_16x16x32_bf16 v[14:17], v[156:159], v[202:205], v[14:17]
	v_mfma_f32_16x16x32_bf16 v[10:13], v[164:167], v[202:205], v[10:13]
	v_mfma_f32_16x16x32_bf16 v[6:9], v[156:159], v[210:213], v[6:9]
	v_mfma_f32_16x16x32_bf16 v[2:5], v[164:167], v[210:213], v[2:5]
	v_mfma_f32_16x16x32_bf16 v[30:33], v[160:163], v[190:193], v[30:33]
	v_mfma_f32_16x16x32_bf16 v[26:29], v[182:185], v[190:193], v[26:29]
	v_mfma_f32_16x16x32_bf16 v[22:25], v[160:163], v[198:201], v[22:25]
	v_mfma_f32_16x16x32_bf16 v[18:21], v[182:185], v[198:201], v[18:21]
	v_mfma_f32_16x16x32_bf16 v[14:17], v[160:163], v[206:209], v[14:17]
	v_mfma_f32_16x16x32_bf16 v[10:13], v[182:185], v[206:209], v[10:13]
	v_mfma_f32_16x16x32_bf16 v[6:9], v[160:163], v[214:217], v[6:9]
	v_mfma_f32_16x16x32_bf16 v[2:5], v[182:185], v[214:217], v[2:5]
	s_setprio 0
	s_barrier
	v_add_u32_e32 v152, s63, v146
	v_add_u32_e32 v182, s55, v146
	ds_read_b128 v[136:139], v152
	ds_read_b128 v[140:143], v152 offset:1024
	ds_read_b128 v[148:151], v152 offset:2048
	ds_read_b128 v[152:155], v152 offset:3072
	ds_read_b128 v[156:159], v182
	ds_read_b128 v[160:163], v182 offset:1024
	ds_read_b128 v[164:167], v182 offset:2048
	ds_read_b128 v[182:185], v182 offset:3072
	s_add_u32 s28, s28, 0x80000
	s_addc_u32 s29, s29, 0
	s_mov_b32 m0, s34
	v_lshl_add_u64 v[224:225], s[28:29], 0, v[0:1]
	ds_read_b128 v[186:189], v147 offset:32768
	ds_read_b128 v[190:193], v147 offset:33792
	ds_read_b128 v[194:197], v147 offset:34816
	ds_read_b128 v[198:201], v147 offset:35840
	ds_read_b128 v[202:205], v147 offset:36864
	ds_read_b128 v[206:209], v147 offset:37888
	ds_read_b128 v[210:213], v147 offset:38912
	ds_read_b128 v[214:217], v147 offset:39936
	global_load_lds_dwordx4 v[224:225], off
	s_mov_b32 m0, s35
	v_lshl_add_u64 v[224:225], s[28:29], 0, v[130:131]
	global_load_lds_dwordx4 v[224:225], off
	s_waitcnt vmcnt(8)
	s_waitcnt lgkmcnt(0)
	s_barrier
	s_setprio 1
	s_waitcnt lgkmcnt(0)
	v_mfma_f32_16x16x32_bf16 v[126:129], v[136:139], v[186:189], v[126:129]
	v_mfma_f32_16x16x32_bf16 v[122:125], v[148:151], v[186:189], v[122:125]
	v_mfma_f32_16x16x32_bf16 v[118:121], v[136:139], v[194:197], v[118:121]
	v_mfma_f32_16x16x32_bf16 v[114:117], v[148:151], v[194:197], v[114:117]
	v_mfma_f32_16x16x32_bf16 v[110:113], v[136:139], v[202:205], v[110:113]
	v_mfma_f32_16x16x32_bf16 v[106:109], v[148:151], v[202:205], v[106:109]
	v_mfma_f32_16x16x32_bf16 v[102:105], v[136:139], v[210:213], v[102:105]
	v_mfma_f32_16x16x32_bf16 v[98:101], v[148:151], v[210:213], v[98:101]
	v_mfma_f32_16x16x32_bf16 v[126:129], v[140:143], v[190:193], v[126:129]
	v_mfma_f32_16x16x32_bf16 v[122:125], v[152:155], v[190:193], v[122:125]
	v_mfma_f32_16x16x32_bf16 v[118:121], v[140:143], v[198:201], v[118:121]
	v_mfma_f32_16x16x32_bf16 v[114:117], v[152:155], v[198:201], v[114:117]
	v_mfma_f32_16x16x32_bf16 v[110:113], v[140:143], v[206:209], v[110:113]
	v_mfma_f32_16x16x32_bf16 v[106:109], v[152:155], v[206:209], v[106:109]
	v_mfma_f32_16x16x32_bf16 v[102:105], v[140:143], v[214:217], v[102:105]
	v_mfma_f32_16x16x32_bf16 v[98:101], v[152:155], v[214:217], v[98:101]
	s_setprio 0
	s_setprio 1
	v_mfma_f32_16x16x32_bf16 v[94:97], v[156:159], v[186:189], v[94:97]
	v_mfma_f32_16x16x32_bf16 v[90:93], v[164:167], v[186:189], v[90:93]
	v_mfma_f32_16x16x32_bf16 v[86:89], v[156:159], v[194:197], v[86:89]
	v_mfma_f32_16x16x32_bf16 v[82:85], v[164:167], v[194:197], v[82:85]
	v_mfma_f32_16x16x32_bf16 v[78:81], v[156:159], v[202:205], v[78:81]
	v_mfma_f32_16x16x32_bf16 v[74:77], v[164:167], v[202:205], v[74:77]
	v_mfma_f32_16x16x32_bf16 v[70:73], v[156:159], v[210:213], v[70:73]
	v_mfma_f32_16x16x32_bf16 v[66:69], v[164:167], v[210:213], v[66:69]
	v_mfma_f32_16x16x32_bf16 v[94:97], v[160:163], v[190:193], v[94:97]
	v_mfma_f32_16x16x32_bf16 v[90:93], v[182:185], v[190:193], v[90:93]
	v_mfma_f32_16x16x32_bf16 v[86:89], v[160:163], v[198:201], v[86:89]
	v_mfma_f32_16x16x32_bf16 v[82:85], v[182:185], v[198:201], v[82:85]
	v_mfma_f32_16x16x32_bf16 v[78:81], v[160:163], v[206:209], v[78:81]
	v_mfma_f32_16x16x32_bf16 v[74:77], v[182:185], v[206:209], v[74:77]
	v_mfma_f32_16x16x32_bf16 v[70:73], v[160:163], v[214:217], v[70:73]
	v_mfma_f32_16x16x32_bf16 v[66:69], v[182:185], v[214:217], v[66:69]
	s_setprio 0
	s_barrier
; #define PG8_STAGE(bufoff, gbase, voff) do { _Pragma("unroll") for (int _i = 0; _i < 2; ++_i) \
;         __builtin_amdgcn_global_load_lds((const unsigned*)((const char*)(gbase) + (voff)[_i]), (PG8_LAS unsigned*)(lds + (bufoff) + ldsw + _i * 8192), 16, 0, 0); } while (0)
; #define PG8_LDA(dst, b, h) do { _Pragma("unroll") for (int m = 0; m < 4; ++m) _Pragma("unroll") for (int k = 0; k < 2; ++k) dst[m][k] = *(const PG8_LAS bf16x8*)(lds + PG8_SA(b, h) + aoff + m * 2048 + k * 1024); } while (0)
; #define PG8_MMA(ai, bj, At, Bt) do { __builtin_amdgcn_s_setprio(1); _Pragma("unroll") for (int m = 0; m < 4; ++m) _Pragma("unroll") for (int n = 0; n < 2; ++n) _Pragma("unroll") for (int k = 0; k < 2; ++k) \
;         acc[ai][bj][m][n] = __builtin_amdgcn_mfma_f32_16x16x32_bf16(Bt[n][k], At[m][k], acc[ai][bj][m][n], 0, 0, 0); __builtin_amdgcn_s_setprio(0); } while (0)
; #define PG8_WAIT_V(n) asm volatile("s_waitcnt vmcnt(" #n ")" ::: "memory")
; #define PG8_WAIT_L(n) asm volatile("s_waitcnt lgkmcnt(" #n ")" ::: "memory")
; #define PG8_BAR __builtin_amdgcn_s_barrier()
; #define PG8_SCHED __builtin_amdgcn_sched_barrier(0)
; template <class Epi, class Sched, bool ALIGN_EPI = false, bool SP2 = false>
; __device__ __forceinline__ void gemm_phase(PG8_LAS unsigned char* lds, const Gemm g, const Sched& S, const Epi& E, int tid_in) {
;     ...
;         for (int t = 0; t < nt; t += 2) {
;             const bool last = (t == nt - 2);
;     ...
;             PG8_LDA(At, 1, 1); PG8_STAGE(PG8_SB(1, 0), b3, voffB); PG8_STAGE(PG8_SB(1, 1), b3 + hstep, voffB); PG8_STAGE(PG8_SA(1, 0), a3, voffA);
;             PG8_WAIT_V(8); PG8_WAIT_L(0); PG8_BAR; PG8_MMA(1, 0, At, B0); PG8_MMA(1, 1, At, B1); PG8_BAR; PG8_SCHED;
	s_add_i32 s28, s63, s30
	v_lshl_add_u64 v[168:169], v[168:169], 0, s[90:91]
	s_mov_b32 m0, s28
	ds_read_b128 v[186:189], v147 offset:49152
	ds_read_b128 v[190:193], v147 offset:50176
	ds_read_b128 v[194:197], v147 offset:51200
	ds_read_b128 v[198:201], v147 offset:52224
	ds_read_b128 v[202:205], v147 offset:53248
	ds_read_b128 v[206:209], v147 offset:54272
	ds_read_b128 v[210:213], v147 offset:55296
	ds_read_b128 v[214:217], v147 offset:56320
	global_load_lds_dwordx4 v[168:169], off
	s_add_i32 m0, s28, 0x2000
	s_add_u32 s26, s26, 0x80080
	v_lshl_add_u64 v[168:169], v[218:219], 0, s[90:91]
	s_addc_u32 s27, s27, 0
	s_add_i32 s28, s55, s30
	global_load_lds_dwordx4 v[168:169], off
	s_mov_b32 m0, s28
	v_lshl_add_u64 v[168:169], s[26:27], 0, v[0:1]
	global_load_lds_dwordx4 v[168:169], off
	s_add_i32 m0, s28, 0x2000
	v_lshl_add_u64 v[168:169], s[26:27], 0, v[130:131]
	global_load_lds_dwordx4 v[168:169], off
	s_mov_b32 m0, s41
	v_lshl_add_u64 v[168:169], v[220:221], 0, s[90:91]
	global_load_lds_dwordx4 v[168:169], off
	s_mov_b32 m0, s42
	v_lshl_add_u64 v[168:169], v[222:223], 0, s[90:91]
	global_load_lds_dwordx4 v[168:169], off
	s_waitcnt vmcnt(8)
	s_waitcnt lgkmcnt(0)
	s_barrier
	s_setprio 1
	s_waitcnt lgkmcnt(0)
	v_mfma_f32_16x16x32_bf16 v[62:65], v[136:139], v[186:189], v[62:65]
	v_mfma_f32_16x16x32_bf16 v[58:61], v[148:151], v[186:189], v[58:61]
	v_mfma_f32_16x16x32_bf16 v[54:57], v[136:139], v[194:197], v[54:57]
	v_mfma_f32_16x16x32_bf16 v[50:53], v[148:151], v[194:197], v[50:53]
	v_mfma_f32_16x16x32_bf16 v[46:49], v[136:139], v[202:205], v[46:49]
	v_mfma_f32_16x16x32_bf16 v[42:45], v[148:151], v[202:205], v[42:45]
	v_mfma_f32_16x16x32_bf16 v[38:41], v[136:139], v[210:213], v[38:41]
	v_mfma_f32_16x16x32_bf16 v[34:37], v[148:151], v[210:213], v[34:37]
	v_mfma_f32_16x16x32_bf16 v[62:65], v[140:143], v[190:193], v[62:65]
	v_mfma_f32_16x16x32_bf16 v[58:61], v[152:155], v[190:193], v[58:61]
	v_mfma_f32_16x16x32_bf16 v[54:57], v[140:143], v[198:201], v[54:57]
	v_mfma_f32_16x16x32_bf16 v[50:53], v[152:155], v[198:201], v[50:53]
	v_mfma_f32_16x16x32_bf16 v[46:49], v[140:143], v[206:209], v[46:49]
	v_mfma_f32_16x16x32_bf16 v[42:45], v[152:155], v[206:209], v[42:45]
	v_mfma_f32_16x16x32_bf16 v[38:41], v[140:143], v[214:217], v[38:41]
	v_mfma_f32_16x16x32_bf16 v[34:37], v[152:155], v[214:217], v[34:37]
	s_setprio 0
	s_setprio 1
	v_mfma_f32_16x16x32_bf16 v[30:33], v[156:159], v[186:189], v[30:33]
	v_mfma_f32_16x16x32_bf16 v[26:29], v[164:167], v[186:189], v[26:29]
	v_mfma_f32_16x16x32_bf16 v[22:25], v[156:159], v[194:197], v[22:25]
	v_mfma_f32_16x16x32_bf16 v[18:21], v[164:167], v[194:197], v[18:21]
	v_mfma_f32_16x16x32_bf16 v[14:17], v[156:159], v[202:205], v[14:17]
	v_mfma_f32_16x16x32_bf16 v[10:13], v[164:167], v[202:205], v[10:13]
	v_mfma_f32_16x16x32_bf16 v[6:9], v[156:159], v[210:213], v[6:9]
	v_mfma_f32_16x16x32_bf16 v[2:5], v[164:167], v[210:213], v[2:5]
	v_mfma_f32_16x16x32_bf16 v[30:33], v[160:163], v[190:193], v[30:33]
	v_mfma_f32_16x16x32_bf16 v[26:29], v[182:185], v[190:193], v[26:29]
	v_mfma_f32_16x16x32_bf16 v[22:25], v[160:163], v[198:201], v[22:25]
	v_mfma_f32_16x16x32_bf16 v[18:21], v[182:185], v[198:201], v[18:21]
	v_mfma_f32_16x16x32_bf16 v[14:17], v[160:163], v[206:209], v[14:17]
	v_mfma_f32_16x16x32_bf16 v[10:13], v[182:185], v[206:209], v[10:13]
	v_mfma_f32_16x16x32_bf16 v[6:9], v[160:163], v[214:217], v[6:9]
	v_mfma_f32_16x16x32_bf16 v[2:5], v[182:185], v[214:217], v[2:5]
	s_setprio 0
	s_barrier
	s_add_u32 s24, s24, 0x100
	s_addc_u32 s25, s25, 0
	s_add_u32 s68, s68, 0x100
	s_addc_u32 s70, s70, 0
	s_cmp_ge_u32 s76, s45
	s_mov_b32 s26, s76
	s_cbranch_scc0 .LBB0_1348
	s_and_b64 vcc, exec, s[16:17]
	s_cbranch_vccz .LBB0_1351
	s_barrier

; #define PG8_STAGE(bufoff, gbase, voff) do { _Pragma("unroll") for (int _i = 0; _i < 2; ++_i) \
;         __builtin_amdgcn_global_load_lds((const unsigned*)((const char*)(gbase) + (voff)[_i]), (PG8_LAS unsigned*)(lds + (bufoff) + ldsw + _i * 8192), 16, 0, 0); } while (0)
; #define PG8_LDA(dst, b, h) do { _Pragma("unroll") for (int m = 0; m < 4; ++m) _Pragma("unroll") for (int k = 0; k < 2; ++k) dst[m][k] = *(const PG8_LAS bf16x8*)(lds + PG8_SA(b, h) + aoff + m * 2048 + k * 1024); } while (0)
; #define PG8_LDB(dst, b, h) do { _Pragma("unroll") for (int n = 0; n < 2; ++n) _Pragma("unroll") for (int k = 0; k < 2; ++k) dst[n][k] = *(const PG8_LAS bf16x8*)(lds + PG8_SB(b, h) + boff + n * 2048 + k * 1024); } while (0)
; #define PG8_MMA(ai, bj, At, Bt) do { __builtin_amdgcn_s_setprio(1); _Pragma("unroll") for (int m = 0; m < 4; ++m) _Pragma("unroll") for (int n = 0; n < 2; ++n) _Pragma("unroll") for (int k = 0; k < 2; ++k) \
;         acc[ai][bj][m][n] = __builtin_amdgcn_mfma_f32_16x16x32_bf16(Bt[n][k], At[m][k], acc[ai][bj][m][n], 0, 0, 0); __builtin_amdgcn_s_setprio(0); } while (0)
; #define PG8_WAIT_V(n) asm volatile("s_waitcnt vmcnt(" #n ")" ::: "memory")
; #define PG8_WAIT_L(n) asm volatile("s_waitcnt lgkmcnt(" #n ")" ::: "memory")
; template <class Epi, class Sched, bool ALIGN_EPI = false, bool SP2 = false>
; __device__ __forceinline__ void gemm_phase(PG8_LAS unsigned char* lds, const Gemm g, const Sched& S, const Epi& E, int tid_in) {
;     ...
;             const bool last = (t == nt - 2);
;             const char* a1 = cA + (size_t)(t + 1) * kstep;
;             const char* a2 = last ? nA : cA + (size_t)(t + 2) * kstep; const char* b2 = last ? nB : cB + (size_t)(t + 2) * kstep;
;             const char* a3 = a2 + kstep; const char* b3 = b2 + kstep;
;             if (last && has_next) S.a_ready(nxt);
;             if constexpr (SP2) {
;             PG8_LDB(B0, 0, 0); PG8_LDB(B1, 0, 1); PG8_SCHED; PG8_LDA(At, 0, 0); PG8_STAGE(PG8_SA(1, 1), a1 + hstepA, voffA);
;             PG8_WAIT_V(8); PG8_WAIT_L(0); PG8_BAR; PG8_MMA(0, 0, At, B0); PG8_MMA(0, 1, At, B1); PG8_BAR; PG8_SCHED;
;             PG8_LDA(At, 0, 1); PG8_STAGE(PG8_SB(0, 0), b2, voffB); PG8_STAGE(PG8_SB(0, 1), b2 + hstep, voffB); PG8_STAGE(PG8_SA(0, 0), a2, voffA);
;             PG8_WAIT_V(8); PG8_WAIT_L(0); PG8_BAR; PG8_MMA(1, 0, At, B0); PG8_MMA(1, 1, At, B1); PG8_BAR; PG8_SCHED;
.LBB0_1507:
	v_add_u32_e32 v158, s4, v152
	v_add_u32_e32 v186, s5, v152
	ds_read_b128 v[142:145], v158
	ds_read_b128 v[146:149], v158 offset:1024
	ds_read_b128 v[154:157], v158 offset:2048
	ds_read_b128 v[158:161], v158 offset:3072
	ds_read_b128 v[162:165], v186
	ds_read_b128 v[166:169], v186 offset:1024
	ds_read_b128 v[182:185], v186 offset:2048
	ds_read_b128 v[186:189], v186 offset:3072
	s_add_u32 s26, s24, 0xfff80080
	s_addc_u32 s27, s25, -1
	s_cmp_eq_u32 s23, 28
	s_cselect_b32 s29, s19, s27
	s_cselect_b32 s28, s18, s26
	s_cselect_b32 s27, s21, s17
	s_cselect_b32 s26, s20, s15
	v_lshl_add_u64 v[222:223], s[24:25], 0, v[138:139]
	s_add_i32 m0, s35, 0xc000
	ds_read_b128 v[190:193], v153
	ds_read_b128 v[194:197], v153 offset:1024
	ds_read_b128 v[198:201], v153 offset:2048
	ds_read_b128 v[202:205], v153 offset:3072
	ds_read_b128 v[206:209], v153 offset:4096
	ds_read_b128 v[210:213], v153 offset:5120
	ds_read_b128 v[214:217], v153 offset:6144
	ds_read_b128 v[218:221], v153 offset:7168
	global_load_lds_dwordx4 v[222:223], off
	s_add_i32 m0, s35, 0xe000
	v_lshl_add_u64 v[222:223], s[24:25], 0, v[140:141]
	global_load_lds_dwordx4 v[222:223], off
	s_waitcnt vmcnt(8)
	s_waitcnt lgkmcnt(0)
	s_barrier
	s_setprio 1
	s_waitcnt lgkmcnt(0)
	v_mfma_f32_16x16x32_bf16 v[126:129], v[142:145], v[190:193], v[126:129]
	v_mfma_f32_16x16x32_bf16 v[118:121], v[154:157], v[190:193], v[118:121]
	v_mfma_f32_16x16x32_bf16 v[110:113], v[142:145], v[198:201], v[110:113]
	v_mfma_f32_16x16x32_bf16 v[102:105], v[154:157], v[198:201], v[102:105]
	v_mfma_f32_16x16x32_bf16 v[94:97], v[142:145], v[206:209], v[94:97]
	v_mfma_f32_16x16x32_bf16 v[86:89], v[154:157], v[206:209], v[86:89]
	v_mfma_f32_16x16x32_bf16 v[78:81], v[142:145], v[214:217], v[78:81]
	v_mfma_f32_16x16x32_bf16 v[70:73], v[154:157], v[214:217], v[70:73]
	v_mfma_f32_16x16x32_bf16 v[126:129], v[146:149], v[194:197], v[126:129]
	v_mfma_f32_16x16x32_bf16 v[118:121], v[158:161], v[194:197], v[118:121]
	v_mfma_f32_16x16x32_bf16 v[110:113], v[146:149], v[202:205], v[110:113]
	v_mfma_f32_16x16x32_bf16 v[102:105], v[158:161], v[202:205], v[102:105]
	v_mfma_f32_16x16x32_bf16 v[94:97], v[146:149], v[210:213], v[94:97]
	v_mfma_f32_16x16x32_bf16 v[86:89], v[158:161], v[210:213], v[86:89]
	v_mfma_f32_16x16x32_bf16 v[78:81], v[146:149], v[218:221], v[78:81]
	v_mfma_f32_16x16x32_bf16 v[70:73], v[158:161], v[218:221], v[70:73]
	s_setprio 0
	s_setprio 1
	v_mfma_f32_16x16x32_bf16 v[122:125], v[162:165], v[190:193], v[122:125]
	v_mfma_f32_16x16x32_bf16 v[114:117], v[182:185], v[190:193], v[114:117]
	v_mfma_f32_16x16x32_bf16 v[106:109], v[162:165], v[198:201], v[106:109]
	v_mfma_f32_16x16x32_bf16 v[98:101], v[182:185], v[198:201], v[98:101]
	v_mfma_f32_16x16x32_bf16 v[90:93], v[162:165], v[206:209], v[90:93]
	v_mfma_f32_16x16x32_bf16 v[82:85], v[182:185], v[206:209], v[82:85]
	v_mfma_f32_16x16x32_bf16 v[74:77], v[162:165], v[214:217], v[74:77]
	v_mfma_f32_16x16x32_bf16 v[66:69], v[182:185], v[214:217], v[66:69]
	v_mfma_f32_16x16x32_bf16 v[122:125], v[166:169], v[194:197], v[122:125]
	v_mfma_f32_16x16x32_bf16 v[114:117], v[186:189], v[194:197], v[114:117]
	v_mfma_f32_16x16x32_bf16 v[106:109], v[166:169], v[202:205], v[106:109]
	v_mfma_f32_16x16x32_bf16 v[98:101], v[186:189], v[202:205], v[98:101]
	v_mfma_f32_16x16x32_bf16 v[90:93], v[166:169], v[210:213], v[90:93]
	v_mfma_f32_16x16x32_bf16 v[82:85], v[186:189], v[210:213], v[82:85]
	v_mfma_f32_16x16x32_bf16 v[74:77], v[166:169], v[218:221], v[74:77]
	v_mfma_f32_16x16x32_bf16 v[66:69], v[186:189], v[218:221], v[66:69]
	s_setprio 0
	s_barrier
	s_add_i32 s47, s4, s34
	v_lshl_add_u64 v[222:223], s[26:27], 0, v[0:1]
	s_mov_b32 m0, s47
	ds_read_b128 v[190:193], v153 offset:16384
	ds_read_b128 v[194:197], v153 offset:17408
	ds_read_b128 v[198:201], v153 offset:18432
	ds_read_b128 v[202:205], v153 offset:19456
	ds_read_b128 v[206:209], v153 offset:20480
	ds_read_b128 v[210:213], v153 offset:21504
	ds_read_b128 v[214:217], v153 offset:22528
	ds_read_b128 v[218:221], v153 offset:23552
	global_load_lds_dwordx4 v[222:223], off
	s_add_i32 m0, s47, 0x2000
	s_add_u32 s48, s26, 0x80000
	v_lshl_add_u64 v[224:225], s[26:27], 0, v[130:131]
	s_addc_u32 s49, s27, 0
	s_add_i32 s47, s5, s34
	global_load_lds_dwordx4 v[224:225], off
	v_lshl_add_u64 v[226:227], s[48:49], 0, v[0:1]
	s_mov_b32 m0, s47
	v_lshl_add_u64 v[228:229], s[28:29], 0, v[132:133]
	global_load_lds_dwordx4 v[226:227], off
	s_add_i32 m0, s47, 0x2000
	v_lshl_add_u64 v[226:227], s[48:49], 0, v[130:131]
	global_load_lds_dwordx4 v[226:227], off
	s_mov_b32 m0, s35
	v_lshl_add_u64 v[226:227], s[28:29], 0, v[134:135]
	global_load_lds_dwordx4 v[226:227], off
	s_mov_b32 m0, s36
	s_nop 0
	global_load_lds_dwordx4 v[228:229], off
	s_waitcnt vmcnt(8)
	s_waitcnt lgkmcnt(0)
	s_barrier
; #define PG8_STAGE(bufoff, gbase, voff) do { _Pragma("unroll") for (int _i = 0; _i < 2; ++_i) \
;         __builtin_amdgcn_global_load_lds((const unsigned*)((const char*)(gbase) + (voff)[_i]), (PG8_LAS unsigned*)(lds + (bufoff) + ldsw + _i * 8192), 16, 0, 0); } while (0)
; #define PG8_LDA(dst, b, h) do { _Pragma("unroll") for (int m = 0; m < 4; ++m) _Pragma("unroll") for (int k = 0; k < 2; ++k) dst[m][k] = *(const PG8_LAS bf16x8*)(lds + PG8_SA(b, h) + aoff + m * 2048 + k * 1024); } while (0)
; #define PG8_LDB(dst, b, h) do { _Pragma("unroll") for (int n = 0; n < 2; ++n) _Pragma("unroll") for (int k = 0; k < 2; ++k) dst[n][k] = *(const PG8_LAS bf16x8*)(lds + PG8_SB(b, h) + boff + n * 2048 + k * 1024); } while (0)
; #define PG8_MMA(ai, bj, At, Bt) do { __builtin_amdgcn_s_setprio(1); _Pragma("unroll") for (int m = 0; m < 4; ++m) _Pragma("unroll") for (int n = 0; n < 2; ++n) _Pragma("unroll") for (int k = 0; k < 2; ++k) \
;         acc[ai][bj][m][n] = __builtin_amdgcn_mfma_f32_16x16x32_bf16(Bt[n][k], At[m][k], acc[ai][bj][m][n], 0, 0, 0); __builtin_amdgcn_s_setprio(0); } while (0)
; #define PG8_WAIT_V(n) asm volatile("s_waitcnt vmcnt(" #n ")" ::: "memory")
; #define PG8_WAIT_L(n) asm volatile("s_waitcnt lgkmcnt(" #n ")" ::: "memory")
; #define PG8_BAR __builtin_amdgcn_s_barrier()
; #define PG8_SCHED __builtin_amdgcn_sched_barrier(0)
; template <class Epi, class Sched, bool ALIGN_EPI = false, bool SP2 = false>
; __device__ __forceinline__ void gemm_phase(PG8_LAS unsigned char* lds, const Gemm g, const Sched& S, const Epi& E, int tid_in) {
;     ...
;             PG8_WAIT_V(8); PG8_WAIT_L(0); PG8_BAR; PG8_MMA(1, 0, At, B0); PG8_MMA(1, 1, At, B1); PG8_BAR; PG8_SCHED;
;             PG8_LDB(B0, 1, 0); PG8_LDB(B1, 1, 1); PG8_SCHED; PG8_LDA(At, 1, 0); PG8_STAGE(PG8_SA(0, 1), a2 + hstepA, voffA);
;             PG8_WAIT_V(8); PG8_WAIT_L(0); PG8_BAR; PG8_MMA(0, 0, At, B0); PG8_MMA(0, 1, At, B1); PG8_BAR; PG8_SCHED;
	s_setprio 1
	s_waitcnt lgkmcnt(0)
	v_mfma_f32_16x16x32_bf16 v[62:65], v[142:145], v[190:193], v[62:65]
	v_mfma_f32_16x16x32_bf16 v[54:57], v[154:157], v[190:193], v[54:57]
	v_mfma_f32_16x16x32_bf16 v[46:49], v[142:145], v[198:201], v[46:49]
	v_mfma_f32_16x16x32_bf16 v[38:41], v[154:157], v[198:201], v[38:41]
	v_mfma_f32_16x16x32_bf16 v[30:33], v[142:145], v[206:209], v[30:33]
	v_mfma_f32_16x16x32_bf16 v[22:25], v[154:157], v[206:209], v[22:25]
	v_mfma_f32_16x16x32_bf16 v[14:17], v[142:145], v[214:217], v[14:17]
	v_mfma_f32_16x16x32_bf16 v[6:9], v[154:157], v[214:217], v[6:9]
	v_mfma_f32_16x16x32_bf16 v[62:65], v[146:149], v[194:197], v[62:65]
	v_mfma_f32_16x16x32_bf16 v[54:57], v[158:161], v[194:197], v[54:57]
	v_mfma_f32_16x16x32_bf16 v[46:49], v[146:149], v[202:205], v[46:49]
	v_mfma_f32_16x16x32_bf16 v[38:41], v[158:161], v[202:205], v[38:41]
	v_mfma_f32_16x16x32_bf16 v[30:33], v[146:149], v[210:213], v[30:33]
	v_mfma_f32_16x16x32_bf16 v[22:25], v[158:161], v[210:213], v[22:25]
	v_mfma_f32_16x16x32_bf16 v[14:17], v[146:149], v[218:221], v[14:17]
	v_mfma_f32_16x16x32_bf16 v[6:9], v[158:161], v[218:221], v[6:9]
	s_setprio 0
	s_setprio 1
	v_mfma_f32_16x16x32_bf16 v[58:61], v[162:165], v[190:193], v[58:61]
	v_mfma_f32_16x16x32_bf16 v[50:53], v[182:185], v[190:193], v[50:53]
	v_mfma_f32_16x16x32_bf16 v[42:45], v[162:165], v[198:201], v[42:45]
	v_mfma_f32_16x16x32_bf16 v[34:37], v[182:185], v[198:201], v[34:37]
	v_mfma_f32_16x16x32_bf16 v[26:29], v[162:165], v[206:209], v[26:29]
	v_mfma_f32_16x16x32_bf16 v[18:21], v[182:185], v[206:209], v[18:21]
	v_mfma_f32_16x16x32_bf16 v[10:13], v[162:165], v[214:217], v[10:13]
	v_mfma_f32_16x16x32_bf16 v[2:5], v[182:185], v[214:217], v[2:5]
	v_mfma_f32_16x16x32_bf16 v[58:61], v[166:169], v[194:197], v[58:61]
	v_mfma_f32_16x16x32_bf16 v[50:53], v[186:189], v[194:197], v[50:53]
	v_mfma_f32_16x16x32_bf16 v[42:45], v[166:169], v[202:205], v[42:45]
	v_mfma_f32_16x16x32_bf16 v[34:37], v[186:189], v[202:205], v[34:37]
	v_mfma_f32_16x16x32_bf16 v[26:29], v[166:169], v[210:213], v[26:29]
	v_mfma_f32_16x16x32_bf16 v[18:21], v[186:189], v[210:213], v[18:21]
	v_mfma_f32_16x16x32_bf16 v[10:13], v[166:169], v[218:221], v[10:13]
	v_mfma_f32_16x16x32_bf16 v[2:5], v[186:189], v[218:221], v[2:5]
	s_setprio 0
	s_barrier
	v_add_u32_e32 v158, s63, v152
	v_add_u32_e32 v186, s55, v152
	ds_read_b128 v[142:145], v158
	ds_read_b128 v[146:149], v158 offset:1024
	ds_read_b128 v[154:157], v158 offset:2048
	ds_read_b128 v[158:161], v158 offset:3072
	ds_read_b128 v[162:165], v186
	ds_read_b128 v[166:169], v186 offset:1024
	ds_read_b128 v[182:185], v186 offset:2048
	ds_read_b128 v[186:189], v186 offset:3072
	s_add_u32 s28, s28, 0x80000
	s_addc_u32 s29, s29, 0
	s_mov_b32 m0, s37
	v_lshl_add_u64 v[240:241], s[28:29], 0, v[134:135]
	ds_read_b128 v[190:193], v153 offset:32768
	ds_read_b128 v[194:197], v153 offset:33792
	ds_read_b128 v[198:201], v153 offset:34816
	ds_read_b128 v[202:205], v153 offset:35840
	ds_read_b128 v[206:209], v153 offset:36864
	ds_read_b128 v[210:213], v153 offset:37888
	ds_read_b128 v[214:217], v153 offset:38912
	ds_read_b128 v[218:221], v153 offset:39936
	global_load_lds_dwordx4 v[240:241], off
	s_mov_b32 m0, s38
	v_lshl_add_u64 v[240:241], s[28:29], 0, v[132:133]
	global_load_lds_dwordx4 v[240:241], off
	s_waitcnt vmcnt(8)
	s_waitcnt lgkmcnt(0)
	s_barrier
	s_setprio 1
	s_waitcnt lgkmcnt(0)
	v_mfma_f32_16x16x32_bf16 v[126:129], v[142:145], v[190:193], v[126:129]
	v_mfma_f32_16x16x32_bf16 v[118:121], v[154:157], v[190:193], v[118:121]
	v_mfma_f32_16x16x32_bf16 v[110:113], v[142:145], v[198:201], v[110:113]
	v_mfma_f32_16x16x32_bf16 v[102:105], v[154:157], v[198:201], v[102:105]
	v_mfma_f32_16x16x32_bf16 v[94:97], v[142:145], v[206:209], v[94:97]
	v_mfma_f32_16x16x32_bf16 v[86:89], v[154:157], v[206:209], v[86:89]
	v_mfma_f32_16x16x32_bf16 v[78:81], v[142:145], v[214:217], v[78:81]
	v_mfma_f32_16x16x32_bf16 v[70:73], v[154:157], v[214:217], v[70:73]
	v_mfma_f32_16x16x32_bf16 v[126:129], v[146:149], v[194:197], v[126:129]
	v_mfma_f32_16x16x32_bf16 v[118:121], v[158:161], v[194:197], v[118:121]
	v_mfma_f32_16x16x32_bf16 v[110:113], v[146:149], v[202:205], v[110:113]
	v_mfma_f32_16x16x32_bf16 v[102:105], v[158:161], v[202:205], v[102:105]
	v_mfma_f32_16x16x32_bf16 v[94:97], v[146:149], v[210:213], v[94:97]
	v_mfma_f32_16x16x32_bf16 v[86:89], v[158:161], v[210:213], v[86:89]
	v_mfma_f32_16x16x32_bf16 v[78:81], v[146:149], v[218:221], v[78:81]
	v_mfma_f32_16x16x32_bf16 v[70:73], v[158:161], v[218:221], v[70:73]
	s_setprio 0
	s_setprio 1
	v_mfma_f32_16x16x32_bf16 v[122:125], v[162:165], v[190:193], v[122:125]
	v_mfma_f32_16x16x32_bf16 v[114:117], v[182:185], v[190:193], v[114:117]
	v_mfma_f32_16x16x32_bf16 v[106:109], v[162:165], v[198:201], v[106:109]
	v_mfma_f32_16x16x32_bf16 v[98:101], v[182:185], v[198:201], v[98:101]
	v_mfma_f32_16x16x32_bf16 v[90:93], v[162:165], v[206:209], v[90:93]
	v_mfma_f32_16x16x32_bf16 v[82:85], v[182:185], v[206:209], v[82:85]
	v_mfma_f32_16x16x32_bf16 v[74:77], v[162:165], v[214:217], v[74:77]
	v_mfma_f32_16x16x32_bf16 v[66:69], v[182:185], v[214:217], v[66:69]
	v_mfma_f32_16x16x32_bf16 v[122:125], v[166:169], v[194:197], v[122:125]
	v_mfma_f32_16x16x32_bf16 v[114:117], v[186:189], v[194:197], v[114:117]
	v_mfma_f32_16x16x32_bf16 v[106:109], v[166:169], v[202:205], v[106:109]
	v_mfma_f32_16x16x32_bf16 v[98:101], v[186:189], v[202:205], v[98:101]
	v_mfma_f32_16x16x32_bf16 v[90:93], v[166:169], v[210:213], v[90:93]
	v_mfma_f32_16x16x32_bf16 v[82:85], v[186:189], v[210:213], v[82:85]
	v_mfma_f32_16x16x32_bf16 v[74:77], v[166:169], v[218:221], v[74:77]
	v_mfma_f32_16x16x32_bf16 v[66:69], v[186:189], v[218:221], v[66:69]
	s_setprio 0
	s_barrier
; #define PG8_STAGE(bufoff, gbase, voff) do { _Pragma("unroll") for (int _i = 0; _i < 2; ++_i) \
;         __builtin_amdgcn_global_load_lds((const unsigned*)((const char*)(gbase) + (voff)[_i]), (PG8_LAS unsigned*)(lds + (bufoff) + ldsw + _i * 8192), 16, 0, 0); } while (0)
; #define PG8_LDA(dst, b, h) do { _Pragma("unroll") for (int m = 0; m < 4; ++m) _Pragma("unroll") for (int k = 0; k < 2; ++k) dst[m][k] = *(const PG8_LAS bf16x8*)(lds + PG8_SA(b, h) + aoff + m * 2048 + k * 1024); } while (0)
; #define PG8_MMA(ai, bj, At, Bt) do { __builtin_amdgcn_s_setprio(1); _Pragma("unroll") for (int m = 0; m < 4; ++m) _Pragma("unroll") for (int n = 0; n < 2; ++n) _Pragma("unroll") for (int k = 0; k < 2; ++k) \
;         acc[ai][bj][m][n] = __builtin_amdgcn_mfma_f32_16x16x32_bf16(Bt[n][k], At[m][k], acc[ai][bj][m][n], 0, 0, 0); __builtin_amdgcn_s_setprio(0); } while (0)
; #define PG8_WAIT_V(n) asm volatile("s_waitcnt vmcnt(" #n ")" ::: "memory")
; #define PG8_WAIT_L(n) asm volatile("s_waitcnt lgkmcnt(" #n ")" ::: "memory")
; #define PG8_BAR __builtin_amdgcn_s_barrier()
; #define PG8_SCHED __builtin_amdgcn_sched_barrier(0)
; template <class Epi, class Sched, bool ALIGN_EPI = false, bool SP2 = false>
; __device__ __forceinline__ void gemm_phase(PG8_LAS unsigned char* lds, const Gemm g, const Sched& S, const Epi& E, int tid_in) {
;     ...
;         for (int t = 0; t < nt; t += 2) {
;             const bool last = (t == nt - 2);
;     ...
;             PG8_LDA(At, 1, 1); PG8_STAGE(PG8_SB(1, 0), b3, voffB); PG8_STAGE(PG8_SB(1, 1), b3 + hstep, voffB); PG8_STAGE(PG8_SA(1, 0), a3, voffA);
;             PG8_WAIT_V(8); PG8_WAIT_L(0); PG8_BAR; PG8_MMA(1, 0, At, B0); PG8_MMA(1, 1, At, B1); PG8_BAR; PG8_SCHED;
	s_add_i32 s28, s63, s34
	v_lshl_add_u64 v[222:223], v[222:223], 0, s[90:91]
	s_mov_b32 m0, s28
	ds_read_b128 v[190:193], v153 offset:49152
	ds_read_b128 v[194:197], v153 offset:50176
	ds_read_b128 v[198:201], v153 offset:51200
	ds_read_b128 v[202:205], v153 offset:52224
	ds_read_b128 v[206:209], v153 offset:53248
	ds_read_b128 v[210:213], v153 offset:54272
	ds_read_b128 v[214:217], v153 offset:55296
	ds_read_b128 v[218:221], v153 offset:56320
	global_load_lds_dwordx4 v[222:223], off
	s_add_i32 m0, s28, 0x2000
	s_add_u32 s26, s26, 0x80080
	v_lshl_add_u64 v[222:223], v[224:225], 0, s[90:91]
	s_addc_u32 s27, s27, 0
	s_add_i32 s28, s55, s34
	global_load_lds_dwordx4 v[222:223], off
	s_mov_b32 m0, s28
	v_lshl_add_u64 v[222:223], s[26:27], 0, v[0:1]
	global_load_lds_dwordx4 v[222:223], off
	s_add_i32 m0, s28, 0x2000
	v_lshl_add_u64 v[222:223], s[26:27], 0, v[130:131]
	global_load_lds_dwordx4 v[222:223], off
	s_mov_b32 m0, s41
	v_lshl_add_u64 v[222:223], v[226:227], 0, s[90:91]
	global_load_lds_dwordx4 v[222:223], off
	s_mov_b32 m0, s42
	v_lshl_add_u64 v[222:223], v[228:229], 0, s[90:91]
	global_load_lds_dwordx4 v[222:223], off
	s_waitcnt vmcnt(8)
	s_waitcnt lgkmcnt(0)
	s_barrier
	s_setprio 1
	s_waitcnt lgkmcnt(0)
	v_mfma_f32_16x16x32_bf16 v[62:65], v[142:145], v[190:193], v[62:65]
	v_mfma_f32_16x16x32_bf16 v[54:57], v[154:157], v[190:193], v[54:57]
	v_mfma_f32_16x16x32_bf16 v[46:49], v[142:145], v[198:201], v[46:49]
	v_mfma_f32_16x16x32_bf16 v[38:41], v[154:157], v[198:201], v[38:41]
	v_mfma_f32_16x16x32_bf16 v[30:33], v[142:145], v[206:209], v[30:33]
	v_mfma_f32_16x16x32_bf16 v[22:25], v[154:157], v[206:209], v[22:25]
	v_mfma_f32_16x16x32_bf16 v[14:17], v[142:145], v[214:217], v[14:17]
	v_mfma_f32_16x16x32_bf16 v[6:9], v[154:157], v[214:217], v[6:9]
	v_mfma_f32_16x16x32_bf16 v[62:65], v[146:149], v[194:197], v[62:65]
	v_mfma_f32_16x16x32_bf16 v[54:57], v[158:161], v[194:197], v[54:57]
	v_mfma_f32_16x16x32_bf16 v[46:49], v[146:149], v[202:205], v[46:49]
	v_mfma_f32_16x16x32_bf16 v[38:41], v[158:161], v[202:205], v[38:41]
	v_mfma_f32_16x16x32_bf16 v[30:33], v[146:149], v[210:213], v[30:33]
	v_mfma_f32_16x16x32_bf16 v[22:25], v[158:161], v[210:213], v[22:25]
	v_mfma_f32_16x16x32_bf16 v[14:17], v[146:149], v[218:221], v[14:17]
	v_mfma_f32_16x16x32_bf16 v[6:9], v[158:161], v[218:221], v[6:9]
	s_setprio 0
	s_setprio 1
	v_mfma_f32_16x16x32_bf16 v[58:61], v[162:165], v[190:193], v[58:61]
	v_mfma_f32_16x16x32_bf16 v[50:53], v[182:185], v[190:193], v[50:53]
	v_mfma_f32_16x16x32_bf16 v[42:45], v[162:165], v[198:201], v[42:45]
	v_mfma_f32_16x16x32_bf16 v[34:37], v[182:185], v[198:201], v[34:37]
	v_mfma_f32_16x16x32_bf16 v[26:29], v[162:165], v[206:209], v[26:29]
	v_mfma_f32_16x16x32_bf16 v[18:21], v[182:185], v[206:209], v[18:21]
	v_mfma_f32_16x16x32_bf16 v[10:13], v[162:165], v[214:217], v[10:13]
	v_mfma_f32_16x16x32_bf16 v[2:5], v[182:185], v[214:217], v[2:5]
	v_mfma_f32_16x16x32_bf16 v[58:61], v[166:169], v[194:197], v[58:61]
	v_mfma_f32_16x16x32_bf16 v[50:53], v[186:189], v[194:197], v[50:53]
	v_mfma_f32_16x16x32_bf16 v[42:45], v[166:169], v[202:205], v[42:45]
	v_mfma_f32_16x16x32_bf16 v[34:37], v[186:189], v[202:205], v[34:37]
	v_mfma_f32_16x16x32_bf16 v[26:29], v[166:169], v[210:213], v[26:29]
	v_mfma_f32_16x16x32_bf16 v[18:21], v[186:189], v[210:213], v[18:21]
	v_mfma_f32_16x16x32_bf16 v[10:13], v[166:169], v[218:221], v[10:13]
	v_mfma_f32_16x16x32_bf16 v[2:5], v[186:189], v[218:221], v[2:5]
	s_setprio 0
	s_barrier
	s_add_i32 s23, s23, 2
	s_add_u32 s24, s24, 0x100
	s_addc_u32 s25, s25, 0
	s_add_u32 s15, s15, 0x100
	s_addc_u32 s17, s17, 0
	s_cmp_gt_u32 s23, 29
	s_cbranch_scc0 .LBB0_1507
	s_and_b64 vcc, exec, s[12:13]
	s_cbranch_vccz .LBB0_1510
	s_barrier

; #define PG8_STAGE(bufoff, gbase, voff) do { _Pragma("unroll") for (int _i = 0; _i < 2; ++_i) \
;         __builtin_amdgcn_global_load_lds((const unsigned*)((const char*)(gbase) + (voff)[_i]), (PG8_LAS unsigned*)(lds + (bufoff) + ldsw + _i * 8192), 16, 0, 0); } while (0)
; #define PG8_LDA(dst, b, h) do { _Pragma("unroll") for (int m = 0; m < 4; ++m) _Pragma("unroll") for (int k = 0; k < 2; ++k) dst[m][k] = *(const PG8_LAS bf16x8*)(lds + PG8_SA(b, h) + aoff + m * 2048 + k * 1024); } while (0)
; #define PG8_LDB(dst, b, h) do { _Pragma("unroll") for (int n = 0; n < 2; ++n) _Pragma("unroll") for (int k = 0; k < 2; ++k) dst[n][k] = *(const PG8_LAS bf16x8*)(lds + PG8_SB(b, h) + boff + n * 2048 + k * 1024); } while (0)
; #define PG8_MMA(ai, bj, At, Bt) do { __builtin_amdgcn_s_setprio(1); _Pragma("unroll") for (int m = 0; m < 4; ++m) _Pragma("unroll") for (int n = 0; n < 2; ++n) _Pragma("unroll") for (int k = 0; k < 2; ++k) \
;         acc[ai][bj][m][n] = __builtin_amdgcn_mfma_f32_16x16x32_bf16(Bt[n][k], At[m][k], acc[ai][bj][m][n], 0, 0, 0); __builtin_amdgcn_s_setprio(0); } while (0)
; #define PG8_WAIT_V(n) asm volatile("s_waitcnt vmcnt(" #n ")" ::: "memory")
; #define PG8_WAIT_L(n) asm volatile("s_waitcnt lgkmcnt(" #n ")" ::: "memory")
; template <class Epi, class Sched, bool ALIGN_EPI = false, bool SP2 = false>
; __device__ __forceinline__ void gemm_phase(PG8_LAS unsigned char* lds, const Gemm g, const Sched& S, const Epi& E, int tid_in) {
;     ...
;             const bool last = (t == nt - 2);
;             const char* a1 = cA + (size_t)(t + 1) * kstep;
;             const char* a2 = last ? nA : cA + (size_t)(t + 2) * kstep; const char* b2 = last ? nB : cB + (size_t)(t + 2) * kstep;
;             const char* a3 = a2 + kstep; const char* b3 = b2 + kstep;
;             if (last && has_next) S.a_ready(nxt);
;             if constexpr (SP2) {
;             PG8_LDB(B0, 0, 0); PG8_LDB(B1, 0, 1); PG8_SCHED; PG8_LDA(At, 0, 0); PG8_STAGE(PG8_SA(1, 1), a1 + hstepA, voffA);
;             PG8_WAIT_V(8); PG8_WAIT_L(0); PG8_BAR; PG8_MMA(0, 0, At, B0); PG8_MMA(0, 1, At, B1); PG8_BAR; PG8_SCHED;
;             PG8_LDA(At, 0, 1); PG8_STAGE(PG8_SB(0, 0), b2, voffB); PG8_STAGE(PG8_SB(0, 1), b2 + hstep, voffB); PG8_STAGE(PG8_SA(0, 0), a2, voffA);
;             PG8_WAIT_V(8); PG8_WAIT_L(0); PG8_BAR; PG8_MMA(1, 0, At, B0); PG8_MMA(1, 1, At, B1); PG8_BAR; PG8_SCHED;
.LBB0_1577:
	v_add_u32_e32 v0, s4, v164
	ds_read_b128 v[130:133], v0
	ds_read_b128 v[142:145], v0 offset:1024
	ds_read_b128 v[146:149], v0 offset:2048
	ds_read_b128 v[150:153], v0 offset:3072
	v_add_u32_e32 v0, s5, v164
	ds_read_b128 v[154:157], v0
	ds_read_b128 v[158:161], v0 offset:1024
	ds_read_b128 v[166:169], v0 offset:2048
	ds_read_b128 v[182:185], v0 offset:3072
	s_add_i32 vcc_lo, s10, 2
	s_add_u32 s8, s6, 0x100
	s_addc_u32 s9, s7, 0
	s_cmp_eq_u32 s83, s10
	s_cselect_b32 s10, s82, s84
	s_cselect_b32 s37, s46, s9
	s_cselect_b32 s36, s47, s8
	s_cselect_b32 s11, s76, s85
	v_lshl_add_u64 v[218:219], s[6:7], 0, v[138:139]
	s_add_i32 m0, s38, 0xc000
	ds_read_b128 v[186:189], v165
	ds_read_b128 v[190:193], v165 offset:1024
	ds_read_b128 v[194:197], v165 offset:2048
	ds_read_b128 v[198:201], v165 offset:3072
	ds_read_b128 v[202:205], v165 offset:4096
	ds_read_b128 v[206:209], v165 offset:5120
	ds_read_b128 v[210:213], v165 offset:6144
	ds_read_b128 v[214:217], v165 offset:7168
	global_load_lds_dwordx4 v[218:219], off
	s_add_i32 m0, s38, 0xe000
	v_lshl_add_u64 v[218:219], s[6:7], 0, v[140:141]
	global_load_lds_dwordx4 v[218:219], off
	s_waitcnt vmcnt(8)
	s_waitcnt lgkmcnt(0)
	s_barrier
	s_setprio 1
	s_waitcnt lgkmcnt(0)
	v_mfma_f32_16x16x32_bf16 v[126:129], v[130:133], v[186:189], v[126:129]
	v_mfma_f32_16x16x32_bf16 v[122:125], v[146:149], v[186:189], v[122:125]
	v_mfma_f32_16x16x32_bf16 v[118:121], v[130:133], v[194:197], v[118:121]
	v_mfma_f32_16x16x32_bf16 v[114:117], v[146:149], v[194:197], v[114:117]
	v_mfma_f32_16x16x32_bf16 v[110:113], v[130:133], v[202:205], v[110:113]
	v_mfma_f32_16x16x32_bf16 v[106:109], v[146:149], v[202:205], v[106:109]
	v_mfma_f32_16x16x32_bf16 v[102:105], v[130:133], v[210:213], v[102:105]
	v_mfma_f32_16x16x32_bf16 v[98:101], v[146:149], v[210:213], v[98:101]
	v_mfma_f32_16x16x32_bf16 v[126:129], v[142:145], v[190:193], v[126:129]
	v_mfma_f32_16x16x32_bf16 v[122:125], v[150:153], v[190:193], v[122:125]
	v_mfma_f32_16x16x32_bf16 v[118:121], v[142:145], v[198:201], v[118:121]
	v_mfma_f32_16x16x32_bf16 v[114:117], v[150:153], v[198:201], v[114:117]
	v_mfma_f32_16x16x32_bf16 v[110:113], v[142:145], v[206:209], v[110:113]
	v_mfma_f32_16x16x32_bf16 v[106:109], v[150:153], v[206:209], v[106:109]
	v_mfma_f32_16x16x32_bf16 v[102:105], v[142:145], v[214:217], v[102:105]
	v_mfma_f32_16x16x32_bf16 v[98:101], v[150:153], v[214:217], v[98:101]
	s_setprio 0
	s_setprio 1
	v_mfma_f32_16x16x32_bf16 v[94:97], v[154:157], v[186:189], v[94:97]
	v_mfma_f32_16x16x32_bf16 v[90:93], v[166:169], v[186:189], v[90:93]
	v_mfma_f32_16x16x32_bf16 v[86:89], v[154:157], v[194:197], v[86:89]
	v_mfma_f32_16x16x32_bf16 v[82:85], v[166:169], v[194:197], v[82:85]
	v_mfma_f32_16x16x32_bf16 v[78:81], v[154:157], v[202:205], v[78:81]
	v_mfma_f32_16x16x32_bf16 v[74:77], v[166:169], v[202:205], v[74:77]
	v_mfma_f32_16x16x32_bf16 v[70:73], v[154:157], v[210:213], v[70:73]
	v_mfma_f32_16x16x32_bf16 v[66:69], v[166:169], v[210:213], v[66:69]
	v_mfma_f32_16x16x32_bf16 v[94:97], v[158:161], v[190:193], v[94:97]
	v_mfma_f32_16x16x32_bf16 v[90:93], v[182:185], v[190:193], v[90:93]
	v_mfma_f32_16x16x32_bf16 v[86:89], v[158:161], v[198:201], v[86:89]
	v_mfma_f32_16x16x32_bf16 v[82:85], v[182:185], v[198:201], v[82:85]
	v_mfma_f32_16x16x32_bf16 v[78:81], v[158:161], v[206:209], v[78:81]
	v_mfma_f32_16x16x32_bf16 v[74:77], v[182:185], v[206:209], v[74:77]
	v_mfma_f32_16x16x32_bf16 v[70:73], v[158:161], v[214:217], v[70:73]
	v_mfma_f32_16x16x32_bf16 v[66:69], v[182:185], v[214:217], v[66:69]
	s_setprio 0
	s_barrier
	s_add_i32 s6, s4, s33
	v_lshl_add_u64 v[218:219], s[10:11], 0, v[134:135]
	s_mov_b32 m0, s6
	ds_read_b128 v[186:189], v165 offset:16384
	ds_read_b128 v[190:193], v165 offset:17408
	ds_read_b128 v[194:197], v165 offset:18432
	ds_read_b128 v[198:201], v165 offset:19456
	ds_read_b128 v[202:205], v165 offset:20480
	ds_read_b128 v[206:209], v165 offset:21504
	ds_read_b128 v[210:213], v165 offset:22528
	ds_read_b128 v[214:217], v165 offset:23552
	global_load_lds_dwordx4 v[218:219], off
	s_add_i32 m0, s6, 0x2000
	s_add_u32 s6, s10, 0x160000
	v_lshl_add_u64 v[220:221], s[10:11], 0, v[136:137]
	s_addc_u32 s7, s11, 0
	s_add_i32 s64, s5, s33
	global_load_lds_dwordx4 v[220:221], off
	v_lshl_add_u64 v[222:223], s[6:7], 0, v[134:135]
	s_mov_b32 m0, s64
	v_lshl_add_u64 v[224:225], s[36:37], 0, v[136:137]
	global_load_lds_dwordx4 v[222:223], off
	s_add_i32 m0, s64, 0x2000
	v_lshl_add_u64 v[222:223], s[6:7], 0, v[136:137]
	global_load_lds_dwordx4 v[222:223], off
	s_mov_b32 m0, s38
	v_lshl_add_u64 v[222:223], s[36:37], 0, v[134:135]
	global_load_lds_dwordx4 v[222:223], off
	s_mov_b32 m0, s39
	s_nop 0
	global_load_lds_dwordx4 v[224:225], off
	s_waitcnt vmcnt(8)
	s_waitcnt lgkmcnt(0)
	s_barrier
; #define PG8_STAGE(bufoff, gbase, voff) do { _Pragma("unroll") for (int _i = 0; _i < 2; ++_i) \
;         __builtin_amdgcn_global_load_lds((const unsigned*)((const char*)(gbase) + (voff)[_i]), (PG8_LAS unsigned*)(lds + (bufoff) + ldsw + _i * 8192), 16, 0, 0); } while (0)
; #define PG8_LDA(dst, b, h) do { _Pragma("unroll") for (int m = 0; m < 4; ++m) _Pragma("unroll") for (int k = 0; k < 2; ++k) dst[m][k] = *(const PG8_LAS bf16x8*)(lds + PG8_SA(b, h) + aoff + m * 2048 + k * 1024); } while (0)
; #define PG8_LDB(dst, b, h) do { _Pragma("unroll") for (int n = 0; n < 2; ++n) _Pragma("unroll") for (int k = 0; k < 2; ++k) dst[n][k] = *(const PG8_LAS bf16x8*)(lds + PG8_SB(b, h) + boff + n * 2048 + k * 1024); } while (0)
; #define PG8_MMA(ai, bj, At, Bt) do { __builtin_amdgcn_s_setprio(1); _Pragma("unroll") for (int m = 0; m < 4; ++m) _Pragma("unroll") for (int n = 0; n < 2; ++n) _Pragma("unroll") for (int k = 0; k < 2; ++k) \
;         acc[ai][bj][m][n] = __builtin_amdgcn_mfma_f32_16x16x32_bf16(Bt[n][k], At[m][k], acc[ai][bj][m][n], 0, 0, 0); __builtin_amdgcn_s_setprio(0); } while (0)
; #define PG8_WAIT_V(n) asm volatile("s_waitcnt vmcnt(" #n ")" ::: "memory")
; #define PG8_WAIT_L(n) asm volatile("s_waitcnt lgkmcnt(" #n ")" ::: "memory")
; #define PG8_BAR __builtin_amdgcn_s_barrier()
; #define PG8_SCHED __builtin_amdgcn_sched_barrier(0)
; template <class Epi, class Sched, bool ALIGN_EPI = false, bool SP2 = false>
; __device__ __forceinline__ void gemm_phase(PG8_LAS unsigned char* lds, const Gemm g, const Sched& S, const Epi& E, int tid_in) {
;     ...
;             PG8_WAIT_V(8); PG8_WAIT_L(0); PG8_BAR; PG8_MMA(1, 0, At, B0); PG8_MMA(1, 1, At, B1); PG8_BAR; PG8_SCHED;
;             PG8_LDB(B0, 1, 0); PG8_LDB(B1, 1, 1); PG8_SCHED; PG8_LDA(At, 1, 0); PG8_STAGE(PG8_SA(0, 1), a2 + hstepA, voffA);
;             PG8_WAIT_V(8); PG8_WAIT_L(0); PG8_BAR; PG8_MMA(0, 0, At, B0); PG8_MMA(0, 1, At, B1); PG8_BAR; PG8_SCHED;
	s_setprio 1
	s_waitcnt lgkmcnt(0)
	v_mfma_f32_16x16x32_bf16 v[62:65], v[130:133], v[186:189], v[62:65]
	v_mfma_f32_16x16x32_bf16 v[58:61], v[146:149], v[186:189], v[58:61]
	v_mfma_f32_16x16x32_bf16 v[54:57], v[130:133], v[194:197], v[54:57]
	v_mfma_f32_16x16x32_bf16 v[50:53], v[146:149], v[194:197], v[50:53]
	v_mfma_f32_16x16x32_bf16 v[46:49], v[130:133], v[202:205], v[46:49]
	v_mfma_f32_16x16x32_bf16 v[42:45], v[146:149], v[202:205], v[42:45]
	v_mfma_f32_16x16x32_bf16 v[38:41], v[130:133], v[210:213], v[38:41]
	v_mfma_f32_16x16x32_bf16 v[34:37], v[146:149], v[210:213], v[34:37]
	v_mfma_f32_16x16x32_bf16 v[62:65], v[142:145], v[190:193], v[62:65]
	v_mfma_f32_16x16x32_bf16 v[58:61], v[150:153], v[190:193], v[58:61]
	v_mfma_f32_16x16x32_bf16 v[54:57], v[142:145], v[198:201], v[54:57]
	v_mfma_f32_16x16x32_bf16 v[50:53], v[150:153], v[198:201], v[50:53]
	v_mfma_f32_16x16x32_bf16 v[46:49], v[142:145], v[206:209], v[46:49]
	v_mfma_f32_16x16x32_bf16 v[42:45], v[150:153], v[206:209], v[42:45]
	v_mfma_f32_16x16x32_bf16 v[38:41], v[142:145], v[214:217], v[38:41]
	v_mfma_f32_16x16x32_bf16 v[34:37], v[150:153], v[214:217], v[34:37]
	s_setprio 0
	s_setprio 1
	v_mfma_f32_16x16x32_bf16 v[30:33], v[154:157], v[186:189], v[30:33]
	v_mfma_f32_16x16x32_bf16 v[26:29], v[166:169], v[186:189], v[26:29]
	v_mfma_f32_16x16x32_bf16 v[22:25], v[154:157], v[194:197], v[22:25]
	v_mfma_f32_16x16x32_bf16 v[18:21], v[166:169], v[194:197], v[18:21]
	v_mfma_f32_16x16x32_bf16 v[14:17], v[154:157], v[202:205], v[14:17]
	v_mfma_f32_16x16x32_bf16 v[10:13], v[166:169], v[202:205], v[10:13]
	v_mfma_f32_16x16x32_bf16 v[6:9], v[154:157], v[210:213], v[6:9]
	v_mfma_f32_16x16x32_bf16 v[2:5], v[166:169], v[210:213], v[2:5]
	v_mfma_f32_16x16x32_bf16 v[30:33], v[158:161], v[190:193], v[30:33]
	v_mfma_f32_16x16x32_bf16 v[26:29], v[182:185], v[190:193], v[26:29]
	v_mfma_f32_16x16x32_bf16 v[22:25], v[158:161], v[198:201], v[22:25]
	v_mfma_f32_16x16x32_bf16 v[18:21], v[182:185], v[198:201], v[18:21]
	v_mfma_f32_16x16x32_bf16 v[14:17], v[158:161], v[206:209], v[14:17]
	v_mfma_f32_16x16x32_bf16 v[10:13], v[182:185], v[206:209], v[10:13]
	v_mfma_f32_16x16x32_bf16 v[6:9], v[158:161], v[214:217], v[6:9]
	v_mfma_f32_16x16x32_bf16 v[2:5], v[182:185], v[214:217], v[2:5]
	s_setprio 0
	s_barrier
	v_add_u32_e32 v0, s63, v164
	ds_read_b128 v[130:133], v0
	ds_read_b128 v[142:145], v0 offset:1024
	ds_read_b128 v[146:149], v0 offset:2048
	ds_read_b128 v[150:153], v0 offset:3072
	v_add_u32_e32 v0, s55, v164
	ds_read_b128 v[154:157], v0
	ds_read_b128 v[158:161], v0 offset:1024
	ds_read_b128 v[166:169], v0 offset:2048
	ds_read_b128 v[182:185], v0 offset:3072
	s_add_u32 s6, s36, 0x160000
	s_addc_u32 s7, s37, 0
	s_mov_b32 m0, s40
	v_lshl_add_u64 v[226:227], s[6:7], 0, v[134:135]
	ds_read_b128 v[186:189], v165 offset:32768
	ds_read_b128 v[190:193], v165 offset:33792
	ds_read_b128 v[194:197], v165 offset:34816
	ds_read_b128 v[198:201], v165 offset:35840
	ds_read_b128 v[202:205], v165 offset:36864
	ds_read_b128 v[206:209], v165 offset:37888
	ds_read_b128 v[210:213], v165 offset:38912
	ds_read_b128 v[214:217], v165 offset:39936
	global_load_lds_dwordx4 v[226:227], off
	s_mov_b32 m0, s41
	v_lshl_add_u64 v[226:227], s[6:7], 0, v[136:137]
	global_load_lds_dwordx4 v[226:227], off
	s_waitcnt vmcnt(8)
	s_waitcnt lgkmcnt(0)
	s_barrier
	s_setprio 1
	s_waitcnt lgkmcnt(0)
	v_mfma_f32_16x16x32_bf16 v[126:129], v[130:133], v[186:189], v[126:129]
	v_mfma_f32_16x16x32_bf16 v[122:125], v[146:149], v[186:189], v[122:125]
	v_mfma_f32_16x16x32_bf16 v[118:121], v[130:133], v[194:197], v[118:121]
	v_mfma_f32_16x16x32_bf16 v[114:117], v[146:149], v[194:197], v[114:117]
	v_mfma_f32_16x16x32_bf16 v[110:113], v[130:133], v[202:205], v[110:113]
	v_mfma_f32_16x16x32_bf16 v[106:109], v[146:149], v[202:205], v[106:109]
	v_mfma_f32_16x16x32_bf16 v[102:105], v[130:133], v[210:213], v[102:105]
	v_mfma_f32_16x16x32_bf16 v[98:101], v[146:149], v[210:213], v[98:101]
	v_mfma_f32_16x16x32_bf16 v[126:129], v[142:145], v[190:193], v[126:129]
	v_mfma_f32_16x16x32_bf16 v[122:125], v[150:153], v[190:193], v[122:125]
	v_mfma_f32_16x16x32_bf16 v[118:121], v[142:145], v[198:201], v[118:121]
	v_mfma_f32_16x16x32_bf16 v[114:117], v[150:153], v[198:201], v[114:117]
	v_mfma_f32_16x16x32_bf16 v[110:113], v[142:145], v[206:209], v[110:113]
	v_mfma_f32_16x16x32_bf16 v[106:109], v[150:153], v[206:209], v[106:109]
	v_mfma_f32_16x16x32_bf16 v[102:105], v[142:145], v[214:217], v[102:105]
	v_mfma_f32_16x16x32_bf16 v[98:101], v[150:153], v[214:217], v[98:101]
	s_setprio 0
	s_setprio 1
	v_mfma_f32_16x16x32_bf16 v[94:97], v[154:157], v[186:189], v[94:97]
	v_mfma_f32_16x16x32_bf16 v[90:93], v[166:169], v[186:189], v[90:93]
	v_mfma_f32_16x16x32_bf16 v[86:89], v[154:157], v[194:197], v[86:89]
	v_mfma_f32_16x16x32_bf16 v[82:85], v[166:169], v[194:197], v[82:85]
	v_mfma_f32_16x16x32_bf16 v[78:81], v[154:157], v[202:205], v[78:81]
	v_mfma_f32_16x16x32_bf16 v[74:77], v[166:169], v[202:205], v[74:77]
	v_mfma_f32_16x16x32_bf16 v[70:73], v[154:157], v[210:213], v[70:73]
	v_mfma_f32_16x16x32_bf16 v[66:69], v[166:169], v[210:213], v[66:69]
	v_mfma_f32_16x16x32_bf16 v[94:97], v[158:161], v[190:193], v[94:97]
	v_mfma_f32_16x16x32_bf16 v[90:93], v[182:185], v[190:193], v[90:93]
	v_mfma_f32_16x16x32_bf16 v[86:89], v[158:161], v[198:201], v[86:89]
	v_mfma_f32_16x16x32_bf16 v[82:85], v[182:185], v[198:201], v[82:85]
	v_mfma_f32_16x16x32_bf16 v[78:81], v[158:161], v[206:209], v[78:81]
	v_mfma_f32_16x16x32_bf16 v[74:77], v[182:185], v[206:209], v[74:77]
	v_mfma_f32_16x16x32_bf16 v[70:73], v[158:161], v[214:217], v[70:73]
	v_mfma_f32_16x16x32_bf16 v[66:69], v[182:185], v[214:217], v[66:69]
	s_setprio 0
	s_barrier
; #define PG8_STAGE(bufoff, gbase, voff) do { _Pragma("unroll") for (int _i = 0; _i < 2; ++_i) \
;         __builtin_amdgcn_global_load_lds((const unsigned*)((const char*)(gbase) + (voff)[_i]), (PG8_LAS unsigned*)(lds + (bufoff) + ldsw + _i * 8192), 16, 0, 0); } while (0)
; #define PG8_LDA(dst, b, h) do { _Pragma("unroll") for (int m = 0; m < 4; ++m) _Pragma("unroll") for (int k = 0; k < 2; ++k) dst[m][k] = *(const PG8_LAS bf16x8*)(lds + PG8_SA(b, h) + aoff + m * 2048 + k * 1024); } while (0)
; #define PG8_MMA(ai, bj, At, Bt) do { __builtin_amdgcn_s_setprio(1); _Pragma("unroll") for (int m = 0; m < 4; ++m) _Pragma("unroll") for (int n = 0; n < 2; ++n) _Pragma("unroll") for (int k = 0; k < 2; ++k) \
;         acc[ai][bj][m][n] = __builtin_amdgcn_mfma_f32_16x16x32_bf16(Bt[n][k], At[m][k], acc[ai][bj][m][n], 0, 0, 0); __builtin_amdgcn_s_setprio(0); } while (0)
; #define PG8_WAIT_V(n) asm volatile("s_waitcnt vmcnt(" #n ")" ::: "memory")
; #define PG8_WAIT_L(n) asm volatile("s_waitcnt lgkmcnt(" #n ")" ::: "memory")
; #define PG8_BAR __builtin_amdgcn_s_barrier()
; #define PG8_SCHED __builtin_amdgcn_sched_barrier(0)
; template <class Epi, class Sched, bool ALIGN_EPI = false, bool SP2 = false>
; __device__ __forceinline__ void gemm_phase(PG8_LAS unsigned char* lds, const Gemm g, const Sched& S, const Epi& E, int tid_in) {
;     ...
;         for (int t = 0; t < nt; t += 2) {
;             const bool last = (t == nt - 2);
;     ...
;             PG8_LDA(At, 1, 1); PG8_STAGE(PG8_SB(1, 0), b3, voffB); PG8_STAGE(PG8_SB(1, 1), b3 + hstep, voffB); PG8_STAGE(PG8_SA(1, 0), a3, voffA);
;             PG8_WAIT_V(8); PG8_WAIT_L(0); PG8_BAR; PG8_MMA(1, 0, At, B0); PG8_MMA(1, 1, At, B1); PG8_BAR; PG8_SCHED;
	s_add_i32 s6, s63, s33
	v_lshl_add_u64 v[218:219], v[218:219], 0, s[90:91]
	s_mov_b32 m0, s6
	ds_read_b128 v[186:189], v165 offset:49152
	ds_read_b128 v[190:193], v165 offset:50176
	ds_read_b128 v[194:197], v165 offset:51200
	ds_read_b128 v[198:201], v165 offset:52224
	ds_read_b128 v[202:205], v165 offset:53248
	ds_read_b128 v[206:209], v165 offset:54272
	ds_read_b128 v[210:213], v165 offset:55296
	ds_read_b128 v[214:217], v165 offset:56320
	global_load_lds_dwordx4 v[218:219], off
	s_add_i32 m0, s6, 0x2000
	s_add_u32 s6, s10, 0x160080
	v_lshl_add_u64 v[218:219], v[220:221], 0, s[90:91]
	s_addc_u32 s7, s11, 0
	s_add_i32 s10, s55, s33
	global_load_lds_dwordx4 v[218:219], off
	s_mov_b32 m0, s10
	v_lshl_add_u64 v[218:219], s[6:7], 0, v[134:135]
	global_load_lds_dwordx4 v[218:219], off
	s_add_i32 m0, s10, 0x2000
	v_lshl_add_u64 v[218:219], s[6:7], 0, v[136:137]
	global_load_lds_dwordx4 v[218:219], off
	s_mov_b32 m0, s49
	v_lshl_add_u64 v[218:219], v[222:223], 0, s[90:91]
	global_load_lds_dwordx4 v[218:219], off
	s_mov_b32 m0, s66
	v_lshl_add_u64 v[218:219], v[224:225], 0, s[90:91]
	global_load_lds_dwordx4 v[218:219], off
	s_waitcnt vmcnt(8)
	s_waitcnt lgkmcnt(0)
	s_barrier
	s_setprio 1
	s_waitcnt lgkmcnt(0)
	v_mfma_f32_16x16x32_bf16 v[62:65], v[130:133], v[186:189], v[62:65]
	v_mfma_f32_16x16x32_bf16 v[58:61], v[146:149], v[186:189], v[58:61]
	v_mfma_f32_16x16x32_bf16 v[54:57], v[130:133], v[194:197], v[54:57]
	v_mfma_f32_16x16x32_bf16 v[50:53], v[146:149], v[194:197], v[50:53]
	v_mfma_f32_16x16x32_bf16 v[46:49], v[130:133], v[202:205], v[46:49]
	v_mfma_f32_16x16x32_bf16 v[42:45], v[146:149], v[202:205], v[42:45]
	v_mfma_f32_16x16x32_bf16 v[38:41], v[130:133], v[210:213], v[38:41]
	v_mfma_f32_16x16x32_bf16 v[34:37], v[146:149], v[210:213], v[34:37]
	v_mfma_f32_16x16x32_bf16 v[62:65], v[142:145], v[190:193], v[62:65]
	v_mfma_f32_16x16x32_bf16 v[58:61], v[150:153], v[190:193], v[58:61]
	v_mfma_f32_16x16x32_bf16 v[54:57], v[142:145], v[198:201], v[54:57]
	v_mfma_f32_16x16x32_bf16 v[50:53], v[150:153], v[198:201], v[50:53]
	v_mfma_f32_16x16x32_bf16 v[46:49], v[142:145], v[206:209], v[46:49]
	v_mfma_f32_16x16x32_bf16 v[42:45], v[150:153], v[206:209], v[42:45]
	v_mfma_f32_16x16x32_bf16 v[38:41], v[142:145], v[214:217], v[38:41]
	v_mfma_f32_16x16x32_bf16 v[34:37], v[150:153], v[214:217], v[34:37]
	s_setprio 0
	s_setprio 1
	v_mfma_f32_16x16x32_bf16 v[30:33], v[154:157], v[186:189], v[30:33]
	v_mfma_f32_16x16x32_bf16 v[26:29], v[166:169], v[186:189], v[26:29]
	v_mfma_f32_16x16x32_bf16 v[22:25], v[154:157], v[194:197], v[22:25]
	v_mfma_f32_16x16x32_bf16 v[18:21], v[166:169], v[194:197], v[18:21]
	v_mfma_f32_16x16x32_bf16 v[14:17], v[154:157], v[202:205], v[14:17]
	v_mfma_f32_16x16x32_bf16 v[10:13], v[166:169], v[202:205], v[10:13]
	v_mfma_f32_16x16x32_bf16 v[6:9], v[154:157], v[210:213], v[6:9]
	v_mfma_f32_16x16x32_bf16 v[2:5], v[166:169], v[210:213], v[2:5]
	v_mfma_f32_16x16x32_bf16 v[30:33], v[158:161], v[190:193], v[30:33]
	v_mfma_f32_16x16x32_bf16 v[26:29], v[182:185], v[190:193], v[26:29]
	v_mfma_f32_16x16x32_bf16 v[22:25], v[158:161], v[198:201], v[22:25]
	v_mfma_f32_16x16x32_bf16 v[18:21], v[182:185], v[198:201], v[18:21]
	v_mfma_f32_16x16x32_bf16 v[14:17], v[158:161], v[206:209], v[14:17]
	v_mfma_f32_16x16x32_bf16 v[10:13], v[182:185], v[206:209], v[10:13]
	v_mfma_f32_16x16x32_bf16 v[6:9], v[158:161], v[214:217], v[6:9]
	v_mfma_f32_16x16x32_bf16 v[2:5], v[182:185], v[214:217], v[2:5]
	s_setprio 0
	s_barrier
	s_add_u32 s84, s84, 0x100
	s_addc_u32 s85, s85, 0
	s_cmp_ge_u32 vcc_lo, s79
	s_mov_b64 s[6:7], s[8:9]
	s_mov_b32 s10, vcc_lo
	s_cbranch_scc0 .LBB0_1577
	s_and_b64 vcc, exec, s[24:25]
	s_cbranch_vccz .LBB0_1580
	s_barrier
